# stack: register-resident RG-LRU scan (LA/UU/SG loaded once), tail_merge loads up front, Q-norm sums via LDS reduce + plain store instead of float atomics, lazy softmax rescale, merge-loop wait hoist
# speedup vs baseline: 1.0334x; 1.0231x over previous
.LBB0_18:
	s_lshl_b32 s4, s11, 5
	s_and_b32 s4, s4, 0x60
	v_readlane_b32 s5, v255, 52
	v_mbcnt_lo_u32_b32 v4, -1, 0
	v_mbcnt_hi_u32_b32 v4, -1, v4
	s_or_b32 s12, s4, s5
	v_and_b32_e32 v40, 15, v4
	v_or_b32_e32 v0, s12, v40
	v_readlane_b32 s4, v252, 24
	v_lshlrev_b32_e32 v0, 11, v0
	v_readlane_b32 s5, v252, 25
	v_readlane_b32 s8, v252, 26
	v_and_b32_e32 v36, 48, v4
	s_waitcnt lgkmcnt(0)
	v_lshl_add_u64 v[2:3], s[4:5], 0, v[0:1]
	v_mov_b32_e32 v37, v1
	v_readlane_b32 s9, v252, 27
	v_and_b32_e32 v5, 63, v4
	v_lshl_add_u64 v[30:31], v[2:3], 0, v[36:37]
	v_lshl_add_u64 v[2:3], s[8:9], 0, v[0:1]
	v_readlane_b32 s4, v252, 30
	v_bfe_u32 v39, v4, 4, 2
	v_lshl_add_u64 v[34:35], v[2:3], 0, v[36:37]
	v_lshl_add_u32 v38, v5, 4, s4
	global_load_dwordx4 v[2:5], v[30:31], off
	global_load_dwordx4 v[6:9], v[30:31], off offset:64
	global_load_dwordx4 v[10:13], v[30:31], off offset:128
	global_load_dwordx4 v[14:17], v[30:31], off offset:192
	global_load_dwordx4 v[18:21], v[30:31], off offset:256
	global_load_dwordx4 v[22:25], v[30:31], off offset:320
	global_load_dwordx4 v[26:29], v[30:31], off offset:384
	s_nop 0
	global_load_dwordx4 v[30:33], v[30:31], off offset:448
	s_lshl_b32 s4, s10, 11
	v_lshlrev_b32_e32 v0, 11, v40
	s_and_b32 s4, s4, 0x1f8000
	v_or3_b32 v0, s4, v0, v36
	v_lshl_add_u64 v[36:37], s[8:9], 0, v[0:1]
	s_mov_b64 s[8:9], 0
	v_mov_b32_e32 v0, v38
	s_mov_b64 s[4:5], 0xf80000
	v_lshl_add_u64 v[50:51], v[36:37], 0, s[4:5]
	s_mov_b64 s[4:5], 0x6200000
	v_lshl_add_u64 v[54:55], v[34:35], 0, s[4:5]
	s_mov_b64 s[4:5], 0x1580000
	v_lshl_add_u64 v[52:53], v[36:37], 0, s[4:5]
	global_load_dwordx4 v[56:59], v[50:51], off
	global_load_dwordx4 v[60:63], v[50:51], off offset:64
	global_load_dwordx4 v[64:67], v[50:51], off offset:128
	global_load_dwordx4 v[68:71], v[50:51], off offset:192
	global_load_dwordx4 v[72:75], v[50:51], off offset:256
	global_load_dwordx4 v[76:79], v[50:51], off offset:320
	global_load_dwordx4 v[80:83], v[50:51], off offset:384
	global_load_dwordx4 v[84:87], v[50:51], off offset:448
	global_load_dwordx4 v[88:91], v[54:55], off
	global_load_dwordx4 v[92:95], v[54:55], off offset:64
	global_load_dwordx4 v[96:99], v[54:55], off offset:128
	global_load_dwordx4 v[100:103], v[54:55], off offset:192
	global_load_dwordx4 v[104:107], v[54:55], off offset:256
	global_load_dwordx4 v[108:111], v[54:55], off offset:320
	global_load_dwordx4 v[112:115], v[54:55], off offset:384
	global_load_dwordx4 v[116:119], v[54:55], off offset:448
	global_load_dwordx4 v[120:123], v[52:53], off
	global_load_dwordx4 v[124:127], v[52:53], off offset:64
	global_load_dwordx4 v[128:131], v[52:53], off offset:128
	global_load_dwordx4 v[132:135], v[52:53], off offset:192
	global_load_dwordx4 v[136:139], v[52:53], off offset:256
	global_load_dwordx4 v[140:143], v[52:53], off offset:320
	global_load_dwordx4 v[144:147], v[52:53], off offset:384
	global_load_dwordx4 v[148:151], v[52:53], off offset:448
	s_mov_b64 s[4:5], 0x1180000
	v_lshl_add_u64 v[50:51], v[36:37], 0, s[4:5]
	s_mov_b64 s[4:5], 0xa300000
	v_lshl_add_u64 v[54:55], v[34:35], 0, s[4:5]
	s_mov_b64 s[4:5], 0x1780000
	v_lshl_add_u64 v[52:53], v[36:37], 0, s[4:5]
	global_load_dwordx4 v[152:155], v[50:51], off
	global_load_dwordx4 v[156:159], v[50:51], off offset:64
	global_load_dwordx4 v[160:163], v[50:51], off offset:128
	global_load_dwordx4 v[164:167], v[50:51], off offset:192
	global_load_dwordx4 v[168:171], v[50:51], off offset:256
	global_load_dwordx4 v[172:175], v[50:51], off offset:320
	global_load_dwordx4 v[176:179], v[50:51], off offset:384
	global_load_dwordx4 v[180:183], v[50:51], off offset:448
	global_load_dwordx4 v[184:187], v[54:55], off
	global_load_dwordx4 v[188:191], v[54:55], off offset:64
	global_load_dwordx4 v[192:195], v[54:55], off offset:128
	global_load_dwordx4 v[196:199], v[54:55], off offset:192
	global_load_dwordx4 v[200:203], v[54:55], off offset:256
	global_load_dwordx4 v[204:207], v[54:55], off offset:320
	global_load_dwordx4 v[208:211], v[54:55], off offset:384
	global_load_dwordx4 v[212:215], v[54:55], off offset:448
	global_load_dwordx4 v[216:219], v[52:53], off
	global_load_dwordx4 v[220:223], v[52:53], off offset:64
	global_load_dwordx4 v[224:227], v[52:53], off offset:128
	global_load_dwordx4 v[228:231], v[52:53], off offset:192
	global_load_dwordx4 v[232:235], v[52:53], off offset:256
	global_load_dwordx4 v[236:239], v[52:53], off offset:320
	global_load_dwordx4 v[240:243], v[52:53], off offset:384
	global_load_dwordx4 v[244:247], v[52:53], off offset:448
	s_waitcnt vmcnt(40)
	v_mfma_f32_16x16x32_bf16 v[42:45], v[2:5], v[56:59], 0
	v_mfma_f32_16x16x32_bf16 v[42:45], v[6:9], v[60:63], v[42:45]
	v_mfma_f32_16x16x32_bf16 v[42:45], v[10:13], v[64:67], v[42:45]
	v_mfma_f32_16x16x32_bf16 v[42:45], v[14:17], v[68:71], v[42:45]
	v_mfma_f32_16x16x32_bf16 v[42:45], v[18:21], v[72:75], v[42:45]
	v_mfma_f32_16x16x32_bf16 v[42:45], v[22:25], v[76:79], v[42:45]
	v_mfma_f32_16x16x32_bf16 v[42:45], v[26:29], v[80:83], v[42:45]
	v_mfma_f32_16x16x32_bf16 v[42:45], v[30:33], v[84:87], v[42:45]
	s_waitcnt vmcnt(24)
	v_mfma_f32_16x16x32_bf16 v[46:49], v[88:91], v[120:123], 0
	v_mfma_f32_16x16x32_bf16 v[46:49], v[92:95], v[124:127], v[46:49]
	v_mfma_f32_16x16x32_bf16 v[46:49], v[96:99], v[128:131], v[46:49]
	v_mfma_f32_16x16x32_bf16 v[46:49], v[100:103], v[132:135], v[46:49]
	v_mfma_f32_16x16x32_bf16 v[46:49], v[104:107], v[136:139], v[46:49]
	v_mfma_f32_16x16x32_bf16 v[46:49], v[108:111], v[140:143], v[46:49]
	v_mfma_f32_16x16x32_bf16 v[46:49], v[112:115], v[144:147], v[46:49]
	v_mfma_f32_16x16x32_bf16 v[46:49], v[116:119], v[148:151], v[46:49]
	s_mov_b64 s[4:5], 0x1380000
	v_lshl_add_u64 v[50:51], v[36:37], 0, s[4:5]
	s_mov_b64 s[4:5], 0xc380000
	v_lshl_add_u64 v[54:55], v[34:35], 0, s[4:5]
	s_mov_b64 s[4:5], 0x1980000
	v_lshl_add_u64 v[52:53], v[36:37], 0, s[4:5]
	global_load_dwordx4 v[56:59], v[50:51], off
	global_load_dwordx4 v[60:63], v[50:51], off offset:64
	global_load_dwordx4 v[64:67], v[50:51], off offset:128
	global_load_dwordx4 v[68:71], v[50:51], off offset:192
	global_load_dwordx4 v[72:75], v[50:51], off offset:256
	global_load_dwordx4 v[76:79], v[50:51], off offset:320
	global_load_dwordx4 v[80:83], v[50:51], off offset:384
	global_load_dwordx4 v[84:87], v[50:51], off offset:448
	global_load_dwordx4 v[88:91], v[54:55], off
	global_load_dwordx4 v[92:95], v[54:55], off offset:64
	global_load_dwordx4 v[96:99], v[54:55], off offset:128
	global_load_dwordx4 v[100:103], v[54:55], off offset:192
	global_load_dwordx4 v[104:107], v[54:55], off offset:256
	global_load_dwordx4 v[108:111], v[54:55], off offset:320
	global_load_dwordx4 v[112:115], v[54:55], off offset:384
	global_load_dwordx4 v[116:119], v[54:55], off offset:448
	global_load_dwordx4 v[120:123], v[52:53], off
	global_load_dwordx4 v[124:127], v[52:53], off offset:64
	global_load_dwordx4 v[128:131], v[52:53], off offset:128
	global_load_dwordx4 v[132:135], v[52:53], off offset:192
	global_load_dwordx4 v[136:139], v[52:53], off offset:256
	global_load_dwordx4 v[140:143], v[52:53], off offset:320
	global_load_dwordx4 v[144:147], v[52:53], off offset:384
	global_load_dwordx4 v[148:151], v[52:53], off offset:448
	ds_write_b128 v0, v[42:45]
	ds_write_b128 v0, v[46:49] offset:1024
	s_nop 1
	s_waitcnt vmcnt(40)
	v_mfma_f32_16x16x32_bf16 v[42:45], v[2:5], v[152:155], 0
	v_mfma_f32_16x16x32_bf16 v[42:45], v[6:9], v[156:159], v[42:45]
	v_mfma_f32_16x16x32_bf16 v[42:45], v[10:13], v[160:163], v[42:45]
	v_mfma_f32_16x16x32_bf16 v[42:45], v[14:17], v[164:167], v[42:45]
	v_mfma_f32_16x16x32_bf16 v[42:45], v[18:21], v[168:171], v[42:45]
	v_mfma_f32_16x16x32_bf16 v[42:45], v[22:25], v[172:175], v[42:45]
	v_mfma_f32_16x16x32_bf16 v[42:45], v[26:29], v[176:179], v[42:45]
	v_mfma_f32_16x16x32_bf16 v[42:45], v[30:33], v[180:183], v[42:45]
	s_waitcnt vmcnt(24)
	v_mfma_f32_16x16x32_bf16 v[46:49], v[184:187], v[216:219], 0
	v_mfma_f32_16x16x32_bf16 v[46:49], v[188:191], v[220:223], v[46:49]
	v_mfma_f32_16x16x32_bf16 v[46:49], v[192:195], v[224:227], v[46:49]
	v_mfma_f32_16x16x32_bf16 v[46:49], v[196:199], v[228:231], v[46:49]
	v_mfma_f32_16x16x32_bf16 v[46:49], v[200:203], v[232:235], v[46:49]
	v_mfma_f32_16x16x32_bf16 v[46:49], v[204:207], v[236:239], v[46:49]
	v_mfma_f32_16x16x32_bf16 v[46:49], v[208:211], v[240:243], v[46:49]
	v_mfma_f32_16x16x32_bf16 v[46:49], v[212:215], v[244:247], v[46:49]
	s_nop 7
	s_nop 0
	ds_write_b128 v0, v[42:45] offset:2048
	ds_write_b128 v0, v[46:49] offset:3072
	s_nop 1
	s_waitcnt vmcnt(16)
	v_mfma_f32_16x16x32_bf16 v[42:45], v[2:5], v[56:59], 0
	v_mfma_f32_16x16x32_bf16 v[42:45], v[6:9], v[60:63], v[42:45]
	v_mfma_f32_16x16x32_bf16 v[42:45], v[10:13], v[64:67], v[42:45]
	v_mfma_f32_16x16x32_bf16 v[42:45], v[14:17], v[68:71], v[42:45]
	v_mfma_f32_16x16x32_bf16 v[42:45], v[18:21], v[72:75], v[42:45]
	v_mfma_f32_16x16x32_bf16 v[42:45], v[22:25], v[76:79], v[42:45]
	v_mfma_f32_16x16x32_bf16 v[42:45], v[26:29], v[80:83], v[42:45]
	v_mfma_f32_16x16x32_bf16 v[42:45], v[30:33], v[84:87], v[42:45]
	s_waitcnt vmcnt(0)
	v_mfma_f32_16x16x32_bf16 v[46:49], v[88:91], v[120:123], 0
	v_mfma_f32_16x16x32_bf16 v[46:49], v[92:95], v[124:127], v[46:49]
	v_mfma_f32_16x16x32_bf16 v[46:49], v[96:99], v[128:131], v[46:49]
	v_mfma_f32_16x16x32_bf16 v[46:49], v[100:103], v[132:135], v[46:49]
	v_mfma_f32_16x16x32_bf16 v[46:49], v[104:107], v[136:139], v[46:49]
	v_mfma_f32_16x16x32_bf16 v[46:49], v[108:111], v[140:143], v[46:49]
	v_mfma_f32_16x16x32_bf16 v[46:49], v[112:115], v[144:147], v[46:49]
	v_mfma_f32_16x16x32_bf16 v[46:49], v[116:119], v[148:151], v[46:49]
	s_nop 7
	s_nop 0
	ds_write_b128 v0, v[42:45] offset:4096
	ds_write_b128 v0, v[46:49] offset:5120
	v_add_u32_e32 v0, 0x1800, v0
	s_mov_b64 s[8:9], 0x600000
	v_readlane_b32 s4, v252, 31
	v_readlane_b32 s5, v252, 32
	s_and_b64 vcc, exec, s[4:5]
	s_waitcnt lgkmcnt(0)
	s_barrier
	s_cbranch_vccz .LBB0_17
	s_lshl_b32 s4, s11, 2
	v_mov_b32_e32 v0, s4
	s_movk_i32 s4, 0x3e3
	v_bitop3_b32 v9, v40, s4, v0 bitop3:0xc8
	v_lshl_or_b32 v12, v39, 2, s12
	v_readlane_b32 s4, v252, 37
	v_lshlrev_b32_e32 v0, 2, v12
	v_readlane_b32 s5, v252, 38
	s_mov_b32 s12, 0x3a800000
	v_lshlrev_b32_e32 v8, 1, v40
	s_and_b32 s8, s11, 4
	s_nop 1
	global_load_dwordx4 v[2:5], v0, s[4:5]
	s_mov_b32 s4, 0x358637bd
	v_mov_b64_e32 v[6:7], s[4:5]
	s_waitcnt vmcnt(0)
	v_pk_fma_f32 v[2:3], v[2:3], s[12:13], v[6:7] op_sel_hi:[1,0,0]
	s_nop 0
	v_mul_f32_e32 v0, 0x4b800000, v2
	v_cmp_gt_f32_e64 s[4:5], s54, v2
	v_cmp_gt_f32_e32 vcc, s54, v3
	s_nop 0
	v_cndmask_b32_e64 v0, v2, v0, s[4:5]
	v_rsq_f32_e32 v0, v0
	s_nop 0
	v_mul_f32_e32 v2, 0x45800000, v0
	v_cndmask_b32_e64 v15, v0, v2, s[4:5]
	v_mul_f32_e32 v0, 0x4b800000, v3
	v_cndmask_b32_e32 v0, v3, v0, vcc
	v_rsq_f32_e32 v0, v0
	s_nop 0
	v_mul_f32_e32 v2, 0x45800000, v0
	v_cndmask_b32_e32 v14, v0, v2, vcc
	v_pk_fma_f32 v[2:3], v[4:5], s[12:13], v[6:7] op_sel_hi:[1,0,0]
	s_nop 0
	v_mul_f32_e32 v0, 0x4b800000, v2
	v_cmp_gt_f32_e64 s[4:5], s54, v2
	v_cmp_gt_f32_e32 vcc, s54, v3
	s_nop 0
	v_cndmask_b32_e64 v0, v2, v0, s[4:5]
	v_rsq_f32_e32 v0, v0
	s_nop 0
	v_mul_f32_e32 v2, 0x45800000, v0
	v_cndmask_b32_e64 v13, v0, v2, s[4:5]
	v_mul_f32_e32 v0, 0x4b800000, v3
	v_cndmask_b32_e32 v0, v3, v0, vcc
	v_rsq_f32_e32 v0, v0
	v_readlane_b32 s4, v252, 49
	v_readlane_b32 s5, v252, 50
	v_mul_f32_e32 v2, 0x45800000, v0
	v_cndmask_b32_e32 v0, v0, v2, vcc
	v_and_b32_e32 v2, 24, v8
	v_or3_b32 v16, v9, s8, v2
	ds_read_b128 v[2:5], v38
	ds_read_b128 v[6:9], v38 offset:1024
	ds_read_b128 v[18:21], v38 offset:12288
	v_or_b32_e32 v10, s4, v16
	v_ashrrev_i32_e32 v11, 31, v10
	v_readlane_b32 s4, v255, 37
	v_readlane_b32 s5, v255, 38
	s_waitcnt lgkmcnt(0)
	v_pk_add_f32 v[20:21], v[4:5], v[20:21]
	v_pk_add_f32 v[18:19], v[2:3], v[18:19]
	ds_read_b128 v[2:5], v38 offset:13312
	s_waitcnt lgkmcnt(0)
	v_pk_add_f32 v[8:9], v[8:9], v[4:5]
	v_pk_add_f32 v[6:7], v[6:7], v[2:3]
	ds_read_b128 v[2:5], v38 offset:24576
	s_waitcnt lgkmcnt(0)
	v_pk_add_f32 v[20:21], v[20:21], v[4:5]
	v_pk_add_f32 v[18:19], v[18:19], v[2:3]
	ds_read_b128 v[2:5], v38 offset:25600
	s_waitcnt lgkmcnt(0)
	v_pk_add_f32 v[8:9], v[8:9], v[4:5]
	v_pk_add_f32 v[6:7], v[6:7], v[2:3]
	ds_read_b128 v[2:5], v38 offset:36864
	s_waitcnt lgkmcnt(0)
	v_pk_add_f32 v[20:21], v[20:21], v[4:5]
	v_pk_add_f32 v[18:19], v[18:19], v[2:3]
	ds_read_b128 v[2:5], v38 offset:37888
	s_waitcnt lgkmcnt(0)
	v_pk_add_f32 v[2:3], v[6:7], v[2:3]
	v_lshl_add_u64 v[6:7], v[10:11], 2, s[6:7]
	global_load_dword v6, v[6:7], off
	v_pk_add_f32 v[4:5], v[8:9], v[4:5]
	s_waitcnt vmcnt(0)
	v_fma_f32 v7, v15, v18, v6
	v_mul_f32_e32 v7, 0xbfb8aa3b, v7
	v_exp_f32_e32 v7, v7
	s_nop 0
	v_add_f32_e32 v7, 1.0, v7
	v_rcp_f32_e32 v7, v7
	s_nop 0
	v_fma_f32 v11, v2, v7, 0
	v_fma_f32 v2, v14, v19, v6
	v_mul_f32_e32 v2, 0xbfb8aa3b, v2
	v_exp_f32_e32 v2, v2
	s_nop 0
	v_add_f32_e32 v2, 1.0, v2
	v_rcp_f32_e32 v2, v2
	s_nop 0
	v_fma_f32 v17, v3, v2, 0
	v_fma_f32 v2, v13, v20, v6
	v_mul_f32_e32 v2, 0xbfb8aa3b, v2
	v_exp_f32_e32 v2, v2
	v_fmac_f32_e32 v6, v0, v21
	v_add_f32_e32 v2, 1.0, v2
	v_rcp_f32_e32 v2, v2
	s_nop 0
	v_fma_f32 v18, v4, v2, 0
	v_mul_f32_e32 v2, 0xbfb8aa3b, v6
	v_exp_f32_e32 v2, v2
	s_nop 0
	v_add_f32_e32 v2, 1.0, v2
	v_rcp_f32_e32 v2, v2
	s_nop 0
	v_fma_f32 v19, v5, v2, 0
	ds_read_b128 v[2:5], v38 offset:2048
	ds_read_b128 v[6:9], v38 offset:3072
	ds_read_b128 v[20:23], v38 offset:14336
	s_waitcnt lgkmcnt(0)
	v_pk_add_f32 v[22:23], v[4:5], v[22:23]
	v_pk_add_f32 v[20:21], v[2:3], v[20:21]
	ds_read_b128 v[2:5], v38 offset:15360
	s_waitcnt lgkmcnt(0)
	v_pk_add_f32 v[8:9], v[8:9], v[4:5]
	v_pk_add_f32 v[6:7], v[6:7], v[2:3]
	ds_read_b128 v[2:5], v38 offset:26624
	s_waitcnt lgkmcnt(0)
	v_pk_add_f32 v[22:23], v[22:23], v[4:5]
	v_pk_add_f32 v[20:21], v[20:21], v[2:3]
	ds_read_b128 v[2:5], v38 offset:27648
	s_waitcnt lgkmcnt(0)
	v_pk_add_f32 v[8:9], v[8:9], v[4:5]
	v_pk_add_f32 v[6:7], v[6:7], v[2:3]
	ds_read_b128 v[2:5], v38 offset:38912
	s_waitcnt lgkmcnt(0)
	v_pk_add_f32 v[22:23], v[22:23], v[4:5]
	v_pk_add_f32 v[20:21], v[20:21], v[2:3]
	ds_read_b128 v[2:5], v38 offset:39936
	s_waitcnt lgkmcnt(0)
	v_pk_add_f32 v[2:3], v[6:7], v[2:3]
	v_add_u32_e32 v6, 0x400, v10
	v_ashrrev_i32_e32 v7, 31, v6
	v_lshl_add_u64 v[6:7], v[6:7], 2, s[6:7]
	global_load_dword v6, v[6:7], off
	v_pk_add_f32 v[4:5], v[8:9], v[4:5]
	s_waitcnt vmcnt(0)
	v_fma_f32 v7, v15, v20, v6
	v_mul_f32_e32 v7, 0xbfb8aa3b, v7
	v_exp_f32_e32 v7, v7
	s_nop 0
	v_add_f32_e32 v7, 1.0, v7
	v_rcp_f32_e32 v7, v7
	s_nop 0
	v_fmac_f32_e32 v11, v2, v7
	v_fma_f32 v2, v14, v21, v6
	v_mul_f32_e32 v2, 0xbfb8aa3b, v2
	v_exp_f32_e32 v2, v2
	s_nop 0
	v_add_f32_e32 v2, 1.0, v2
	v_rcp_f32_e32 v2, v2
	s_nop 0
	v_fmac_f32_e32 v17, v3, v2
	v_fma_f32 v2, v13, v22, v6
	v_mul_f32_e32 v2, 0xbfb8aa3b, v2
	v_exp_f32_e32 v2, v2
	v_fmac_f32_e32 v6, v0, v23
	v_add_f32_e32 v2, 1.0, v2
	v_rcp_f32_e32 v2, v2
	s_nop 0
	v_fmac_f32_e32 v18, v4, v2
	v_mul_f32_e32 v2, 0xbfb8aa3b, v6
	v_exp_f32_e32 v2, v2
	s_nop 0
	v_add_f32_e32 v2, 1.0, v2
	v_rcp_f32_e32 v2, v2
	s_nop 0
	v_fmac_f32_e32 v19, v5, v2
	ds_read_b128 v[2:5], v38 offset:4096
	ds_read_b128 v[6:9], v38 offset:5120
	ds_read_b128 v[20:23], v38 offset:16384
	s_waitcnt lgkmcnt(0)
	v_pk_add_f32 v[22:23], v[4:5], v[22:23]
	v_pk_add_f32 v[20:21], v[2:3], v[20:21]
	ds_read_b128 v[2:5], v38 offset:17408
	s_waitcnt lgkmcnt(0)
	v_pk_add_f32 v[8:9], v[8:9], v[4:5]
	v_pk_add_f32 v[6:7], v[6:7], v[2:3]
	ds_read_b128 v[2:5], v38 offset:28672
	s_waitcnt lgkmcnt(0)
	v_pk_add_f32 v[22:23], v[22:23], v[4:5]
	v_pk_add_f32 v[20:21], v[20:21], v[2:3]
	ds_read_b128 v[2:5], v38 offset:29696
	s_waitcnt lgkmcnt(0)
	v_pk_add_f32 v[24:25], v[8:9], v[4:5]
	v_pk_add_f32 v[6:7], v[6:7], v[2:3]
	ds_read_b128 v[2:5], v38 offset:40960
	s_waitcnt lgkmcnt(0)
	v_pk_add_f32 v[4:5], v[22:23], v[4:5]
	v_pk_add_f32 v[8:9], v[20:21], v[2:3]
	ds_read_b128 v[20:23], v38 offset:41984
	s_waitcnt lgkmcnt(0)
	v_pk_add_f32 v[6:7], v[6:7], v[20:21]
	v_add_u32_e32 v20, 0x800, v10
	v_ashrrev_i32_e32 v21, 31, v20
	v_lshl_add_u64 v[20:21], v[20:21], 2, s[6:7]
	global_load_dword v10, v[20:21], off
	v_pk_add_f32 v[2:3], v[24:25], v[22:23]
	s_waitcnt vmcnt(0)
	v_fma_f32 v8, v15, v8, v10
	v_mul_f32_e32 v8, 0xbfb8aa3b, v8
	v_exp_f32_e32 v8, v8
	v_fma_f32 v4, v13, v4, v10
	v_mul_f32_e32 v4, 0xbfb8aa3b, v4
	v_exp_f32_e32 v4, v4
	v_add_f32_e32 v8, 1.0, v8
	v_rcp_f32_e32 v8, v8
	v_add_f32_e32 v4, 1.0, v4
	v_rcp_f32_e32 v4, v4
	v_fmac_f32_e32 v11, v6, v8
	v_fma_f32 v6, v14, v9, v10
	v_fmac_f32_e32 v10, v0, v5
	v_mul_f32_e32 v0, 0xbfb8aa3b, v10
	v_exp_f32_e32 v0, v0
	v_mul_f32_e32 v6, 0xbfb8aa3b, v6
	v_exp_f32_e32 v6, v6
	v_fmac_f32_e32 v18, v2, v4
	v_add_f32_e32 v0, 1.0, v0
	v_rcp_f32_e32 v0, v0
	v_add_f32_e32 v6, 1.0, v6
	v_rcp_f32_e32 v6, v6
	v_fmac_f32_e32 v19, v3, v0
	v_lshlrev_b32_e32 v0, 1, v16
	v_lshl_add_u64 v[2:3], s[4:5], 0, v[0:1]
	v_lshlrev_b32_e32 v0, 11, v12
	v_fmac_f32_e32 v17, v7, v6
	v_cvt_pk_bf16_f32 v6, v11, s0
	v_lshl_add_u64 v[4:5], v[2:3], 0, v[0:1]
	global_store_short v[4:5], v6, off
	v_cvt_pk_bf16_f32 v6, v17, s0
	v_or_b32_e32 v0, 0x1000, v0
	global_store_short v[4:5], v6, off offset:2048
	v_cvt_pk_bf16_f32 v6, v18, s0
	v_lshl_add_u64 v[2:3], v[2:3], 0, v[0:1]
	global_store_short v[2:3], v6, off
	v_add_co_u32_e32 v2, vcc, 0x1000, v4
	v_cvt_pk_bf16_f32 v0, v19, s0
	s_nop 0
	v_addc_co_u32_e32 v3, vcc, 0, v5, vcc
	global_store_short v[2:3], v0, off offset:2048
	s_branch .LBB0_17

.LBB0_186:
	v_mbcnt_lo_u32_b32 v0, -1, 0
	v_mbcnt_hi_u32_b32 v0, -1, v0
	v_readlane_b32 s6, v253, 15
	v_readlane_b32 s8, v254, 0
	v_readlane_b32 s9, v254, 1
	v_readlane_b32 s10, v254, 2
	v_readlane_b32 s11, v254, 3
	v_readlane_b32 s12, v252, 39
	v_readlane_b32 s13, v252, 40
	v_add_u32_e32 v2, s6, v0
	s_lshr_b32 s18, s6, 6
	v_ashrrev_i32_e32 v248, 3, v2
	v_and_b32_e32 v0, 7, v2
	v_lshlrev_b32_e32 v247, 4, v2
	v_lshlrev_b32_e32 v249, 4, v0
	v_lshlrev_b32_e32 v0, 3, v0
	s_lshr_b32 s7, s43, 5
	s_mul_i32 s7, s7, 0x810
	s_lshl_b32 s14, s43, 6
	s_and_b32 s14, s14, 0x7c0
	v_mul_u32_u24_e32 v3, 34, v248
	v_add_u32_e32 v3, s7, v3
	v_lshlrev_b32_e32 v3, 11, v3
	v_add3_u32 v3, v3, s14, v0
	v_mov_b32_e32 v2, v3
	global_load_dwordx2 v[4:5], v2, s[8:9]
	global_load_dwordx2 v[72:73], v2, s[10:11]
	global_load_dwordx2 v[6:7], v2, s[8:9] offset:2048
	global_load_dwordx2 v[74:75], v2, s[10:11] offset:2048
	v_add_u32_e32 v2, 0x1000, v3
	global_load_dwordx2 v[8:9], v2, s[8:9]
	global_load_dwordx2 v[76:77], v2, s[10:11]
	global_load_dwordx2 v[10:11], v2, s[8:9] offset:2048
	global_load_dwordx2 v[78:79], v2, s[10:11] offset:2048
	v_add_u32_e32 v2, 0x2000, v3
	global_load_dwordx2 v[12:13], v2, s[8:9]
	global_load_dwordx2 v[80:81], v2, s[10:11]
	global_load_dwordx2 v[14:15], v2, s[8:9] offset:2048
	global_load_dwordx2 v[82:83], v2, s[10:11] offset:2048
	v_add_u32_e32 v2, 0x3000, v3
	global_load_dwordx2 v[16:17], v2, s[8:9]
	global_load_dwordx2 v[84:85], v2, s[10:11]
	global_load_dwordx2 v[18:19], v2, s[8:9] offset:2048
	global_load_dwordx2 v[86:87], v2, s[10:11] offset:2048
	v_add_u32_e32 v2, 0x4000, v3
	global_load_dwordx2 v[20:21], v2, s[8:9]
	global_load_dwordx2 v[88:89], v2, s[10:11]
	global_load_dwordx2 v[22:23], v2, s[8:9] offset:2048
	global_load_dwordx2 v[90:91], v2, s[10:11] offset:2048
	v_add_u32_e32 v2, 0x5000, v3
	global_load_dwordx2 v[24:25], v2, s[8:9]
	global_load_dwordx2 v[92:93], v2, s[10:11]
	global_load_dwordx2 v[26:27], v2, s[8:9] offset:2048
	global_load_dwordx2 v[94:95], v2, s[10:11] offset:2048
	v_add_u32_e32 v2, 0x6000, v3
	global_load_dwordx2 v[28:29], v2, s[8:9]
	global_load_dwordx2 v[96:97], v2, s[10:11]
	global_load_dwordx2 v[30:31], v2, s[8:9] offset:2048
	global_load_dwordx2 v[98:99], v2, s[10:11] offset:2048
	v_add_u32_e32 v2, 0x7000, v3
	global_load_dwordx2 v[32:33], v2, s[8:9]
	global_load_dwordx2 v[100:101], v2, s[10:11]
	global_load_dwordx2 v[34:35], v2, s[8:9] offset:2048
	global_load_dwordx2 v[102:103], v2, s[10:11] offset:2048
	v_add_u32_e32 v2, 0x8000, v3
	global_load_dwordx2 v[36:37], v2, s[8:9]
	global_load_dwordx2 v[104:105], v2, s[10:11]
	global_load_dwordx2 v[38:39], v2, s[8:9] offset:2048
	global_load_dwordx2 v[106:107], v2, s[10:11] offset:2048
	v_add_u32_e32 v2, 0x9000, v3
	global_load_dwordx2 v[40:41], v2, s[8:9]
	global_load_dwordx2 v[108:109], v2, s[10:11]
	global_load_dwordx2 v[42:43], v2, s[8:9] offset:2048
	global_load_dwordx2 v[110:111], v2, s[10:11] offset:2048
	v_add_u32_e32 v2, 0xa000, v3
	global_load_dwordx2 v[44:45], v2, s[8:9]
	global_load_dwordx2 v[112:113], v2, s[10:11]
	global_load_dwordx2 v[46:47], v2, s[8:9] offset:2048
	global_load_dwordx2 v[114:115], v2, s[10:11] offset:2048
	v_add_u32_e32 v2, 0xb000, v3
	global_load_dwordx2 v[48:49], v2, s[8:9]
	global_load_dwordx2 v[116:117], v2, s[10:11]
	global_load_dwordx2 v[50:51], v2, s[8:9] offset:2048
	global_load_dwordx2 v[118:119], v2, s[10:11] offset:2048
	v_add_u32_e32 v2, 0xc000, v3
	global_load_dwordx2 v[52:53], v2, s[8:9]
	global_load_dwordx2 v[120:121], v2, s[10:11]
	global_load_dwordx2 v[54:55], v2, s[8:9] offset:2048
	global_load_dwordx2 v[122:123], v2, s[10:11] offset:2048
	v_add_u32_e32 v2, 0xd000, v3
	global_load_dwordx2 v[56:57], v2, s[8:9]
	global_load_dwordx2 v[124:125], v2, s[10:11]
	global_load_dwordx2 v[58:59], v2, s[8:9] offset:2048
	global_load_dwordx2 v[126:127], v2, s[10:11] offset:2048
	v_add_u32_e32 v2, 0xe000, v3
	global_load_dwordx2 v[60:61], v2, s[8:9]
	global_load_dwordx2 v[128:129], v2, s[10:11]
	global_load_dwordx2 v[62:63], v2, s[8:9] offset:2048
	global_load_dwordx2 v[130:131], v2, s[10:11] offset:2048
	v_mov_b32_e32 v208, 1.0
	v_mov_b32_e32 v209, 1.0
	v_mov_b32_e32 v210, 1.0
	v_mov_b32_e32 v211, 1.0
	v_mov_b32_e32 v212, 0
	v_mov_b32_e32 v213, 0
	v_mov_b32_e32 v214, 0
	v_mov_b32_e32 v215, 0
	s_waitcnt vmcnt(58)
	v_lshlrev_b32_e32 v216, 16, v4
	v_and_b32_e32 v217, 0xffff0000, v4
	v_lshlrev_b32_e32 v218, 16, v5
	v_and_b32_e32 v219, 0xffff0000, v5
	v_exp_f32_e32 v216, v216
	v_exp_f32_e32 v217, v217
	v_exp_f32_e32 v218, v218
	v_exp_f32_e32 v219, v219
	v_lshlrev_b32_e32 v220, 16, v72
	v_and_b32_e32 v221, 0xffff0000, v72
	v_lshlrev_b32_e32 v222, 16, v73
	v_and_b32_e32 v223, 0xffff0000, v73
	v_fma_f32 v212, v216, v212, v220
	v_fma_f32 v213, v217, v213, v221
	v_fma_f32 v214, v218, v214, v222
	v_fma_f32 v215, v219, v215, v223
	v_mul_f32_e32 v208, v208, v216
	v_mul_f32_e32 v209, v209, v217
	v_mul_f32_e32 v210, v210, v218
	v_mul_f32_e32 v211, v211, v219
	v_add_u32_e32 v2, 0xf000, v3
	global_load_dwordx2 v[64:65], v2, s[8:9]
	global_load_dwordx2 v[132:133], v2, s[10:11]
	s_waitcnt vmcnt(58)
	v_lshlrev_b32_e32 v216, 16, v6
	v_and_b32_e32 v217, 0xffff0000, v6
	v_lshlrev_b32_e32 v218, 16, v7
	v_and_b32_e32 v219, 0xffff0000, v7
	v_exp_f32_e32 v216, v216
	v_exp_f32_e32 v217, v217
	v_exp_f32_e32 v218, v218
	v_exp_f32_e32 v219, v219
	v_lshlrev_b32_e32 v220, 16, v74
	v_and_b32_e32 v221, 0xffff0000, v74
	v_lshlrev_b32_e32 v222, 16, v75
	v_and_b32_e32 v223, 0xffff0000, v75
	v_fma_f32 v212, v216, v212, v220
	v_fma_f32 v213, v217, v213, v221
	v_fma_f32 v214, v218, v214, v222
	v_fma_f32 v215, v219, v215, v223
	v_mul_f32_e32 v208, v208, v216
	v_mul_f32_e32 v209, v209, v217
	v_mul_f32_e32 v210, v210, v218
	v_mul_f32_e32 v211, v211, v219
	global_load_dwordx2 v[66:67], v2, s[8:9] offset:2048
	global_load_dwordx2 v[134:135], v2, s[10:11] offset:2048
	s_waitcnt vmcnt(58)
	v_lshlrev_b32_e32 v216, 16, v8
	v_and_b32_e32 v217, 0xffff0000, v8
	v_lshlrev_b32_e32 v218, 16, v9
	v_and_b32_e32 v219, 0xffff0000, v9
	v_exp_f32_e32 v216, v216
	v_exp_f32_e32 v217, v217
	v_exp_f32_e32 v218, v218
	v_exp_f32_e32 v219, v219
	v_lshlrev_b32_e32 v220, 16, v76
	v_and_b32_e32 v221, 0xffff0000, v76
	v_lshlrev_b32_e32 v222, 16, v77
	v_and_b32_e32 v223, 0xffff0000, v77
	v_fma_f32 v212, v216, v212, v220
	v_fma_f32 v213, v217, v213, v221
	v_fma_f32 v214, v218, v214, v222
	v_fma_f32 v215, v219, v215, v223
	v_mul_f32_e32 v208, v208, v216
	v_mul_f32_e32 v209, v209, v217
	v_mul_f32_e32 v210, v210, v218
	v_mul_f32_e32 v211, v211, v219
	v_add_u32_e32 v2, 0x10000, v3
	global_load_dwordx2 v[68:69], v2, s[8:9]
	global_load_dwordx2 v[136:137], v2, s[10:11]
	s_waitcnt vmcnt(58)
	v_lshlrev_b32_e32 v216, 16, v10
	v_and_b32_e32 v217, 0xffff0000, v10
	v_lshlrev_b32_e32 v218, 16, v11
	v_and_b32_e32 v219, 0xffff0000, v11
	v_exp_f32_e32 v216, v216
	v_exp_f32_e32 v217, v217
	v_exp_f32_e32 v218, v218
	v_exp_f32_e32 v219, v219
	v_lshlrev_b32_e32 v220, 16, v78
	v_and_b32_e32 v221, 0xffff0000, v78
	v_lshlrev_b32_e32 v222, 16, v79
	v_and_b32_e32 v223, 0xffff0000, v79
	v_fma_f32 v212, v216, v212, v220
	v_fma_f32 v213, v217, v213, v221
	v_fma_f32 v214, v218, v214, v222
	v_fma_f32 v215, v219, v215, v223
	v_mul_f32_e32 v208, v208, v216
	v_mul_f32_e32 v209, v209, v217
	v_mul_f32_e32 v210, v210, v218
	v_mul_f32_e32 v211, v211, v219
	global_load_dwordx2 v[70:71], v2, s[8:9] offset:2048
	global_load_dwordx2 v[138:139], v2, s[10:11] offset:2048
	s_waitcnt vmcnt(58)
	v_lshlrev_b32_e32 v216, 16, v12
	v_and_b32_e32 v217, 0xffff0000, v12
	v_lshlrev_b32_e32 v218, 16, v13
	v_and_b32_e32 v219, 0xffff0000, v13
	v_exp_f32_e32 v216, v216
	v_exp_f32_e32 v217, v217
	v_exp_f32_e32 v218, v218
	v_exp_f32_e32 v219, v219
	v_lshlrev_b32_e32 v220, 16, v80
	v_and_b32_e32 v221, 0xffff0000, v80
	v_lshlrev_b32_e32 v222, 16, v81
	v_and_b32_e32 v223, 0xffff0000, v81
	v_fma_f32 v212, v216, v212, v220
	v_fma_f32 v213, v217, v213, v221
	v_fma_f32 v214, v218, v214, v222
	v_fma_f32 v215, v219, v215, v223
	v_mul_f32_e32 v208, v208, v216
	v_mul_f32_e32 v209, v209, v217
	v_mul_f32_e32 v210, v210, v218
	v_mul_f32_e32 v211, v211, v219
	v_mov_b32_e32 v2, v3
	global_load_dwordx2 v[140:141], v2, s[12:13]
	global_load_dwordx2 v[142:143], v2, s[12:13] offset:2048
	s_waitcnt vmcnt(58)
	v_lshlrev_b32_e32 v216, 16, v14
	v_and_b32_e32 v217, 0xffff0000, v14
	v_lshlrev_b32_e32 v218, 16, v15
	v_and_b32_e32 v219, 0xffff0000, v15
	v_exp_f32_e32 v216, v216
	v_exp_f32_e32 v217, v217
	v_exp_f32_e32 v218, v218
	v_exp_f32_e32 v219, v219
	v_lshlrev_b32_e32 v220, 16, v82
	v_and_b32_e32 v221, 0xffff0000, v82
	v_lshlrev_b32_e32 v222, 16, v83
	v_and_b32_e32 v223, 0xffff0000, v83
	v_fma_f32 v212, v216, v212, v220
	v_fma_f32 v213, v217, v213, v221
	v_fma_f32 v214, v218, v214, v222
	v_fma_f32 v215, v219, v215, v223
	v_mul_f32_e32 v208, v208, v216
	v_mul_f32_e32 v209, v209, v217
	v_mul_f32_e32 v210, v210, v218
	v_mul_f32_e32 v211, v211, v219
	v_add_u32_e32 v2, 0x1000, v3
	global_load_dwordx2 v[144:145], v2, s[12:13]
	global_load_dwordx2 v[146:147], v2, s[12:13] offset:2048
	s_waitcnt vmcnt(58)
	v_lshlrev_b32_e32 v216, 16, v16
	v_and_b32_e32 v217, 0xffff0000, v16
	v_lshlrev_b32_e32 v218, 16, v17
	v_and_b32_e32 v219, 0xffff0000, v17
	v_exp_f32_e32 v216, v216
	v_exp_f32_e32 v217, v217
	v_exp_f32_e32 v218, v218
	v_exp_f32_e32 v219, v219
	v_lshlrev_b32_e32 v220, 16, v84
	v_and_b32_e32 v221, 0xffff0000, v84
	v_lshlrev_b32_e32 v222, 16, v85
	v_and_b32_e32 v223, 0xffff0000, v85
	v_fma_f32 v212, v216, v212, v220
	v_fma_f32 v213, v217, v213, v221
	v_fma_f32 v214, v218, v214, v222
	v_fma_f32 v215, v219, v215, v223
	v_mul_f32_e32 v208, v208, v216
	v_mul_f32_e32 v209, v209, v217
	v_mul_f32_e32 v210, v210, v218
	v_mul_f32_e32 v211, v211, v219
	v_add_u32_e32 v2, 0x2000, v3
	global_load_dwordx2 v[148:149], v2, s[12:13]
	global_load_dwordx2 v[150:151], v2, s[12:13] offset:2048
	s_waitcnt vmcnt(58)
	v_lshlrev_b32_e32 v216, 16, v18
	v_and_b32_e32 v217, 0xffff0000, v18
	v_lshlrev_b32_e32 v218, 16, v19
	v_and_b32_e32 v219, 0xffff0000, v19
	v_exp_f32_e32 v216, v216
	v_exp_f32_e32 v217, v217
	v_exp_f32_e32 v218, v218
	v_exp_f32_e32 v219, v219
	v_lshlrev_b32_e32 v220, 16, v86
	v_and_b32_e32 v221, 0xffff0000, v86
	v_lshlrev_b32_e32 v222, 16, v87
	v_and_b32_e32 v223, 0xffff0000, v87
	v_fma_f32 v212, v216, v212, v220
	v_fma_f32 v213, v217, v213, v221
	v_fma_f32 v214, v218, v214, v222
	v_fma_f32 v215, v219, v215, v223
	v_mul_f32_e32 v208, v208, v216
	v_mul_f32_e32 v209, v209, v217
	v_mul_f32_e32 v210, v210, v218
	v_mul_f32_e32 v211, v211, v219
	v_add_u32_e32 v2, 0x3000, v3
	global_load_dwordx2 v[152:153], v2, s[12:13]
	global_load_dwordx2 v[154:155], v2, s[12:13] offset:2048
	s_waitcnt vmcnt(58)
	v_lshlrev_b32_e32 v216, 16, v20
	v_and_b32_e32 v217, 0xffff0000, v20
	v_lshlrev_b32_e32 v218, 16, v21
	v_and_b32_e32 v219, 0xffff0000, v21
	v_exp_f32_e32 v216, v216
	v_exp_f32_e32 v217, v217
	v_exp_f32_e32 v218, v218
	v_exp_f32_e32 v219, v219
	v_lshlrev_b32_e32 v220, 16, v88
	v_and_b32_e32 v221, 0xffff0000, v88
	v_lshlrev_b32_e32 v222, 16, v89
	v_and_b32_e32 v223, 0xffff0000, v89
	v_fma_f32 v212, v216, v212, v220
	v_fma_f32 v213, v217, v213, v221
	v_fma_f32 v214, v218, v214, v222
	v_fma_f32 v215, v219, v215, v223
	v_mul_f32_e32 v208, v208, v216
	v_mul_f32_e32 v209, v209, v217
	v_mul_f32_e32 v210, v210, v218
	v_mul_f32_e32 v211, v211, v219
	v_add_u32_e32 v2, 0x4000, v3
	global_load_dwordx2 v[156:157], v2, s[12:13]
	global_load_dwordx2 v[158:159], v2, s[12:13] offset:2048
	s_waitcnt vmcnt(58)
	v_lshlrev_b32_e32 v216, 16, v22
	v_and_b32_e32 v217, 0xffff0000, v22
	v_lshlrev_b32_e32 v218, 16, v23
	v_and_b32_e32 v219, 0xffff0000, v23
	v_exp_f32_e32 v216, v216
	v_exp_f32_e32 v217, v217
	v_exp_f32_e32 v218, v218
	v_exp_f32_e32 v219, v219
	v_lshlrev_b32_e32 v220, 16, v90
	v_and_b32_e32 v221, 0xffff0000, v90
	v_lshlrev_b32_e32 v222, 16, v91
	v_and_b32_e32 v223, 0xffff0000, v91
	v_fma_f32 v212, v216, v212, v220
	v_fma_f32 v213, v217, v213, v221
	v_fma_f32 v214, v218, v214, v222
	v_fma_f32 v215, v219, v215, v223
	v_mul_f32_e32 v208, v208, v216
	v_mul_f32_e32 v209, v209, v217
	v_mul_f32_e32 v210, v210, v218
	v_mul_f32_e32 v211, v211, v219
	v_add_u32_e32 v2, 0x5000, v3
	global_load_dwordx2 v[160:161], v2, s[12:13]
	global_load_dwordx2 v[162:163], v2, s[12:13] offset:2048
	s_waitcnt vmcnt(58)
	v_lshlrev_b32_e32 v216, 16, v24
	v_and_b32_e32 v217, 0xffff0000, v24
	v_lshlrev_b32_e32 v218, 16, v25
	v_and_b32_e32 v219, 0xffff0000, v25
	v_exp_f32_e32 v216, v216
	v_exp_f32_e32 v217, v217
	v_exp_f32_e32 v218, v218
	v_exp_f32_e32 v219, v219
	v_lshlrev_b32_e32 v220, 16, v92
	v_and_b32_e32 v221, 0xffff0000, v92
	v_lshlrev_b32_e32 v222, 16, v93
	v_and_b32_e32 v223, 0xffff0000, v93
	v_fma_f32 v212, v216, v212, v220
	v_fma_f32 v213, v217, v213, v221
	v_fma_f32 v214, v218, v214, v222
	v_fma_f32 v215, v219, v215, v223
	v_mul_f32_e32 v208, v208, v216
	v_mul_f32_e32 v209, v209, v217
	v_mul_f32_e32 v210, v210, v218
	v_mul_f32_e32 v211, v211, v219
	v_add_u32_e32 v2, 0x6000, v3
	global_load_dwordx2 v[164:165], v2, s[12:13]
	global_load_dwordx2 v[166:167], v2, s[12:13] offset:2048
	s_waitcnt vmcnt(58)
	v_lshlrev_b32_e32 v216, 16, v26
	v_and_b32_e32 v217, 0xffff0000, v26
	v_lshlrev_b32_e32 v218, 16, v27
	v_and_b32_e32 v219, 0xffff0000, v27
	v_exp_f32_e32 v216, v216
	v_exp_f32_e32 v217, v217
	v_exp_f32_e32 v218, v218
	v_exp_f32_e32 v219, v219
	v_lshlrev_b32_e32 v220, 16, v94
	v_and_b32_e32 v221, 0xffff0000, v94
	v_lshlrev_b32_e32 v222, 16, v95
	v_and_b32_e32 v223, 0xffff0000, v95
	v_fma_f32 v212, v216, v212, v220
	v_fma_f32 v213, v217, v213, v221
	v_fma_f32 v214, v218, v214, v222
	v_fma_f32 v215, v219, v215, v223
	v_mul_f32_e32 v208, v208, v216
	v_mul_f32_e32 v209, v209, v217
	v_mul_f32_e32 v210, v210, v218
	v_mul_f32_e32 v211, v211, v219
	v_add_u32_e32 v2, 0x7000, v3
	global_load_dwordx2 v[168:169], v2, s[12:13]
	global_load_dwordx2 v[170:171], v2, s[12:13] offset:2048
	s_waitcnt vmcnt(58)
	v_lshlrev_b32_e32 v216, 16, v28
	v_and_b32_e32 v217, 0xffff0000, v28
	v_lshlrev_b32_e32 v218, 16, v29
	v_and_b32_e32 v219, 0xffff0000, v29
	v_exp_f32_e32 v216, v216
	v_exp_f32_e32 v217, v217
	v_exp_f32_e32 v218, v218
	v_exp_f32_e32 v219, v219
	v_lshlrev_b32_e32 v220, 16, v96
	v_and_b32_e32 v221, 0xffff0000, v96
	v_lshlrev_b32_e32 v222, 16, v97
	v_and_b32_e32 v223, 0xffff0000, v97
	v_fma_f32 v212, v216, v212, v220
	v_fma_f32 v213, v217, v213, v221
	v_fma_f32 v214, v218, v214, v222
	v_fma_f32 v215, v219, v215, v223
	v_mul_f32_e32 v208, v208, v216
	v_mul_f32_e32 v209, v209, v217
	v_mul_f32_e32 v210, v210, v218
	v_mul_f32_e32 v211, v211, v219
	v_add_u32_e32 v2, 0x8000, v3
	global_load_dwordx2 v[172:173], v2, s[12:13]
	global_load_dwordx2 v[174:175], v2, s[12:13] offset:2048
	s_waitcnt vmcnt(58)
	v_lshlrev_b32_e32 v216, 16, v30
	v_and_b32_e32 v217, 0xffff0000, v30
	v_lshlrev_b32_e32 v218, 16, v31
	v_and_b32_e32 v219, 0xffff0000, v31
	v_exp_f32_e32 v216, v216
	v_exp_f32_e32 v217, v217
	v_exp_f32_e32 v218, v218
	v_exp_f32_e32 v219, v219
	v_lshlrev_b32_e32 v220, 16, v98
	v_and_b32_e32 v221, 0xffff0000, v98
	v_lshlrev_b32_e32 v222, 16, v99
	v_and_b32_e32 v223, 0xffff0000, v99
	v_fma_f32 v212, v216, v212, v220
	v_fma_f32 v213, v217, v213, v221
	v_fma_f32 v214, v218, v214, v222
	v_fma_f32 v215, v219, v215, v223
	v_mul_f32_e32 v208, v208, v216
	v_mul_f32_e32 v209, v209, v217
	v_mul_f32_e32 v210, v210, v218
	v_mul_f32_e32 v211, v211, v219
	v_add_u32_e32 v2, 0x9000, v3
	global_load_dwordx2 v[176:177], v2, s[12:13]
	global_load_dwordx2 v[178:179], v2, s[12:13] offset:2048
	s_waitcnt vmcnt(58)
	v_lshlrev_b32_e32 v216, 16, v32
	v_and_b32_e32 v217, 0xffff0000, v32
	v_lshlrev_b32_e32 v218, 16, v33
	v_and_b32_e32 v219, 0xffff0000, v33
	v_exp_f32_e32 v216, v216
	v_exp_f32_e32 v217, v217
	v_exp_f32_e32 v218, v218
	v_exp_f32_e32 v219, v219
	v_lshlrev_b32_e32 v220, 16, v100
	v_and_b32_e32 v221, 0xffff0000, v100
	v_lshlrev_b32_e32 v222, 16, v101
	v_and_b32_e32 v223, 0xffff0000, v101
	v_fma_f32 v212, v216, v212, v220
	v_fma_f32 v213, v217, v213, v221
	v_fma_f32 v214, v218, v214, v222
	v_fma_f32 v215, v219, v215, v223
	v_mul_f32_e32 v208, v208, v216
	v_mul_f32_e32 v209, v209, v217
	v_mul_f32_e32 v210, v210, v218
	v_mul_f32_e32 v211, v211, v219
	v_add_u32_e32 v2, 0xa000, v3
	global_load_dwordx2 v[180:181], v2, s[12:13]
	global_load_dwordx2 v[182:183], v2, s[12:13] offset:2048
	s_waitcnt vmcnt(58)
	v_lshlrev_b32_e32 v216, 16, v34
	v_and_b32_e32 v217, 0xffff0000, v34
	v_lshlrev_b32_e32 v218, 16, v35
	v_and_b32_e32 v219, 0xffff0000, v35
	v_exp_f32_e32 v216, v216
	v_exp_f32_e32 v217, v217
	v_exp_f32_e32 v218, v218
	v_exp_f32_e32 v219, v219
	v_lshlrev_b32_e32 v220, 16, v102
	v_and_b32_e32 v221, 0xffff0000, v102
	v_lshlrev_b32_e32 v222, 16, v103
	v_and_b32_e32 v223, 0xffff0000, v103
	v_fma_f32 v212, v216, v212, v220
	v_fma_f32 v213, v217, v213, v221
	v_fma_f32 v214, v218, v214, v222
	v_fma_f32 v215, v219, v215, v223
	v_mul_f32_e32 v208, v208, v216
	v_mul_f32_e32 v209, v209, v217
	v_mul_f32_e32 v210, v210, v218
	v_mul_f32_e32 v211, v211, v219
	v_add_u32_e32 v2, 0xb000, v3
	global_load_dwordx2 v[184:185], v2, s[12:13]
	global_load_dwordx2 v[186:187], v2, s[12:13] offset:2048
	s_waitcnt vmcnt(58)
	v_lshlrev_b32_e32 v216, 16, v36
	v_and_b32_e32 v217, 0xffff0000, v36
	v_lshlrev_b32_e32 v218, 16, v37
	v_and_b32_e32 v219, 0xffff0000, v37
	v_exp_f32_e32 v216, v216
	v_exp_f32_e32 v217, v217
	v_exp_f32_e32 v218, v218
	v_exp_f32_e32 v219, v219
	v_lshlrev_b32_e32 v220, 16, v104
	v_and_b32_e32 v221, 0xffff0000, v104
	v_lshlrev_b32_e32 v222, 16, v105
	v_and_b32_e32 v223, 0xffff0000, v105
	v_fma_f32 v212, v216, v212, v220
	v_fma_f32 v213, v217, v213, v221
	v_fma_f32 v214, v218, v214, v222
	v_fma_f32 v215, v219, v215, v223
	v_mul_f32_e32 v208, v208, v216
	v_mul_f32_e32 v209, v209, v217
	v_mul_f32_e32 v210, v210, v218
	v_mul_f32_e32 v211, v211, v219
	v_add_u32_e32 v2, 0xc000, v3
	global_load_dwordx2 v[188:189], v2, s[12:13]
	global_load_dwordx2 v[190:191], v2, s[12:13] offset:2048
	s_waitcnt vmcnt(58)
	v_lshlrev_b32_e32 v216, 16, v38
	v_and_b32_e32 v217, 0xffff0000, v38
	v_lshlrev_b32_e32 v218, 16, v39
	v_and_b32_e32 v219, 0xffff0000, v39
	v_exp_f32_e32 v216, v216
	v_exp_f32_e32 v217, v217
	v_exp_f32_e32 v218, v218
	v_exp_f32_e32 v219, v219
	v_lshlrev_b32_e32 v220, 16, v106
	v_and_b32_e32 v221, 0xffff0000, v106
	v_lshlrev_b32_e32 v222, 16, v107
	v_and_b32_e32 v223, 0xffff0000, v107
	v_fma_f32 v212, v216, v212, v220
	v_fma_f32 v213, v217, v213, v221
	v_fma_f32 v214, v218, v214, v222
	v_fma_f32 v215, v219, v215, v223
	v_mul_f32_e32 v208, v208, v216
	v_mul_f32_e32 v209, v209, v217
	v_mul_f32_e32 v210, v210, v218
	v_mul_f32_e32 v211, v211, v219
	v_add_u32_e32 v2, 0xd000, v3
	global_load_dwordx2 v[192:193], v2, s[12:13]
	global_load_dwordx2 v[194:195], v2, s[12:13] offset:2048
	s_waitcnt vmcnt(58)
	v_lshlrev_b32_e32 v216, 16, v40
	v_and_b32_e32 v217, 0xffff0000, v40
	v_lshlrev_b32_e32 v218, 16, v41
	v_and_b32_e32 v219, 0xffff0000, v41
	v_exp_f32_e32 v216, v216
	v_exp_f32_e32 v217, v217
	v_exp_f32_e32 v218, v218
	v_exp_f32_e32 v219, v219
	v_lshlrev_b32_e32 v220, 16, v108
	v_and_b32_e32 v221, 0xffff0000, v108
	v_lshlrev_b32_e32 v222, 16, v109
	v_and_b32_e32 v223, 0xffff0000, v109
	v_fma_f32 v212, v216, v212, v220
	v_fma_f32 v213, v217, v213, v221
	v_fma_f32 v214, v218, v214, v222
	v_fma_f32 v215, v219, v215, v223
	v_mul_f32_e32 v208, v208, v216
	v_mul_f32_e32 v209, v209, v217
	v_mul_f32_e32 v210, v210, v218
	v_mul_f32_e32 v211, v211, v219
	v_add_u32_e32 v2, 0xe000, v3
	global_load_dwordx2 v[196:197], v2, s[12:13]
	global_load_dwordx2 v[198:199], v2, s[12:13] offset:2048
	s_waitcnt vmcnt(58)
	v_lshlrev_b32_e32 v216, 16, v42
	v_and_b32_e32 v217, 0xffff0000, v42
	v_lshlrev_b32_e32 v218, 16, v43
	v_and_b32_e32 v219, 0xffff0000, v43
	v_exp_f32_e32 v216, v216
	v_exp_f32_e32 v217, v217
	v_exp_f32_e32 v218, v218
	v_exp_f32_e32 v219, v219
	v_lshlrev_b32_e32 v220, 16, v110
	v_and_b32_e32 v221, 0xffff0000, v110
	v_lshlrev_b32_e32 v222, 16, v111
	v_and_b32_e32 v223, 0xffff0000, v111
	v_fma_f32 v212, v216, v212, v220
	v_fma_f32 v213, v217, v213, v221
	v_fma_f32 v214, v218, v214, v222
	v_fma_f32 v215, v219, v215, v223
	v_mul_f32_e32 v208, v208, v216
	v_mul_f32_e32 v209, v209, v217
	v_mul_f32_e32 v210, v210, v218
	v_mul_f32_e32 v211, v211, v219
	v_add_u32_e32 v2, 0xf000, v3
	global_load_dwordx2 v[200:201], v2, s[12:13]
	global_load_dwordx2 v[202:203], v2, s[12:13] offset:2048
	s_waitcnt vmcnt(58)
	v_lshlrev_b32_e32 v216, 16, v44
	v_and_b32_e32 v217, 0xffff0000, v44
	v_lshlrev_b32_e32 v218, 16, v45
	v_and_b32_e32 v219, 0xffff0000, v45
	v_exp_f32_e32 v216, v216
	v_exp_f32_e32 v217, v217
	v_exp_f32_e32 v218, v218
	v_exp_f32_e32 v219, v219
	v_lshlrev_b32_e32 v220, 16, v112
	v_and_b32_e32 v221, 0xffff0000, v112
	v_lshlrev_b32_e32 v222, 16, v113
	v_and_b32_e32 v223, 0xffff0000, v113
	v_fma_f32 v212, v216, v212, v220
	v_fma_f32 v213, v217, v213, v221
	v_fma_f32 v214, v218, v214, v222
	v_fma_f32 v215, v219, v215, v223
	v_mul_f32_e32 v208, v208, v216
	v_mul_f32_e32 v209, v209, v217
	v_mul_f32_e32 v210, v210, v218
	v_mul_f32_e32 v211, v211, v219
	v_add_u32_e32 v2, 0x10000, v3
	global_load_dwordx2 v[204:205], v2, s[12:13]
	global_load_dwordx2 v[206:207], v2, s[12:13] offset:2048
	s_waitcnt vmcnt(58)
	v_lshlrev_b32_e32 v216, 16, v46
	v_and_b32_e32 v217, 0xffff0000, v46
	v_lshlrev_b32_e32 v218, 16, v47
	v_and_b32_e32 v219, 0xffff0000, v47
	v_exp_f32_e32 v216, v216
	v_exp_f32_e32 v217, v217
	v_exp_f32_e32 v218, v218
	v_exp_f32_e32 v219, v219
	v_lshlrev_b32_e32 v220, 16, v114
	v_and_b32_e32 v221, 0xffff0000, v114
	v_lshlrev_b32_e32 v222, 16, v115
	v_and_b32_e32 v223, 0xffff0000, v115
	v_fma_f32 v212, v216, v212, v220
	v_fma_f32 v213, v217, v213, v221
	v_fma_f32 v214, v218, v214, v222
	v_fma_f32 v215, v219, v215, v223
	v_mul_f32_e32 v208, v208, v216
	v_mul_f32_e32 v209, v209, v217
	v_mul_f32_e32 v210, v210, v218
	v_mul_f32_e32 v211, v211, v219
	s_waitcnt vmcnt(56)
	v_lshlrev_b32_e32 v216, 16, v48
	v_and_b32_e32 v217, 0xffff0000, v48
	v_lshlrev_b32_e32 v218, 16, v49
	v_and_b32_e32 v219, 0xffff0000, v49
	v_exp_f32_e32 v216, v216
	v_exp_f32_e32 v217, v217
	v_exp_f32_e32 v218, v218
	v_exp_f32_e32 v219, v219
	v_lshlrev_b32_e32 v220, 16, v116
	v_and_b32_e32 v221, 0xffff0000, v116
	v_lshlrev_b32_e32 v222, 16, v117
	v_and_b32_e32 v223, 0xffff0000, v117
	v_fma_f32 v212, v216, v212, v220
	v_fma_f32 v213, v217, v213, v221
	v_fma_f32 v214, v218, v214, v222
	v_fma_f32 v215, v219, v215, v223
	v_mul_f32_e32 v208, v208, v216
	v_mul_f32_e32 v209, v209, v217
	v_mul_f32_e32 v210, v210, v218
	v_mul_f32_e32 v211, v211, v219
	s_waitcnt vmcnt(54)
	v_lshlrev_b32_e32 v216, 16, v50
	v_and_b32_e32 v217, 0xffff0000, v50
	v_lshlrev_b32_e32 v218, 16, v51
	v_and_b32_e32 v219, 0xffff0000, v51
	v_exp_f32_e32 v216, v216
	v_exp_f32_e32 v217, v217
	v_exp_f32_e32 v218, v218
	v_exp_f32_e32 v219, v219
	v_lshlrev_b32_e32 v220, 16, v118
	v_and_b32_e32 v221, 0xffff0000, v118
	v_lshlrev_b32_e32 v222, 16, v119
	v_and_b32_e32 v223, 0xffff0000, v119
	v_fma_f32 v212, v216, v212, v220
	v_fma_f32 v213, v217, v213, v221
	v_fma_f32 v214, v218, v214, v222
	v_fma_f32 v215, v219, v215, v223
	v_mul_f32_e32 v208, v208, v216
	v_mul_f32_e32 v209, v209, v217
	v_mul_f32_e32 v210, v210, v218
	v_mul_f32_e32 v211, v211, v219
	s_waitcnt vmcnt(52)
	v_lshlrev_b32_e32 v216, 16, v52
	v_and_b32_e32 v217, 0xffff0000, v52
	v_lshlrev_b32_e32 v218, 16, v53
	v_and_b32_e32 v219, 0xffff0000, v53
	v_exp_f32_e32 v216, v216
	v_exp_f32_e32 v217, v217
	v_exp_f32_e32 v218, v218
	v_exp_f32_e32 v219, v219
	v_lshlrev_b32_e32 v220, 16, v120
	v_and_b32_e32 v221, 0xffff0000, v120
	v_lshlrev_b32_e32 v222, 16, v121
	v_and_b32_e32 v223, 0xffff0000, v121
	v_fma_f32 v212, v216, v212, v220
	v_fma_f32 v213, v217, v213, v221
	v_fma_f32 v214, v218, v214, v222
	v_fma_f32 v215, v219, v215, v223
	v_mul_f32_e32 v208, v208, v216
	v_mul_f32_e32 v209, v209, v217
	v_mul_f32_e32 v210, v210, v218
	v_mul_f32_e32 v211, v211, v219
	s_waitcnt vmcnt(50)
	v_lshlrev_b32_e32 v216, 16, v54
	v_and_b32_e32 v217, 0xffff0000, v54
	v_lshlrev_b32_e32 v218, 16, v55
	v_and_b32_e32 v219, 0xffff0000, v55
	v_exp_f32_e32 v216, v216
	v_exp_f32_e32 v217, v217
	v_exp_f32_e32 v218, v218
	v_exp_f32_e32 v219, v219
	v_lshlrev_b32_e32 v220, 16, v122
	v_and_b32_e32 v221, 0xffff0000, v122
	v_lshlrev_b32_e32 v222, 16, v123
	v_and_b32_e32 v223, 0xffff0000, v123
	v_fma_f32 v212, v216, v212, v220
	v_fma_f32 v213, v217, v213, v221
	v_fma_f32 v214, v218, v214, v222
	v_fma_f32 v215, v219, v215, v223
	v_mul_f32_e32 v208, v208, v216
	v_mul_f32_e32 v209, v209, v217
	v_mul_f32_e32 v210, v210, v218
	v_mul_f32_e32 v211, v211, v219
	s_waitcnt vmcnt(48)
	v_lshlrev_b32_e32 v216, 16, v56
	v_and_b32_e32 v217, 0xffff0000, v56
	v_lshlrev_b32_e32 v218, 16, v57
	v_and_b32_e32 v219, 0xffff0000, v57
	v_exp_f32_e32 v216, v216
	v_exp_f32_e32 v217, v217
	v_exp_f32_e32 v218, v218
	v_exp_f32_e32 v219, v219
	v_lshlrev_b32_e32 v220, 16, v124
	v_and_b32_e32 v221, 0xffff0000, v124
	v_lshlrev_b32_e32 v222, 16, v125
	v_and_b32_e32 v223, 0xffff0000, v125
	v_fma_f32 v212, v216, v212, v220
	v_fma_f32 v213, v217, v213, v221
	v_fma_f32 v214, v218, v214, v222
	v_fma_f32 v215, v219, v215, v223
	v_mul_f32_e32 v208, v208, v216
	v_mul_f32_e32 v209, v209, v217
	v_mul_f32_e32 v210, v210, v218
	v_mul_f32_e32 v211, v211, v219
	s_waitcnt vmcnt(46)
	v_lshlrev_b32_e32 v216, 16, v58
	v_and_b32_e32 v217, 0xffff0000, v58
	v_lshlrev_b32_e32 v218, 16, v59
	v_and_b32_e32 v219, 0xffff0000, v59
	v_exp_f32_e32 v216, v216
	v_exp_f32_e32 v217, v217
	v_exp_f32_e32 v218, v218
	v_exp_f32_e32 v219, v219
	v_lshlrev_b32_e32 v220, 16, v126
	v_and_b32_e32 v221, 0xffff0000, v126
	v_lshlrev_b32_e32 v222, 16, v127
	v_and_b32_e32 v223, 0xffff0000, v127
	v_fma_f32 v212, v216, v212, v220
	v_fma_f32 v213, v217, v213, v221
	v_fma_f32 v214, v218, v214, v222
	v_fma_f32 v215, v219, v215, v223
	v_mul_f32_e32 v208, v208, v216
	v_mul_f32_e32 v209, v209, v217
	v_mul_f32_e32 v210, v210, v218
	v_mul_f32_e32 v211, v211, v219
	s_waitcnt vmcnt(44)
	v_lshlrev_b32_e32 v216, 16, v60
	v_and_b32_e32 v217, 0xffff0000, v60
	v_lshlrev_b32_e32 v218, 16, v61
	v_and_b32_e32 v219, 0xffff0000, v61
	v_exp_f32_e32 v216, v216
	v_exp_f32_e32 v217, v217
	v_exp_f32_e32 v218, v218
	v_exp_f32_e32 v219, v219
	v_lshlrev_b32_e32 v220, 16, v128
	v_and_b32_e32 v221, 0xffff0000, v128
	v_lshlrev_b32_e32 v222, 16, v129
	v_and_b32_e32 v223, 0xffff0000, v129
	v_fma_f32 v212, v216, v212, v220
	v_fma_f32 v213, v217, v213, v221
	v_fma_f32 v214, v218, v214, v222
	v_fma_f32 v215, v219, v215, v223
	v_mul_f32_e32 v208, v208, v216
	v_mul_f32_e32 v209, v209, v217
	v_mul_f32_e32 v210, v210, v218
	v_mul_f32_e32 v211, v211, v219
	s_waitcnt vmcnt(42)
	v_lshlrev_b32_e32 v216, 16, v62
	v_and_b32_e32 v217, 0xffff0000, v62
	v_lshlrev_b32_e32 v218, 16, v63
	v_and_b32_e32 v219, 0xffff0000, v63
	v_exp_f32_e32 v216, v216
	v_exp_f32_e32 v217, v217
	v_exp_f32_e32 v218, v218
	v_exp_f32_e32 v219, v219
	v_lshlrev_b32_e32 v220, 16, v130
	v_and_b32_e32 v221, 0xffff0000, v130
	v_lshlrev_b32_e32 v222, 16, v131
	v_and_b32_e32 v223, 0xffff0000, v131
	v_fma_f32 v212, v216, v212, v220
	v_fma_f32 v213, v217, v213, v221
	v_fma_f32 v214, v218, v214, v222
	v_fma_f32 v215, v219, v215, v223
	v_mul_f32_e32 v208, v208, v216
	v_mul_f32_e32 v209, v209, v217
	v_mul_f32_e32 v210, v210, v218
	v_mul_f32_e32 v211, v211, v219
	s_waitcnt vmcnt(40)
	v_lshlrev_b32_e32 v216, 16, v64
	v_and_b32_e32 v217, 0xffff0000, v64
	v_lshlrev_b32_e32 v218, 16, v65
	v_and_b32_e32 v219, 0xffff0000, v65
	v_exp_f32_e32 v216, v216
	v_exp_f32_e32 v217, v217
	v_exp_f32_e32 v218, v218
	v_exp_f32_e32 v219, v219
	v_lshlrev_b32_e32 v220, 16, v132
	v_and_b32_e32 v221, 0xffff0000, v132
	v_lshlrev_b32_e32 v222, 16, v133
	v_and_b32_e32 v223, 0xffff0000, v133
	v_fma_f32 v212, v216, v212, v220
	v_fma_f32 v213, v217, v213, v221
	v_fma_f32 v214, v218, v214, v222
	v_fma_f32 v215, v219, v215, v223
	v_mul_f32_e32 v208, v208, v216
	v_mul_f32_e32 v209, v209, v217
	v_mul_f32_e32 v210, v210, v218
	v_mul_f32_e32 v211, v211, v219
	s_waitcnt vmcnt(38)
	v_lshlrev_b32_e32 v216, 16, v66
	v_and_b32_e32 v217, 0xffff0000, v66
	v_lshlrev_b32_e32 v218, 16, v67
	v_and_b32_e32 v219, 0xffff0000, v67
	v_exp_f32_e32 v216, v216
	v_exp_f32_e32 v217, v217
	v_exp_f32_e32 v218, v218
	v_exp_f32_e32 v219, v219
	v_lshlrev_b32_e32 v220, 16, v134
	v_and_b32_e32 v221, 0xffff0000, v134
	v_lshlrev_b32_e32 v222, 16, v135
	v_and_b32_e32 v223, 0xffff0000, v135
	v_fma_f32 v212, v216, v212, v220
	v_fma_f32 v213, v217, v213, v221
	v_fma_f32 v214, v218, v214, v222
	v_fma_f32 v215, v219, v215, v223
	v_mul_f32_e32 v208, v208, v216
	v_mul_f32_e32 v209, v209, v217
	v_mul_f32_e32 v210, v210, v218
	v_mul_f32_e32 v211, v211, v219
	s_waitcnt vmcnt(36)
	v_lshlrev_b32_e32 v216, 16, v68
	v_and_b32_e32 v217, 0xffff0000, v68
	v_lshlrev_b32_e32 v218, 16, v69
	v_and_b32_e32 v219, 0xffff0000, v69
	v_exp_f32_e32 v216, v216
	v_exp_f32_e32 v217, v217
	v_exp_f32_e32 v218, v218
	v_exp_f32_e32 v219, v219
	v_lshlrev_b32_e32 v220, 16, v136
	v_and_b32_e32 v221, 0xffff0000, v136
	v_lshlrev_b32_e32 v222, 16, v137
	v_and_b32_e32 v223, 0xffff0000, v137
	v_fma_f32 v212, v216, v212, v220
	v_fma_f32 v213, v217, v213, v221
	v_fma_f32 v214, v218, v214, v222
	v_fma_f32 v215, v219, v215, v223
	v_mul_f32_e32 v208, v208, v216
	v_mul_f32_e32 v209, v209, v217
	v_mul_f32_e32 v210, v210, v218
	v_mul_f32_e32 v211, v211, v219
	s_waitcnt vmcnt(34)
	v_lshlrev_b32_e32 v216, 16, v70
	v_and_b32_e32 v217, 0xffff0000, v70
	v_lshlrev_b32_e32 v218, 16, v71
	v_and_b32_e32 v219, 0xffff0000, v71
	v_exp_f32_e32 v216, v216
	v_exp_f32_e32 v217, v217
	v_exp_f32_e32 v218, v218
	v_exp_f32_e32 v219, v219
	v_lshlrev_b32_e32 v220, 16, v138
	v_and_b32_e32 v221, 0xffff0000, v138
	v_lshlrev_b32_e32 v222, 16, v139
	v_and_b32_e32 v223, 0xffff0000, v139
	v_fma_f32 v212, v216, v212, v220
	v_fma_f32 v213, v217, v213, v221
	v_fma_f32 v214, v218, v214, v222
	v_fma_f32 v215, v219, v215, v223
	v_mul_f32_e32 v208, v208, v216
	v_mul_f32_e32 v209, v209, v217
	v_mul_f32_e32 v210, v210, v218
	v_mul_f32_e32 v211, v211, v219
	ds_write_b128 v247, v[208:211]
	ds_write_b128 v247, v[212:215] offset:8192
	s_waitcnt lgkmcnt(0)
	s_barrier
	v_mov_b32_e32 v208, 0
	v_mov_b32_e32 v209, 0
	v_mov_b32_e32 v210, 0
	v_mov_b32_e32 v211, 0
	ds_read_b128 v[212:215], v249 offset:0
	ds_read_b128 v[216:219], v249 offset:8192
	ds_read_b128 v[220:223], v249 offset:128
	ds_read_b128 v[224:227], v249 offset:8320
	ds_read_b128 v[228:231], v249 offset:256
	ds_read_b128 v[232:235], v249 offset:8448
	ds_read_b128 v[236:239], v249 offset:384
	ds_read_b128 v[240:243], v249 offset:8576
	s_waitcnt lgkmcnt(6)
	v_cmpx_lt_i32_e32 vcc, 0, v248
	v_fma_f32 v208, v212, v208, v216
	v_fma_f32 v209, v213, v209, v217
	v_fma_f32 v210, v214, v210, v218
	v_fma_f32 v211, v215, v211, v219
	s_waitcnt lgkmcnt(4)
	v_cmpx_lt_i32_e32 vcc, 1, v248
	v_fma_f32 v208, v220, v208, v224
	v_fma_f32 v209, v221, v209, v225
	v_fma_f32 v210, v222, v210, v226
	v_fma_f32 v211, v223, v211, v227
	s_waitcnt lgkmcnt(2)
	v_cmpx_lt_i32_e32 vcc, 2, v248
	v_fma_f32 v208, v228, v208, v232
	v_fma_f32 v209, v229, v209, v233
	v_fma_f32 v210, v230, v210, v234
	v_fma_f32 v211, v231, v211, v235
	s_waitcnt lgkmcnt(0)
	v_cmpx_lt_i32_e32 vcc, 3, v248
	v_fma_f32 v208, v236, v208, v240
	v_fma_f32 v209, v237, v209, v241
	v_fma_f32 v210, v238, v210, v242
	v_fma_f32 v211, v239, v211, v243
	ds_read_b128 v[212:215], v249 offset:512
	ds_read_b128 v[216:219], v249 offset:8704
	ds_read_b128 v[220:223], v249 offset:640
	ds_read_b128 v[224:227], v249 offset:8832
	ds_read_b128 v[228:231], v249 offset:768
	ds_read_b128 v[232:235], v249 offset:8960
	ds_read_b128 v[236:239], v249 offset:896
	ds_read_b128 v[240:243], v249 offset:9088
	s_waitcnt lgkmcnt(6)
	v_cmpx_lt_i32_e32 vcc, 4, v248
	v_fma_f32 v208, v212, v208, v216
	v_fma_f32 v209, v213, v209, v217
	v_fma_f32 v210, v214, v210, v218
	v_fma_f32 v211, v215, v211, v219
	s_waitcnt lgkmcnt(4)
	v_cmpx_lt_i32_e32 vcc, 5, v248
	v_fma_f32 v208, v220, v208, v224
	v_fma_f32 v209, v221, v209, v225
	v_fma_f32 v210, v222, v210, v226
	v_fma_f32 v211, v223, v211, v227
	s_waitcnt lgkmcnt(2)
	v_cmpx_lt_i32_e32 vcc, 6, v248
	v_fma_f32 v208, v228, v208, v232
	v_fma_f32 v209, v229, v209, v233
	v_fma_f32 v210, v230, v210, v234
	v_fma_f32 v211, v231, v211, v235
	s_waitcnt lgkmcnt(0)
	v_cmpx_lt_i32_e32 vcc, 7, v248
	v_fma_f32 v208, v236, v208, v240
	v_fma_f32 v209, v237, v209, v241
	v_fma_f32 v210, v238, v210, v242
	v_fma_f32 v211, v239, v211, v243
	s_cmp_le_u32 s18, 0
	s_cbranch_scc1 .Lscan_fold_done
	ds_read_b128 v[212:215], v249 offset:1024
	ds_read_b128 v[216:219], v249 offset:9216
	ds_read_b128 v[220:223], v249 offset:1152
	ds_read_b128 v[224:227], v249 offset:9344
	ds_read_b128 v[228:231], v249 offset:1280
	ds_read_b128 v[232:235], v249 offset:9472
	ds_read_b128 v[236:239], v249 offset:1408
	ds_read_b128 v[240:243], v249 offset:9600
	s_waitcnt lgkmcnt(6)
	v_cmpx_lt_i32_e32 vcc, 8, v248
	v_fma_f32 v208, v212, v208, v216
	v_fma_f32 v209, v213, v209, v217
	v_fma_f32 v210, v214, v210, v218
	v_fma_f32 v211, v215, v211, v219
	s_waitcnt lgkmcnt(4)
	v_cmpx_lt_i32_e32 vcc, 9, v248
	v_fma_f32 v208, v220, v208, v224
	v_fma_f32 v209, v221, v209, v225
	v_fma_f32 v210, v222, v210, v226
	v_fma_f32 v211, v223, v211, v227
	s_waitcnt lgkmcnt(2)
	v_cmpx_lt_i32_e32 vcc, 10, v248
	v_fma_f32 v208, v228, v208, v232
	v_fma_f32 v209, v229, v209, v233
	v_fma_f32 v210, v230, v210, v234
	v_fma_f32 v211, v231, v211, v235
	s_waitcnt lgkmcnt(0)
	v_cmpx_lt_i32_e32 vcc, 11, v248
	v_fma_f32 v208, v236, v208, v240
	v_fma_f32 v209, v237, v209, v241
	v_fma_f32 v210, v238, v210, v242
	v_fma_f32 v211, v239, v211, v243
	ds_read_b128 v[212:215], v249 offset:1536
	ds_read_b128 v[216:219], v249 offset:9728
	ds_read_b128 v[220:223], v249 offset:1664
	ds_read_b128 v[224:227], v249 offset:9856
	ds_read_b128 v[228:231], v249 offset:1792
	ds_read_b128 v[232:235], v249 offset:9984
	ds_read_b128 v[236:239], v249 offset:1920
	ds_read_b128 v[240:243], v249 offset:10112
	s_waitcnt lgkmcnt(6)
	v_cmpx_lt_i32_e32 vcc, 12, v248
	v_fma_f32 v208, v212, v208, v216
	v_fma_f32 v209, v213, v209, v217
	v_fma_f32 v210, v214, v210, v218
	v_fma_f32 v211, v215, v211, v219
	s_waitcnt lgkmcnt(4)
	v_cmpx_lt_i32_e32 vcc, 13, v248
	v_fma_f32 v208, v220, v208, v224
	v_fma_f32 v209, v221, v209, v225
	v_fma_f32 v210, v222, v210, v226
	v_fma_f32 v211, v223, v211, v227
	s_waitcnt lgkmcnt(2)
	v_cmpx_lt_i32_e32 vcc, 14, v248
	v_fma_f32 v208, v228, v208, v232
	v_fma_f32 v209, v229, v209, v233
	v_fma_f32 v210, v230, v210, v234
	v_fma_f32 v211, v231, v211, v235
	s_waitcnt lgkmcnt(0)
	v_cmpx_lt_i32_e32 vcc, 15, v248
	v_fma_f32 v208, v236, v208, v240
	v_fma_f32 v209, v237, v209, v241
	v_fma_f32 v210, v238, v210, v242
	v_fma_f32 v211, v239, v211, v243
	s_cmp_le_u32 s18, 1
	s_cbranch_scc1 .Lscan_fold_done
	ds_read_b128 v[212:215], v249 offset:2048
	ds_read_b128 v[216:219], v249 offset:10240
	ds_read_b128 v[220:223], v249 offset:2176
	ds_read_b128 v[224:227], v249 offset:10368
	ds_read_b128 v[228:231], v249 offset:2304
	ds_read_b128 v[232:235], v249 offset:10496
	ds_read_b128 v[236:239], v249 offset:2432
	ds_read_b128 v[240:243], v249 offset:10624
	s_waitcnt lgkmcnt(6)
	v_cmpx_lt_i32_e32 vcc, 16, v248
	v_fma_f32 v208, v212, v208, v216
	v_fma_f32 v209, v213, v209, v217
	v_fma_f32 v210, v214, v210, v218
	v_fma_f32 v211, v215, v211, v219
	s_waitcnt lgkmcnt(4)
	v_cmpx_lt_i32_e32 vcc, 17, v248
	v_fma_f32 v208, v220, v208, v224
	v_fma_f32 v209, v221, v209, v225
	v_fma_f32 v210, v222, v210, v226
	v_fma_f32 v211, v223, v211, v227
	s_waitcnt lgkmcnt(2)
	v_cmpx_lt_i32_e32 vcc, 18, v248
	v_fma_f32 v208, v228, v208, v232
	v_fma_f32 v209, v229, v209, v233
	v_fma_f32 v210, v230, v210, v234
	v_fma_f32 v211, v231, v211, v235
	s_waitcnt lgkmcnt(0)
	v_cmpx_lt_i32_e32 vcc, 19, v248
	v_fma_f32 v208, v236, v208, v240
	v_fma_f32 v209, v237, v209, v241
	v_fma_f32 v210, v238, v210, v242
	v_fma_f32 v211, v239, v211, v243
	ds_read_b128 v[212:215], v249 offset:2560
	ds_read_b128 v[216:219], v249 offset:10752
	ds_read_b128 v[220:223], v249 offset:2688
	ds_read_b128 v[224:227], v249 offset:10880
	ds_read_b128 v[228:231], v249 offset:2816
	ds_read_b128 v[232:235], v249 offset:11008
	ds_read_b128 v[236:239], v249 offset:2944
	ds_read_b128 v[240:243], v249 offset:11136
	s_waitcnt lgkmcnt(6)
	v_cmpx_lt_i32_e32 vcc, 20, v248
	v_fma_f32 v208, v212, v208, v216
	v_fma_f32 v209, v213, v209, v217
	v_fma_f32 v210, v214, v210, v218
	v_fma_f32 v211, v215, v211, v219
	s_waitcnt lgkmcnt(4)
	v_cmpx_lt_i32_e32 vcc, 21, v248
	v_fma_f32 v208, v220, v208, v224
	v_fma_f32 v209, v221, v209, v225
	v_fma_f32 v210, v222, v210, v226
	v_fma_f32 v211, v223, v211, v227
	s_waitcnt lgkmcnt(2)
	v_cmpx_lt_i32_e32 vcc, 22, v248
	v_fma_f32 v208, v228, v208, v232
	v_fma_f32 v209, v229, v209, v233
	v_fma_f32 v210, v230, v210, v234
	v_fma_f32 v211, v231, v211, v235
	s_waitcnt lgkmcnt(0)
	v_cmpx_lt_i32_e32 vcc, 23, v248
	v_fma_f32 v208, v236, v208, v240
	v_fma_f32 v209, v237, v209, v241
	v_fma_f32 v210, v238, v210, v242
	v_fma_f32 v211, v239, v211, v243
	s_cmp_le_u32 s18, 2
	s_cbranch_scc1 .Lscan_fold_done
	ds_read_b128 v[212:215], v249 offset:3072
	ds_read_b128 v[216:219], v249 offset:11264
	ds_read_b128 v[220:223], v249 offset:3200
	ds_read_b128 v[224:227], v249 offset:11392
	ds_read_b128 v[228:231], v249 offset:3328
	ds_read_b128 v[232:235], v249 offset:11520
	ds_read_b128 v[236:239], v249 offset:3456
	ds_read_b128 v[240:243], v249 offset:11648
	s_waitcnt lgkmcnt(6)
	v_cmpx_lt_i32_e32 vcc, 24, v248
	v_fma_f32 v208, v212, v208, v216
	v_fma_f32 v209, v213, v209, v217
	v_fma_f32 v210, v214, v210, v218
	v_fma_f32 v211, v215, v211, v219
	s_waitcnt lgkmcnt(4)
	v_cmpx_lt_i32_e32 vcc, 25, v248
	v_fma_f32 v208, v220, v208, v224
	v_fma_f32 v209, v221, v209, v225
	v_fma_f32 v210, v222, v210, v226
	v_fma_f32 v211, v223, v211, v227
	s_waitcnt lgkmcnt(2)
	v_cmpx_lt_i32_e32 vcc, 26, v248
	v_fma_f32 v208, v228, v208, v232
	v_fma_f32 v209, v229, v209, v233
	v_fma_f32 v210, v230, v210, v234
	v_fma_f32 v211, v231, v211, v235
	s_waitcnt lgkmcnt(0)
	v_cmpx_lt_i32_e32 vcc, 27, v248
	v_fma_f32 v208, v236, v208, v240
	v_fma_f32 v209, v237, v209, v241
	v_fma_f32 v210, v238, v210, v242
	v_fma_f32 v211, v239, v211, v243
	ds_read_b128 v[212:215], v249 offset:3584
	ds_read_b128 v[216:219], v249 offset:11776
	ds_read_b128 v[220:223], v249 offset:3712
	ds_read_b128 v[224:227], v249 offset:11904
	ds_read_b128 v[228:231], v249 offset:3840
	ds_read_b128 v[232:235], v249 offset:12032
	ds_read_b128 v[236:239], v249 offset:3968
	ds_read_b128 v[240:243], v249 offset:12160
	s_waitcnt lgkmcnt(6)
	v_cmpx_lt_i32_e32 vcc, 28, v248
	v_fma_f32 v208, v212, v208, v216
	v_fma_f32 v209, v213, v209, v217
	v_fma_f32 v210, v214, v210, v218
	v_fma_f32 v211, v215, v211, v219
	s_waitcnt lgkmcnt(4)
	v_cmpx_lt_i32_e32 vcc, 29, v248
	v_fma_f32 v208, v220, v208, v224
	v_fma_f32 v209, v221, v209, v225
	v_fma_f32 v210, v222, v210, v226
	v_fma_f32 v211, v223, v211, v227
	s_waitcnt lgkmcnt(2)
	v_cmpx_lt_i32_e32 vcc, 30, v248
	v_fma_f32 v208, v228, v208, v232
	v_fma_f32 v209, v229, v209, v233
	v_fma_f32 v210, v230, v210, v234
	v_fma_f32 v211, v231, v211, v235
	s_waitcnt lgkmcnt(0)
	v_cmpx_lt_i32_e32 vcc, 31, v248
	v_fma_f32 v208, v236, v208, v240
	v_fma_f32 v209, v237, v209, v241
	v_fma_f32 v210, v238, v210, v242
	v_fma_f32 v211, v239, v211, v243
	s_cmp_le_u32 s18, 3
	s_cbranch_scc1 .Lscan_fold_done
	ds_read_b128 v[212:215], v249 offset:4096
	ds_read_b128 v[216:219], v249 offset:12288
	ds_read_b128 v[220:223], v249 offset:4224
	ds_read_b128 v[224:227], v249 offset:12416
	ds_read_b128 v[228:231], v249 offset:4352
	ds_read_b128 v[232:235], v249 offset:12544
	ds_read_b128 v[236:239], v249 offset:4480
	ds_read_b128 v[240:243], v249 offset:12672
	s_waitcnt lgkmcnt(6)
	v_cmpx_lt_i32_e32 vcc, 32, v248
	v_fma_f32 v208, v212, v208, v216
	v_fma_f32 v209, v213, v209, v217
	v_fma_f32 v210, v214, v210, v218
	v_fma_f32 v211, v215, v211, v219
	s_waitcnt lgkmcnt(4)
	v_cmpx_lt_i32_e32 vcc, 33, v248
	v_fma_f32 v208, v220, v208, v224
	v_fma_f32 v209, v221, v209, v225
	v_fma_f32 v210, v222, v210, v226
	v_fma_f32 v211, v223, v211, v227
	s_waitcnt lgkmcnt(2)
	v_cmpx_lt_i32_e32 vcc, 34, v248
	v_fma_f32 v208, v228, v208, v232
	v_fma_f32 v209, v229, v209, v233
	v_fma_f32 v210, v230, v210, v234
	v_fma_f32 v211, v231, v211, v235
	s_waitcnt lgkmcnt(0)
	v_cmpx_lt_i32_e32 vcc, 35, v248
	v_fma_f32 v208, v236, v208, v240
	v_fma_f32 v209, v237, v209, v241
	v_fma_f32 v210, v238, v210, v242
	v_fma_f32 v211, v239, v211, v243
	ds_read_b128 v[212:215], v249 offset:4608
	ds_read_b128 v[216:219], v249 offset:12800
	ds_read_b128 v[220:223], v249 offset:4736
	ds_read_b128 v[224:227], v249 offset:12928
	ds_read_b128 v[228:231], v249 offset:4864
	ds_read_b128 v[232:235], v249 offset:13056
	ds_read_b128 v[236:239], v249 offset:4992
	ds_read_b128 v[240:243], v249 offset:13184
	s_waitcnt lgkmcnt(6)
	v_cmpx_lt_i32_e32 vcc, 36, v248
	v_fma_f32 v208, v212, v208, v216
	v_fma_f32 v209, v213, v209, v217
	v_fma_f32 v210, v214, v210, v218
	v_fma_f32 v211, v215, v211, v219
	s_waitcnt lgkmcnt(4)
	v_cmpx_lt_i32_e32 vcc, 37, v248
	v_fma_f32 v208, v220, v208, v224
	v_fma_f32 v209, v221, v209, v225
	v_fma_f32 v210, v222, v210, v226
	v_fma_f32 v211, v223, v211, v227
	s_waitcnt lgkmcnt(2)
	v_cmpx_lt_i32_e32 vcc, 38, v248
	v_fma_f32 v208, v228, v208, v232
	v_fma_f32 v209, v229, v209, v233
	v_fma_f32 v210, v230, v210, v234
	v_fma_f32 v211, v231, v211, v235
	s_waitcnt lgkmcnt(0)
	v_cmpx_lt_i32_e32 vcc, 39, v248
	v_fma_f32 v208, v236, v208, v240
	v_fma_f32 v209, v237, v209, v241
	v_fma_f32 v210, v238, v210, v242
	v_fma_f32 v211, v239, v211, v243
	s_cmp_le_u32 s18, 4
	s_cbranch_scc1 .Lscan_fold_done
	ds_read_b128 v[212:215], v249 offset:5120
	ds_read_b128 v[216:219], v249 offset:13312
	ds_read_b128 v[220:223], v249 offset:5248
	ds_read_b128 v[224:227], v249 offset:13440
	ds_read_b128 v[228:231], v249 offset:5376
	ds_read_b128 v[232:235], v249 offset:13568
	ds_read_b128 v[236:239], v249 offset:5504
	ds_read_b128 v[240:243], v249 offset:13696
	s_waitcnt lgkmcnt(6)
	v_cmpx_lt_i32_e32 vcc, 40, v248
	v_fma_f32 v208, v212, v208, v216
	v_fma_f32 v209, v213, v209, v217
	v_fma_f32 v210, v214, v210, v218
	v_fma_f32 v211, v215, v211, v219
	s_waitcnt lgkmcnt(4)
	v_cmpx_lt_i32_e32 vcc, 41, v248
	v_fma_f32 v208, v220, v208, v224
	v_fma_f32 v209, v221, v209, v225
	v_fma_f32 v210, v222, v210, v226
	v_fma_f32 v211, v223, v211, v227
	s_waitcnt lgkmcnt(2)
	v_cmpx_lt_i32_e32 vcc, 42, v248
	v_fma_f32 v208, v228, v208, v232
	v_fma_f32 v209, v229, v209, v233
	v_fma_f32 v210, v230, v210, v234
	v_fma_f32 v211, v231, v211, v235
	s_waitcnt lgkmcnt(0)
	v_cmpx_lt_i32_e32 vcc, 43, v248
	v_fma_f32 v208, v236, v208, v240
	v_fma_f32 v209, v237, v209, v241
	v_fma_f32 v210, v238, v210, v242
	v_fma_f32 v211, v239, v211, v243
	ds_read_b128 v[212:215], v249 offset:5632
	ds_read_b128 v[216:219], v249 offset:13824
	ds_read_b128 v[220:223], v249 offset:5760
	ds_read_b128 v[224:227], v249 offset:13952
	ds_read_b128 v[228:231], v249 offset:5888
	ds_read_b128 v[232:235], v249 offset:14080
	ds_read_b128 v[236:239], v249 offset:6016
	ds_read_b128 v[240:243], v249 offset:14208
	s_waitcnt lgkmcnt(6)
	v_cmpx_lt_i32_e32 vcc, 44, v248
	v_fma_f32 v208, v212, v208, v216
	v_fma_f32 v209, v213, v209, v217
	v_fma_f32 v210, v214, v210, v218
	v_fma_f32 v211, v215, v211, v219
	s_waitcnt lgkmcnt(4)
	v_cmpx_lt_i32_e32 vcc, 45, v248
	v_fma_f32 v208, v220, v208, v224
	v_fma_f32 v209, v221, v209, v225
	v_fma_f32 v210, v222, v210, v226
	v_fma_f32 v211, v223, v211, v227
	s_waitcnt lgkmcnt(2)
	v_cmpx_lt_i32_e32 vcc, 46, v248
	v_fma_f32 v208, v228, v208, v232
	v_fma_f32 v209, v229, v209, v233
	v_fma_f32 v210, v230, v210, v234
	v_fma_f32 v211, v231, v211, v235
	s_waitcnt lgkmcnt(0)
	v_cmpx_lt_i32_e32 vcc, 47, v248
	v_fma_f32 v208, v236, v208, v240
	v_fma_f32 v209, v237, v209, v241
	v_fma_f32 v210, v238, v210, v242
	v_fma_f32 v211, v239, v211, v243
	s_cmp_le_u32 s18, 5
	s_cbranch_scc1 .Lscan_fold_done
	ds_read_b128 v[212:215], v249 offset:6144
	ds_read_b128 v[216:219], v249 offset:14336
	ds_read_b128 v[220:223], v249 offset:6272
	ds_read_b128 v[224:227], v249 offset:14464
	ds_read_b128 v[228:231], v249 offset:6400
	ds_read_b128 v[232:235], v249 offset:14592
	ds_read_b128 v[236:239], v249 offset:6528
	ds_read_b128 v[240:243], v249 offset:14720
	s_waitcnt lgkmcnt(6)
	v_cmpx_lt_i32_e32 vcc, 48, v248
	v_fma_f32 v208, v212, v208, v216
	v_fma_f32 v209, v213, v209, v217
	v_fma_f32 v210, v214, v210, v218
	v_fma_f32 v211, v215, v211, v219
	s_waitcnt lgkmcnt(4)
	v_cmpx_lt_i32_e32 vcc, 49, v248
	v_fma_f32 v208, v220, v208, v224
	v_fma_f32 v209, v221, v209, v225
	v_fma_f32 v210, v222, v210, v226
	v_fma_f32 v211, v223, v211, v227
	s_waitcnt lgkmcnt(2)
	v_cmpx_lt_i32_e32 vcc, 50, v248
	v_fma_f32 v208, v228, v208, v232
	v_fma_f32 v209, v229, v209, v233
	v_fma_f32 v210, v230, v210, v234
	v_fma_f32 v211, v231, v211, v235
	s_waitcnt lgkmcnt(0)
	v_cmpx_lt_i32_e32 vcc, 51, v248
	v_fma_f32 v208, v236, v208, v240
	v_fma_f32 v209, v237, v209, v241
	v_fma_f32 v210, v238, v210, v242
	v_fma_f32 v211, v239, v211, v243
	ds_read_b128 v[212:215], v249 offset:6656
	ds_read_b128 v[216:219], v249 offset:14848
	ds_read_b128 v[220:223], v249 offset:6784
	ds_read_b128 v[224:227], v249 offset:14976
	ds_read_b128 v[228:231], v249 offset:6912
	ds_read_b128 v[232:235], v249 offset:15104
	ds_read_b128 v[236:239], v249 offset:7040
	ds_read_b128 v[240:243], v249 offset:15232
	s_waitcnt lgkmcnt(6)
	v_cmpx_lt_i32_e32 vcc, 52, v248
	v_fma_f32 v208, v212, v208, v216
	v_fma_f32 v209, v213, v209, v217
	v_fma_f32 v210, v214, v210, v218
	v_fma_f32 v211, v215, v211, v219
	s_waitcnt lgkmcnt(4)
	v_cmpx_lt_i32_e32 vcc, 53, v248
	v_fma_f32 v208, v220, v208, v224
	v_fma_f32 v209, v221, v209, v225
	v_fma_f32 v210, v222, v210, v226
	v_fma_f32 v211, v223, v211, v227
	s_waitcnt lgkmcnt(2)
	v_cmpx_lt_i32_e32 vcc, 54, v248
	v_fma_f32 v208, v228, v208, v232
	v_fma_f32 v209, v229, v209, v233
	v_fma_f32 v210, v230, v210, v234
	v_fma_f32 v211, v231, v211, v235
	s_waitcnt lgkmcnt(0)
	v_cmpx_lt_i32_e32 vcc, 55, v248
	v_fma_f32 v208, v236, v208, v240
	v_fma_f32 v209, v237, v209, v241
	v_fma_f32 v210, v238, v210, v242
	v_fma_f32 v211, v239, v211, v243
	s_cmp_le_u32 s18, 6
	s_cbranch_scc1 .Lscan_fold_done
	ds_read_b128 v[212:215], v249 offset:7168
	ds_read_b128 v[216:219], v249 offset:15360
	ds_read_b128 v[220:223], v249 offset:7296
	ds_read_b128 v[224:227], v249 offset:15488
	ds_read_b128 v[228:231], v249 offset:7424
	ds_read_b128 v[232:235], v249 offset:15616
	ds_read_b128 v[236:239], v249 offset:7552
	ds_read_b128 v[240:243], v249 offset:15744
	s_waitcnt lgkmcnt(6)
	v_cmpx_lt_i32_e32 vcc, 56, v248
	v_fma_f32 v208, v212, v208, v216
	v_fma_f32 v209, v213, v209, v217
	v_fma_f32 v210, v214, v210, v218
	v_fma_f32 v211, v215, v211, v219
	s_waitcnt lgkmcnt(4)
	v_cmpx_lt_i32_e32 vcc, 57, v248
	v_fma_f32 v208, v220, v208, v224
	v_fma_f32 v209, v221, v209, v225
	v_fma_f32 v210, v222, v210, v226
	v_fma_f32 v211, v223, v211, v227
	s_waitcnt lgkmcnt(2)
	v_cmpx_lt_i32_e32 vcc, 58, v248
	v_fma_f32 v208, v228, v208, v232
	v_fma_f32 v209, v229, v209, v233
	v_fma_f32 v210, v230, v210, v234
	v_fma_f32 v211, v231, v211, v235
	s_waitcnt lgkmcnt(0)
	v_cmpx_lt_i32_e32 vcc, 59, v248
	v_fma_f32 v208, v236, v208, v240
	v_fma_f32 v209, v237, v209, v241
	v_fma_f32 v210, v238, v210, v242
	v_fma_f32 v211, v239, v211, v243
	ds_read_b128 v[212:215], v249 offset:7680
	ds_read_b128 v[216:219], v249 offset:15872
	ds_read_b128 v[220:223], v249 offset:7808
	ds_read_b128 v[224:227], v249 offset:16000
	ds_read_b128 v[228:231], v249 offset:7936
	ds_read_b128 v[232:235], v249 offset:16128
	ds_read_b128 v[236:239], v249 offset:8064
	ds_read_b128 v[240:243], v249 offset:16256
	s_waitcnt lgkmcnt(6)
	v_cmpx_lt_i32_e32 vcc, 60, v248
	v_fma_f32 v208, v212, v208, v216
	v_fma_f32 v209, v213, v209, v217
	v_fma_f32 v210, v214, v210, v218
	v_fma_f32 v211, v215, v211, v219
	s_waitcnt lgkmcnt(4)
	v_cmpx_lt_i32_e32 vcc, 61, v248
	v_fma_f32 v208, v220, v208, v224
	v_fma_f32 v209, v221, v209, v225
	v_fma_f32 v210, v222, v210, v226
	v_fma_f32 v211, v223, v211, v227
	s_waitcnt lgkmcnt(2)
	v_cmpx_lt_i32_e32 vcc, 62, v248
	v_fma_f32 v208, v228, v208, v232
	v_fma_f32 v209, v229, v209, v233
	v_fma_f32 v210, v230, v210, v234
	v_fma_f32 v211, v231, v211, v235
	s_waitcnt lgkmcnt(0)
	v_cmpx_lt_i32_e32 vcc, 63, v248
	v_fma_f32 v208, v236, v208, v240
	v_fma_f32 v209, v237, v209, v241
	v_fma_f32 v210, v238, v210, v242
	v_fma_f32 v211, v239, v211, v243
.Lscan_fold_done:
	s_mov_b64 exec, -1
	v_cmp_gt_i32_e32 vcc, 61, v248
	s_and_b64 s[14:15], vcc, s[2:3]
	v_cmp_gt_i32_e32 vcc, 60, v248
	s_and_b64 s[16:17], vcc, s[2:3]
	s_waitcnt vmcnt(0)
	v_mov_b32_e32 v2, v3
	v_lshlrev_b32_e32 v216, 16, v4
	v_and_b32_e32 v217, 0xffff0000, v4
	v_lshlrev_b32_e32 v218, 16, v5
	v_and_b32_e32 v219, 0xffff0000, v5
	v_exp_f32_e32 v216, v216
	v_exp_f32_e32 v217, v217
	v_exp_f32_e32 v218, v218
	v_exp_f32_e32 v219, v219
	v_lshlrev_b32_e32 v220, 16, v72
	v_and_b32_e32 v221, 0xffff0000, v72
	v_lshlrev_b32_e32 v222, 16, v73
	v_and_b32_e32 v223, 0xffff0000, v73
	v_lshlrev_b32_e32 v224, 16, v140
	v_and_b32_e32 v225, 0xffff0000, v140
	v_lshlrev_b32_e32 v226, 16, v141
	v_and_b32_e32 v227, 0xffff0000, v141
	v_fma_f32 v208, v216, v208, v220
	v_fma_f32 v209, v217, v209, v221
	v_fma_f32 v210, v218, v210, v222
	v_fma_f32 v211, v219, v211, v223
	v_mul_f32_e32 v224, v208, v224
	v_mul_f32_e32 v225, v209, v225
	v_mul_f32_e32 v226, v210, v226
	v_mul_f32_e32 v227, v211, v227
	v_cvt_pk_bf16_f32 v228, v224, v225
	v_cvt_pk_bf16_f32 v229, v226, v227
	s_mov_b64 exec, s[14:15]
	global_store_dwordx2 v2, v[228:229], s[12:13]
	s_mov_b64 exec, -1
	v_lshlrev_b32_e32 v216, 16, v6
	v_and_b32_e32 v217, 0xffff0000, v6
	v_lshlrev_b32_e32 v218, 16, v7
	v_and_b32_e32 v219, 0xffff0000, v7
	v_exp_f32_e32 v216, v216
	v_exp_f32_e32 v217, v217
	v_exp_f32_e32 v218, v218
	v_exp_f32_e32 v219, v219
	v_lshlrev_b32_e32 v220, 16, v74
	v_and_b32_e32 v221, 0xffff0000, v74
	v_lshlrev_b32_e32 v222, 16, v75
	v_and_b32_e32 v223, 0xffff0000, v75
	v_lshlrev_b32_e32 v224, 16, v142
	v_and_b32_e32 v225, 0xffff0000, v142
	v_lshlrev_b32_e32 v226, 16, v143
	v_and_b32_e32 v227, 0xffff0000, v143
	v_fma_f32 v208, v216, v208, v220
	v_fma_f32 v209, v217, v209, v221
	v_fma_f32 v210, v218, v210, v222
	v_fma_f32 v211, v219, v211, v223
	v_mul_f32_e32 v224, v208, v224
	v_mul_f32_e32 v225, v209, v225
	v_mul_f32_e32 v226, v210, v226
	v_mul_f32_e32 v227, v211, v227
	v_cvt_pk_bf16_f32 v228, v224, v225
	v_cvt_pk_bf16_f32 v229, v226, v227
	s_mov_b64 exec, s[14:15]
	global_store_dwordx2 v2, v[228:229], s[12:13] offset:2048
	s_mov_b64 exec, -1
	v_add_u32_e32 v2, 0x1000, v3
	v_lshlrev_b32_e32 v216, 16, v8
	v_and_b32_e32 v217, 0xffff0000, v8
	v_lshlrev_b32_e32 v218, 16, v9
	v_and_b32_e32 v219, 0xffff0000, v9
	v_exp_f32_e32 v216, v216
	v_exp_f32_e32 v217, v217
	v_exp_f32_e32 v218, v218
	v_exp_f32_e32 v219, v219
	v_lshlrev_b32_e32 v220, 16, v76
	v_and_b32_e32 v221, 0xffff0000, v76
	v_lshlrev_b32_e32 v222, 16, v77
	v_and_b32_e32 v223, 0xffff0000, v77
	v_lshlrev_b32_e32 v224, 16, v144
	v_and_b32_e32 v225, 0xffff0000, v144
	v_lshlrev_b32_e32 v226, 16, v145
	v_and_b32_e32 v227, 0xffff0000, v145
	v_fma_f32 v208, v216, v208, v220
	v_fma_f32 v209, v217, v209, v221
	v_fma_f32 v210, v218, v210, v222
	v_fma_f32 v211, v219, v211, v223
	v_mul_f32_e32 v224, v208, v224
	v_mul_f32_e32 v225, v209, v225
	v_mul_f32_e32 v226, v210, v226
	v_mul_f32_e32 v227, v211, v227
	v_cvt_pk_bf16_f32 v228, v224, v225
	v_cvt_pk_bf16_f32 v229, v226, v227
	s_mov_b64 exec, s[14:15]
	global_store_dwordx2 v2, v[228:229], s[12:13]
	s_mov_b64 exec, -1
	v_lshlrev_b32_e32 v216, 16, v10
	v_and_b32_e32 v217, 0xffff0000, v10
	v_lshlrev_b32_e32 v218, 16, v11
	v_and_b32_e32 v219, 0xffff0000, v11
	v_exp_f32_e32 v216, v216
	v_exp_f32_e32 v217, v217
	v_exp_f32_e32 v218, v218
	v_exp_f32_e32 v219, v219
	v_lshlrev_b32_e32 v220, 16, v78
	v_and_b32_e32 v221, 0xffff0000, v78
	v_lshlrev_b32_e32 v222, 16, v79
	v_and_b32_e32 v223, 0xffff0000, v79
	v_lshlrev_b32_e32 v224, 16, v146
	v_and_b32_e32 v225, 0xffff0000, v146
	v_lshlrev_b32_e32 v226, 16, v147
	v_and_b32_e32 v227, 0xffff0000, v147
	v_fma_f32 v208, v216, v208, v220
	v_fma_f32 v209, v217, v209, v221
	v_fma_f32 v210, v218, v210, v222
	v_fma_f32 v211, v219, v211, v223
	v_mul_f32_e32 v224, v208, v224
	v_mul_f32_e32 v225, v209, v225
	v_mul_f32_e32 v226, v210, v226
	v_mul_f32_e32 v227, v211, v227
	v_cvt_pk_bf16_f32 v228, v224, v225
	v_cvt_pk_bf16_f32 v229, v226, v227
	s_mov_b64 exec, s[14:15]
	global_store_dwordx2 v2, v[228:229], s[12:13] offset:2048
	s_mov_b64 exec, -1
	v_add_u32_e32 v2, 0x2000, v3
	v_lshlrev_b32_e32 v216, 16, v12
	v_and_b32_e32 v217, 0xffff0000, v12
	v_lshlrev_b32_e32 v218, 16, v13
	v_and_b32_e32 v219, 0xffff0000, v13
	v_exp_f32_e32 v216, v216
	v_exp_f32_e32 v217, v217
	v_exp_f32_e32 v218, v218
	v_exp_f32_e32 v219, v219
	v_lshlrev_b32_e32 v220, 16, v80
	v_and_b32_e32 v221, 0xffff0000, v80
	v_lshlrev_b32_e32 v222, 16, v81
	v_and_b32_e32 v223, 0xffff0000, v81
	v_lshlrev_b32_e32 v224, 16, v148
	v_and_b32_e32 v225, 0xffff0000, v148
	v_lshlrev_b32_e32 v226, 16, v149
	v_and_b32_e32 v227, 0xffff0000, v149
	v_fma_f32 v208, v216, v208, v220
	v_fma_f32 v209, v217, v209, v221
	v_fma_f32 v210, v218, v210, v222
	v_fma_f32 v211, v219, v211, v223
	v_mul_f32_e32 v224, v208, v224
	v_mul_f32_e32 v225, v209, v225
	v_mul_f32_e32 v226, v210, v226
	v_mul_f32_e32 v227, v211, v227
	v_cvt_pk_bf16_f32 v228, v224, v225
	v_cvt_pk_bf16_f32 v229, v226, v227
	s_mov_b64 exec, s[14:15]
	global_store_dwordx2 v2, v[228:229], s[12:13]
	s_mov_b64 exec, -1
	v_lshlrev_b32_e32 v216, 16, v14
	v_and_b32_e32 v217, 0xffff0000, v14
	v_lshlrev_b32_e32 v218, 16, v15
	v_and_b32_e32 v219, 0xffff0000, v15
	v_exp_f32_e32 v216, v216
	v_exp_f32_e32 v217, v217
	v_exp_f32_e32 v218, v218
	v_exp_f32_e32 v219, v219
	v_lshlrev_b32_e32 v220, 16, v82
	v_and_b32_e32 v221, 0xffff0000, v82
	v_lshlrev_b32_e32 v222, 16, v83
	v_and_b32_e32 v223, 0xffff0000, v83
	v_lshlrev_b32_e32 v224, 16, v150
	v_and_b32_e32 v225, 0xffff0000, v150
	v_lshlrev_b32_e32 v226, 16, v151
	v_and_b32_e32 v227, 0xffff0000, v151
	v_fma_f32 v208, v216, v208, v220
	v_fma_f32 v209, v217, v209, v221
	v_fma_f32 v210, v218, v210, v222
	v_fma_f32 v211, v219, v211, v223
	v_mul_f32_e32 v224, v208, v224
	v_mul_f32_e32 v225, v209, v225
	v_mul_f32_e32 v226, v210, v226
	v_mul_f32_e32 v227, v211, v227
	v_cvt_pk_bf16_f32 v228, v224, v225
	v_cvt_pk_bf16_f32 v229, v226, v227
	s_mov_b64 exec, s[14:15]
	global_store_dwordx2 v2, v[228:229], s[12:13] offset:2048
	s_mov_b64 exec, -1
	v_add_u32_e32 v2, 0x3000, v3
	v_lshlrev_b32_e32 v216, 16, v16
	v_and_b32_e32 v217, 0xffff0000, v16
	v_lshlrev_b32_e32 v218, 16, v17
	v_and_b32_e32 v219, 0xffff0000, v17
	v_exp_f32_e32 v216, v216
	v_exp_f32_e32 v217, v217
	v_exp_f32_e32 v218, v218
	v_exp_f32_e32 v219, v219
	v_lshlrev_b32_e32 v220, 16, v84
	v_and_b32_e32 v221, 0xffff0000, v84
	v_lshlrev_b32_e32 v222, 16, v85
	v_and_b32_e32 v223, 0xffff0000, v85
	v_lshlrev_b32_e32 v224, 16, v152
	v_and_b32_e32 v225, 0xffff0000, v152
	v_lshlrev_b32_e32 v226, 16, v153
	v_and_b32_e32 v227, 0xffff0000, v153
	v_fma_f32 v208, v216, v208, v220
	v_fma_f32 v209, v217, v209, v221
	v_fma_f32 v210, v218, v210, v222
	v_fma_f32 v211, v219, v211, v223
	v_mul_f32_e32 v224, v208, v224
	v_mul_f32_e32 v225, v209, v225
	v_mul_f32_e32 v226, v210, v226
	v_mul_f32_e32 v227, v211, v227
	v_cvt_pk_bf16_f32 v228, v224, v225
	v_cvt_pk_bf16_f32 v229, v226, v227
	s_mov_b64 exec, s[14:15]
	global_store_dwordx2 v2, v[228:229], s[12:13]
	s_mov_b64 exec, -1
	v_lshlrev_b32_e32 v216, 16, v18
	v_and_b32_e32 v217, 0xffff0000, v18
	v_lshlrev_b32_e32 v218, 16, v19
	v_and_b32_e32 v219, 0xffff0000, v19
	v_exp_f32_e32 v216, v216
	v_exp_f32_e32 v217, v217
	v_exp_f32_e32 v218, v218
	v_exp_f32_e32 v219, v219
	v_lshlrev_b32_e32 v220, 16, v86
	v_and_b32_e32 v221, 0xffff0000, v86
	v_lshlrev_b32_e32 v222, 16, v87
	v_and_b32_e32 v223, 0xffff0000, v87
	v_lshlrev_b32_e32 v224, 16, v154
	v_and_b32_e32 v225, 0xffff0000, v154
	v_lshlrev_b32_e32 v226, 16, v155
	v_and_b32_e32 v227, 0xffff0000, v155
	v_fma_f32 v208, v216, v208, v220
	v_fma_f32 v209, v217, v209, v221
	v_fma_f32 v210, v218, v210, v222
	v_fma_f32 v211, v219, v211, v223
	v_mul_f32_e32 v224, v208, v224
	v_mul_f32_e32 v225, v209, v225
	v_mul_f32_e32 v226, v210, v226
	v_mul_f32_e32 v227, v211, v227
	v_cvt_pk_bf16_f32 v228, v224, v225
	v_cvt_pk_bf16_f32 v229, v226, v227
	s_mov_b64 exec, s[14:15]
	global_store_dwordx2 v2, v[228:229], s[12:13] offset:2048
	s_mov_b64 exec, -1
	v_add_u32_e32 v2, 0x4000, v3
	v_lshlrev_b32_e32 v216, 16, v20
	v_and_b32_e32 v217, 0xffff0000, v20
	v_lshlrev_b32_e32 v218, 16, v21
	v_and_b32_e32 v219, 0xffff0000, v21
	v_exp_f32_e32 v216, v216
	v_exp_f32_e32 v217, v217
	v_exp_f32_e32 v218, v218
	v_exp_f32_e32 v219, v219
	v_lshlrev_b32_e32 v220, 16, v88
	v_and_b32_e32 v221, 0xffff0000, v88
	v_lshlrev_b32_e32 v222, 16, v89
	v_and_b32_e32 v223, 0xffff0000, v89
	v_lshlrev_b32_e32 v224, 16, v156
	v_and_b32_e32 v225, 0xffff0000, v156
	v_lshlrev_b32_e32 v226, 16, v157
	v_and_b32_e32 v227, 0xffff0000, v157
	v_fma_f32 v208, v216, v208, v220
	v_fma_f32 v209, v217, v209, v221
	v_fma_f32 v210, v218, v210, v222
	v_fma_f32 v211, v219, v211, v223
	v_mul_f32_e32 v224, v208, v224
	v_mul_f32_e32 v225, v209, v225
	v_mul_f32_e32 v226, v210, v226
	v_mul_f32_e32 v227, v211, v227
	v_cvt_pk_bf16_f32 v228, v224, v225
	v_cvt_pk_bf16_f32 v229, v226, v227
	s_mov_b64 exec, s[14:15]
	global_store_dwordx2 v2, v[228:229], s[12:13]
	s_mov_b64 exec, -1
	v_lshlrev_b32_e32 v216, 16, v22
	v_and_b32_e32 v217, 0xffff0000, v22
	v_lshlrev_b32_e32 v218, 16, v23
	v_and_b32_e32 v219, 0xffff0000, v23
	v_exp_f32_e32 v216, v216
	v_exp_f32_e32 v217, v217
	v_exp_f32_e32 v218, v218
	v_exp_f32_e32 v219, v219
	v_lshlrev_b32_e32 v220, 16, v90
	v_and_b32_e32 v221, 0xffff0000, v90
	v_lshlrev_b32_e32 v222, 16, v91
	v_and_b32_e32 v223, 0xffff0000, v91
	v_lshlrev_b32_e32 v224, 16, v158
	v_and_b32_e32 v225, 0xffff0000, v158
	v_lshlrev_b32_e32 v226, 16, v159
	v_and_b32_e32 v227, 0xffff0000, v159
	v_fma_f32 v208, v216, v208, v220
	v_fma_f32 v209, v217, v209, v221
	v_fma_f32 v210, v218, v210, v222
	v_fma_f32 v211, v219, v211, v223
	v_mul_f32_e32 v224, v208, v224
	v_mul_f32_e32 v225, v209, v225
	v_mul_f32_e32 v226, v210, v226
	v_mul_f32_e32 v227, v211, v227
	v_cvt_pk_bf16_f32 v228, v224, v225
	v_cvt_pk_bf16_f32 v229, v226, v227
	s_mov_b64 exec, s[14:15]
	global_store_dwordx2 v2, v[228:229], s[12:13] offset:2048
	s_mov_b64 exec, -1
	v_add_u32_e32 v2, 0x5000, v3
	v_lshlrev_b32_e32 v216, 16, v24
	v_and_b32_e32 v217, 0xffff0000, v24
	v_lshlrev_b32_e32 v218, 16, v25
	v_and_b32_e32 v219, 0xffff0000, v25
	v_exp_f32_e32 v216, v216
	v_exp_f32_e32 v217, v217
	v_exp_f32_e32 v218, v218
	v_exp_f32_e32 v219, v219
	v_lshlrev_b32_e32 v220, 16, v92
	v_and_b32_e32 v221, 0xffff0000, v92
	v_lshlrev_b32_e32 v222, 16, v93
	v_and_b32_e32 v223, 0xffff0000, v93
	v_lshlrev_b32_e32 v224, 16, v160
	v_and_b32_e32 v225, 0xffff0000, v160
	v_lshlrev_b32_e32 v226, 16, v161
	v_and_b32_e32 v227, 0xffff0000, v161
	v_fma_f32 v208, v216, v208, v220
	v_fma_f32 v209, v217, v209, v221
	v_fma_f32 v210, v218, v210, v222
	v_fma_f32 v211, v219, v211, v223
	v_mul_f32_e32 v224, v208, v224
	v_mul_f32_e32 v225, v209, v225
	v_mul_f32_e32 v226, v210, v226
	v_mul_f32_e32 v227, v211, v227
	v_cvt_pk_bf16_f32 v228, v224, v225
	v_cvt_pk_bf16_f32 v229, v226, v227
	s_mov_b64 exec, s[14:15]
	global_store_dwordx2 v2, v[228:229], s[12:13]
	s_mov_b64 exec, -1
	v_lshlrev_b32_e32 v216, 16, v26
	v_and_b32_e32 v217, 0xffff0000, v26
	v_lshlrev_b32_e32 v218, 16, v27
	v_and_b32_e32 v219, 0xffff0000, v27
	v_exp_f32_e32 v216, v216
	v_exp_f32_e32 v217, v217
	v_exp_f32_e32 v218, v218
	v_exp_f32_e32 v219, v219
	v_lshlrev_b32_e32 v220, 16, v94
	v_and_b32_e32 v221, 0xffff0000, v94
	v_lshlrev_b32_e32 v222, 16, v95
	v_and_b32_e32 v223, 0xffff0000, v95
	v_lshlrev_b32_e32 v224, 16, v162
	v_and_b32_e32 v225, 0xffff0000, v162
	v_lshlrev_b32_e32 v226, 16, v163
	v_and_b32_e32 v227, 0xffff0000, v163
	v_fma_f32 v208, v216, v208, v220
	v_fma_f32 v209, v217, v209, v221
	v_fma_f32 v210, v218, v210, v222
	v_fma_f32 v211, v219, v211, v223
	v_mul_f32_e32 v224, v208, v224
	v_mul_f32_e32 v225, v209, v225
	v_mul_f32_e32 v226, v210, v226
	v_mul_f32_e32 v227, v211, v227
	v_cvt_pk_bf16_f32 v228, v224, v225
	v_cvt_pk_bf16_f32 v229, v226, v227
	s_mov_b64 exec, s[14:15]
	global_store_dwordx2 v2, v[228:229], s[12:13] offset:2048
	s_mov_b64 exec, -1
	v_add_u32_e32 v2, 0x6000, v3
	v_lshlrev_b32_e32 v216, 16, v28
	v_and_b32_e32 v217, 0xffff0000, v28
	v_lshlrev_b32_e32 v218, 16, v29
	v_and_b32_e32 v219, 0xffff0000, v29
	v_exp_f32_e32 v216, v216
	v_exp_f32_e32 v217, v217
	v_exp_f32_e32 v218, v218
	v_exp_f32_e32 v219, v219
	v_lshlrev_b32_e32 v220, 16, v96
	v_and_b32_e32 v221, 0xffff0000, v96
	v_lshlrev_b32_e32 v222, 16, v97
	v_and_b32_e32 v223, 0xffff0000, v97
	v_lshlrev_b32_e32 v224, 16, v164
	v_and_b32_e32 v225, 0xffff0000, v164
	v_lshlrev_b32_e32 v226, 16, v165
	v_and_b32_e32 v227, 0xffff0000, v165
	v_fma_f32 v208, v216, v208, v220
	v_fma_f32 v209, v217, v209, v221
	v_fma_f32 v210, v218, v210, v222
	v_fma_f32 v211, v219, v211, v223
	v_mul_f32_e32 v224, v208, v224
	v_mul_f32_e32 v225, v209, v225
	v_mul_f32_e32 v226, v210, v226
	v_mul_f32_e32 v227, v211, v227
	v_cvt_pk_bf16_f32 v228, v224, v225
	v_cvt_pk_bf16_f32 v229, v226, v227
	s_mov_b64 exec, s[14:15]
	global_store_dwordx2 v2, v[228:229], s[12:13]
	s_mov_b64 exec, -1
	v_lshlrev_b32_e32 v216, 16, v30
	v_and_b32_e32 v217, 0xffff0000, v30
	v_lshlrev_b32_e32 v218, 16, v31
	v_and_b32_e32 v219, 0xffff0000, v31
	v_exp_f32_e32 v216, v216
	v_exp_f32_e32 v217, v217
	v_exp_f32_e32 v218, v218
	v_exp_f32_e32 v219, v219
	v_lshlrev_b32_e32 v220, 16, v98
	v_and_b32_e32 v221, 0xffff0000, v98
	v_lshlrev_b32_e32 v222, 16, v99
	v_and_b32_e32 v223, 0xffff0000, v99
	v_lshlrev_b32_e32 v224, 16, v166
	v_and_b32_e32 v225, 0xffff0000, v166
	v_lshlrev_b32_e32 v226, 16, v167
	v_and_b32_e32 v227, 0xffff0000, v167
	v_fma_f32 v208, v216, v208, v220
	v_fma_f32 v209, v217, v209, v221
	v_fma_f32 v210, v218, v210, v222
	v_fma_f32 v211, v219, v211, v223
	v_mul_f32_e32 v224, v208, v224
	v_mul_f32_e32 v225, v209, v225
	v_mul_f32_e32 v226, v210, v226
	v_mul_f32_e32 v227, v211, v227
	v_cvt_pk_bf16_f32 v228, v224, v225
	v_cvt_pk_bf16_f32 v229, v226, v227
	s_mov_b64 exec, s[14:15]
	global_store_dwordx2 v2, v[228:229], s[12:13] offset:2048
	s_mov_b64 exec, -1
	v_add_u32_e32 v2, 0x7000, v3
	v_lshlrev_b32_e32 v216, 16, v32
	v_and_b32_e32 v217, 0xffff0000, v32
	v_lshlrev_b32_e32 v218, 16, v33
	v_and_b32_e32 v219, 0xffff0000, v33
	v_exp_f32_e32 v216, v216
	v_exp_f32_e32 v217, v217
	v_exp_f32_e32 v218, v218
	v_exp_f32_e32 v219, v219
	v_lshlrev_b32_e32 v220, 16, v100
	v_and_b32_e32 v221, 0xffff0000, v100
	v_lshlrev_b32_e32 v222, 16, v101
	v_and_b32_e32 v223, 0xffff0000, v101
	v_lshlrev_b32_e32 v224, 16, v168
	v_and_b32_e32 v225, 0xffff0000, v168
	v_lshlrev_b32_e32 v226, 16, v169
	v_and_b32_e32 v227, 0xffff0000, v169
	v_fma_f32 v208, v216, v208, v220
	v_fma_f32 v209, v217, v209, v221
	v_fma_f32 v210, v218, v210, v222
	v_fma_f32 v211, v219, v211, v223
	v_mul_f32_e32 v224, v208, v224
	v_mul_f32_e32 v225, v209, v225
	v_mul_f32_e32 v226, v210, v226
	v_mul_f32_e32 v227, v211, v227
	v_cvt_pk_bf16_f32 v228, v224, v225
	v_cvt_pk_bf16_f32 v229, v226, v227
	s_mov_b64 exec, s[14:15]
	global_store_dwordx2 v2, v[228:229], s[12:13]
	s_mov_b64 exec, -1
	v_lshlrev_b32_e32 v216, 16, v34
	v_and_b32_e32 v217, 0xffff0000, v34
	v_lshlrev_b32_e32 v218, 16, v35
	v_and_b32_e32 v219, 0xffff0000, v35
	v_exp_f32_e32 v216, v216
	v_exp_f32_e32 v217, v217
	v_exp_f32_e32 v218, v218
	v_exp_f32_e32 v219, v219
	v_lshlrev_b32_e32 v220, 16, v102
	v_and_b32_e32 v221, 0xffff0000, v102
	v_lshlrev_b32_e32 v222, 16, v103
	v_and_b32_e32 v223, 0xffff0000, v103
	v_lshlrev_b32_e32 v224, 16, v170
	v_and_b32_e32 v225, 0xffff0000, v170
	v_lshlrev_b32_e32 v226, 16, v171
	v_and_b32_e32 v227, 0xffff0000, v171
	v_fma_f32 v208, v216, v208, v220
	v_fma_f32 v209, v217, v209, v221
	v_fma_f32 v210, v218, v210, v222
	v_fma_f32 v211, v219, v211, v223
	v_mul_f32_e32 v224, v208, v224
	v_mul_f32_e32 v225, v209, v225
	v_mul_f32_e32 v226, v210, v226
	v_mul_f32_e32 v227, v211, v227
	v_cvt_pk_bf16_f32 v228, v224, v225
	v_cvt_pk_bf16_f32 v229, v226, v227
	s_mov_b64 exec, s[14:15]
	global_store_dwordx2 v2, v[228:229], s[12:13] offset:2048
	s_mov_b64 exec, -1
	v_add_u32_e32 v2, 0x8000, v3
	v_lshlrev_b32_e32 v216, 16, v36
	v_and_b32_e32 v217, 0xffff0000, v36
	v_lshlrev_b32_e32 v218, 16, v37
	v_and_b32_e32 v219, 0xffff0000, v37
	v_exp_f32_e32 v216, v216
	v_exp_f32_e32 v217, v217
	v_exp_f32_e32 v218, v218
	v_exp_f32_e32 v219, v219
	v_lshlrev_b32_e32 v220, 16, v104
	v_and_b32_e32 v221, 0xffff0000, v104
	v_lshlrev_b32_e32 v222, 16, v105
	v_and_b32_e32 v223, 0xffff0000, v105
	v_lshlrev_b32_e32 v224, 16, v172
	v_and_b32_e32 v225, 0xffff0000, v172
	v_lshlrev_b32_e32 v226, 16, v173
	v_and_b32_e32 v227, 0xffff0000, v173
	v_fma_f32 v208, v216, v208, v220
	v_fma_f32 v209, v217, v209, v221
	v_fma_f32 v210, v218, v210, v222
	v_fma_f32 v211, v219, v211, v223
	v_mul_f32_e32 v224, v208, v224
	v_mul_f32_e32 v225, v209, v225
	v_mul_f32_e32 v226, v210, v226
	v_mul_f32_e32 v227, v211, v227
	v_cvt_pk_bf16_f32 v228, v224, v225
	v_cvt_pk_bf16_f32 v229, v226, v227
	s_mov_b64 exec, s[14:15]
	global_store_dwordx2 v2, v[228:229], s[12:13]
	s_mov_b64 exec, -1
	v_lshlrev_b32_e32 v216, 16, v38
	v_and_b32_e32 v217, 0xffff0000, v38
	v_lshlrev_b32_e32 v218, 16, v39
	v_and_b32_e32 v219, 0xffff0000, v39
	v_exp_f32_e32 v216, v216
	v_exp_f32_e32 v217, v217
	v_exp_f32_e32 v218, v218
	v_exp_f32_e32 v219, v219
	v_lshlrev_b32_e32 v220, 16, v106
	v_and_b32_e32 v221, 0xffff0000, v106
	v_lshlrev_b32_e32 v222, 16, v107
	v_and_b32_e32 v223, 0xffff0000, v107
	v_lshlrev_b32_e32 v224, 16, v174
	v_and_b32_e32 v225, 0xffff0000, v174
	v_lshlrev_b32_e32 v226, 16, v175
	v_and_b32_e32 v227, 0xffff0000, v175
	v_fma_f32 v208, v216, v208, v220
	v_fma_f32 v209, v217, v209, v221
	v_fma_f32 v210, v218, v210, v222
	v_fma_f32 v211, v219, v211, v223
	v_mul_f32_e32 v224, v208, v224
	v_mul_f32_e32 v225, v209, v225
	v_mul_f32_e32 v226, v210, v226
	v_mul_f32_e32 v227, v211, v227
	v_cvt_pk_bf16_f32 v228, v224, v225
	v_cvt_pk_bf16_f32 v229, v226, v227
	s_mov_b64 exec, s[14:15]
	global_store_dwordx2 v2, v[228:229], s[12:13] offset:2048
	s_mov_b64 exec, -1
	v_add_u32_e32 v2, 0x9000, v3
	v_lshlrev_b32_e32 v216, 16, v40
	v_and_b32_e32 v217, 0xffff0000, v40
	v_lshlrev_b32_e32 v218, 16, v41
	v_and_b32_e32 v219, 0xffff0000, v41
	v_exp_f32_e32 v216, v216
	v_exp_f32_e32 v217, v217
	v_exp_f32_e32 v218, v218
	v_exp_f32_e32 v219, v219
	v_lshlrev_b32_e32 v220, 16, v108
	v_and_b32_e32 v221, 0xffff0000, v108
	v_lshlrev_b32_e32 v222, 16, v109
	v_and_b32_e32 v223, 0xffff0000, v109
	v_lshlrev_b32_e32 v224, 16, v176
	v_and_b32_e32 v225, 0xffff0000, v176
	v_lshlrev_b32_e32 v226, 16, v177
	v_and_b32_e32 v227, 0xffff0000, v177
	v_fma_f32 v208, v216, v208, v220
	v_fma_f32 v209, v217, v209, v221
	v_fma_f32 v210, v218, v210, v222
	v_fma_f32 v211, v219, v211, v223
	v_mul_f32_e32 v224, v208, v224
	v_mul_f32_e32 v225, v209, v225
	v_mul_f32_e32 v226, v210, v226
	v_mul_f32_e32 v227, v211, v227
	v_cvt_pk_bf16_f32 v228, v224, v225
	v_cvt_pk_bf16_f32 v229, v226, v227
	s_mov_b64 exec, s[14:15]
	global_store_dwordx2 v2, v[228:229], s[12:13]
	s_mov_b64 exec, -1
	v_lshlrev_b32_e32 v216, 16, v42
	v_and_b32_e32 v217, 0xffff0000, v42
	v_lshlrev_b32_e32 v218, 16, v43
	v_and_b32_e32 v219, 0xffff0000, v43
	v_exp_f32_e32 v216, v216
	v_exp_f32_e32 v217, v217
	v_exp_f32_e32 v218, v218
	v_exp_f32_e32 v219, v219
	v_lshlrev_b32_e32 v220, 16, v110
	v_and_b32_e32 v221, 0xffff0000, v110
	v_lshlrev_b32_e32 v222, 16, v111
	v_and_b32_e32 v223, 0xffff0000, v111
	v_lshlrev_b32_e32 v224, 16, v178
	v_and_b32_e32 v225, 0xffff0000, v178
	v_lshlrev_b32_e32 v226, 16, v179
	v_and_b32_e32 v227, 0xffff0000, v179
	v_fma_f32 v208, v216, v208, v220
	v_fma_f32 v209, v217, v209, v221
	v_fma_f32 v210, v218, v210, v222
	v_fma_f32 v211, v219, v211, v223
	v_mul_f32_e32 v224, v208, v224
	v_mul_f32_e32 v225, v209, v225
	v_mul_f32_e32 v226, v210, v226
	v_mul_f32_e32 v227, v211, v227
	v_cvt_pk_bf16_f32 v228, v224, v225
	v_cvt_pk_bf16_f32 v229, v226, v227
	s_mov_b64 exec, s[14:15]
	global_store_dwordx2 v2, v[228:229], s[12:13] offset:2048
	s_mov_b64 exec, -1
	v_add_u32_e32 v2, 0xa000, v3
	v_lshlrev_b32_e32 v216, 16, v44
	v_and_b32_e32 v217, 0xffff0000, v44
	v_lshlrev_b32_e32 v218, 16, v45
	v_and_b32_e32 v219, 0xffff0000, v45
	v_exp_f32_e32 v216, v216
	v_exp_f32_e32 v217, v217
	v_exp_f32_e32 v218, v218
	v_exp_f32_e32 v219, v219
	v_lshlrev_b32_e32 v220, 16, v112
	v_and_b32_e32 v221, 0xffff0000, v112
	v_lshlrev_b32_e32 v222, 16, v113
	v_and_b32_e32 v223, 0xffff0000, v113
	v_lshlrev_b32_e32 v224, 16, v180
	v_and_b32_e32 v225, 0xffff0000, v180
	v_lshlrev_b32_e32 v226, 16, v181
	v_and_b32_e32 v227, 0xffff0000, v181
	v_fma_f32 v208, v216, v208, v220
	v_fma_f32 v209, v217, v209, v221
	v_fma_f32 v210, v218, v210, v222
	v_fma_f32 v211, v219, v211, v223
	v_mul_f32_e32 v224, v208, v224
	v_mul_f32_e32 v225, v209, v225
	v_mul_f32_e32 v226, v210, v226
	v_mul_f32_e32 v227, v211, v227
	v_cvt_pk_bf16_f32 v228, v224, v225
	v_cvt_pk_bf16_f32 v229, v226, v227
	s_mov_b64 exec, s[14:15]
	global_store_dwordx2 v2, v[228:229], s[12:13]
	s_mov_b64 exec, -1
	v_lshlrev_b32_e32 v216, 16, v46
	v_and_b32_e32 v217, 0xffff0000, v46
	v_lshlrev_b32_e32 v218, 16, v47
	v_and_b32_e32 v219, 0xffff0000, v47
	v_exp_f32_e32 v216, v216
	v_exp_f32_e32 v217, v217
	v_exp_f32_e32 v218, v218
	v_exp_f32_e32 v219, v219
	v_lshlrev_b32_e32 v220, 16, v114
	v_and_b32_e32 v221, 0xffff0000, v114
	v_lshlrev_b32_e32 v222, 16, v115
	v_and_b32_e32 v223, 0xffff0000, v115
	v_lshlrev_b32_e32 v224, 16, v182
	v_and_b32_e32 v225, 0xffff0000, v182
	v_lshlrev_b32_e32 v226, 16, v183
	v_and_b32_e32 v227, 0xffff0000, v183
	v_fma_f32 v208, v216, v208, v220
	v_fma_f32 v209, v217, v209, v221
	v_fma_f32 v210, v218, v210, v222
	v_fma_f32 v211, v219, v211, v223
	v_mul_f32_e32 v224, v208, v224
	v_mul_f32_e32 v225, v209, v225
	v_mul_f32_e32 v226, v210, v226
	v_mul_f32_e32 v227, v211, v227
	v_cvt_pk_bf16_f32 v228, v224, v225
	v_cvt_pk_bf16_f32 v229, v226, v227
	s_mov_b64 exec, s[14:15]
	global_store_dwordx2 v2, v[228:229], s[12:13] offset:2048
	s_mov_b64 exec, -1
	v_add_u32_e32 v2, 0xb000, v3
	v_lshlrev_b32_e32 v216, 16, v48
	v_and_b32_e32 v217, 0xffff0000, v48
	v_lshlrev_b32_e32 v218, 16, v49
	v_and_b32_e32 v219, 0xffff0000, v49
	v_exp_f32_e32 v216, v216
	v_exp_f32_e32 v217, v217
	v_exp_f32_e32 v218, v218
	v_exp_f32_e32 v219, v219
	v_lshlrev_b32_e32 v220, 16, v116
	v_and_b32_e32 v221, 0xffff0000, v116
	v_lshlrev_b32_e32 v222, 16, v117
	v_and_b32_e32 v223, 0xffff0000, v117
	v_lshlrev_b32_e32 v224, 16, v184
	v_and_b32_e32 v225, 0xffff0000, v184
	v_lshlrev_b32_e32 v226, 16, v185
	v_and_b32_e32 v227, 0xffff0000, v185
	v_fma_f32 v208, v216, v208, v220
	v_fma_f32 v209, v217, v209, v221
	v_fma_f32 v210, v218, v210, v222
	v_fma_f32 v211, v219, v211, v223
	v_mul_f32_e32 v224, v208, v224
	v_mul_f32_e32 v225, v209, v225
	v_mul_f32_e32 v226, v210, v226
	v_mul_f32_e32 v227, v211, v227
	v_cvt_pk_bf16_f32 v228, v224, v225
	v_cvt_pk_bf16_f32 v229, v226, v227
	s_mov_b64 exec, s[14:15]
	global_store_dwordx2 v2, v[228:229], s[12:13]
	s_mov_b64 exec, -1
	v_lshlrev_b32_e32 v216, 16, v50
	v_and_b32_e32 v217, 0xffff0000, v50
	v_lshlrev_b32_e32 v218, 16, v51
	v_and_b32_e32 v219, 0xffff0000, v51
	v_exp_f32_e32 v216, v216
	v_exp_f32_e32 v217, v217
	v_exp_f32_e32 v218, v218
	v_exp_f32_e32 v219, v219
	v_lshlrev_b32_e32 v220, 16, v118
	v_and_b32_e32 v221, 0xffff0000, v118
	v_lshlrev_b32_e32 v222, 16, v119
	v_and_b32_e32 v223, 0xffff0000, v119
	v_lshlrev_b32_e32 v224, 16, v186
	v_and_b32_e32 v225, 0xffff0000, v186
	v_lshlrev_b32_e32 v226, 16, v187
	v_and_b32_e32 v227, 0xffff0000, v187
	v_fma_f32 v208, v216, v208, v220
	v_fma_f32 v209, v217, v209, v221
	v_fma_f32 v210, v218, v210, v222
	v_fma_f32 v211, v219, v211, v223
	v_mul_f32_e32 v224, v208, v224
	v_mul_f32_e32 v225, v209, v225
	v_mul_f32_e32 v226, v210, v226
	v_mul_f32_e32 v227, v211, v227
	v_cvt_pk_bf16_f32 v228, v224, v225
	v_cvt_pk_bf16_f32 v229, v226, v227
	s_mov_b64 exec, s[14:15]
	global_store_dwordx2 v2, v[228:229], s[12:13] offset:2048
	s_mov_b64 exec, -1
	v_add_u32_e32 v2, 0xc000, v3
	v_lshlrev_b32_e32 v216, 16, v52
	v_and_b32_e32 v217, 0xffff0000, v52
	v_lshlrev_b32_e32 v218, 16, v53
	v_and_b32_e32 v219, 0xffff0000, v53
	v_exp_f32_e32 v216, v216
	v_exp_f32_e32 v217, v217
	v_exp_f32_e32 v218, v218
	v_exp_f32_e32 v219, v219
	v_lshlrev_b32_e32 v220, 16, v120
	v_and_b32_e32 v221, 0xffff0000, v120
	v_lshlrev_b32_e32 v222, 16, v121
	v_and_b32_e32 v223, 0xffff0000, v121
	v_lshlrev_b32_e32 v224, 16, v188
	v_and_b32_e32 v225, 0xffff0000, v188
	v_lshlrev_b32_e32 v226, 16, v189
	v_and_b32_e32 v227, 0xffff0000, v189
	v_fma_f32 v208, v216, v208, v220
	v_fma_f32 v209, v217, v209, v221
	v_fma_f32 v210, v218, v210, v222
	v_fma_f32 v211, v219, v211, v223
	v_mul_f32_e32 v224, v208, v224
	v_mul_f32_e32 v225, v209, v225
	v_mul_f32_e32 v226, v210, v226
	v_mul_f32_e32 v227, v211, v227
	v_cvt_pk_bf16_f32 v228, v224, v225
	v_cvt_pk_bf16_f32 v229, v226, v227
	s_mov_b64 exec, s[16:17]
	global_store_dwordx2 v2, v[228:229], s[12:13]
	s_mov_b64 exec, -1
	v_lshlrev_b32_e32 v216, 16, v54
	v_and_b32_e32 v217, 0xffff0000, v54
	v_lshlrev_b32_e32 v218, 16, v55
	v_and_b32_e32 v219, 0xffff0000, v55
	v_exp_f32_e32 v216, v216
	v_exp_f32_e32 v217, v217
	v_exp_f32_e32 v218, v218
	v_exp_f32_e32 v219, v219
	v_lshlrev_b32_e32 v220, 16, v122
	v_and_b32_e32 v221, 0xffff0000, v122
	v_lshlrev_b32_e32 v222, 16, v123
	v_and_b32_e32 v223, 0xffff0000, v123
	v_lshlrev_b32_e32 v224, 16, v190
	v_and_b32_e32 v225, 0xffff0000, v190
	v_lshlrev_b32_e32 v226, 16, v191
	v_and_b32_e32 v227, 0xffff0000, v191
	v_fma_f32 v208, v216, v208, v220
	v_fma_f32 v209, v217, v209, v221
	v_fma_f32 v210, v218, v210, v222
	v_fma_f32 v211, v219, v211, v223
	v_mul_f32_e32 v224, v208, v224
	v_mul_f32_e32 v225, v209, v225
	v_mul_f32_e32 v226, v210, v226
	v_mul_f32_e32 v227, v211, v227
	v_cvt_pk_bf16_f32 v228, v224, v225
	v_cvt_pk_bf16_f32 v229, v226, v227
	s_mov_b64 exec, s[16:17]
	global_store_dwordx2 v2, v[228:229], s[12:13] offset:2048
	s_mov_b64 exec, -1
	v_add_u32_e32 v2, 0xd000, v3
	v_lshlrev_b32_e32 v216, 16, v56
	v_and_b32_e32 v217, 0xffff0000, v56
	v_lshlrev_b32_e32 v218, 16, v57
	v_and_b32_e32 v219, 0xffff0000, v57
	v_exp_f32_e32 v216, v216
	v_exp_f32_e32 v217, v217
	v_exp_f32_e32 v218, v218
	v_exp_f32_e32 v219, v219
	v_lshlrev_b32_e32 v220, 16, v124
	v_and_b32_e32 v221, 0xffff0000, v124
	v_lshlrev_b32_e32 v222, 16, v125
	v_and_b32_e32 v223, 0xffff0000, v125
	v_lshlrev_b32_e32 v224, 16, v192
	v_and_b32_e32 v225, 0xffff0000, v192
	v_lshlrev_b32_e32 v226, 16, v193
	v_and_b32_e32 v227, 0xffff0000, v193
	v_fma_f32 v208, v216, v208, v220
	v_fma_f32 v209, v217, v209, v221
	v_fma_f32 v210, v218, v210, v222
	v_fma_f32 v211, v219, v211, v223
	v_mul_f32_e32 v224, v208, v224
	v_mul_f32_e32 v225, v209, v225
	v_mul_f32_e32 v226, v210, v226
	v_mul_f32_e32 v227, v211, v227
	v_cvt_pk_bf16_f32 v228, v224, v225
	v_cvt_pk_bf16_f32 v229, v226, v227
	s_mov_b64 exec, s[16:17]
	global_store_dwordx2 v2, v[228:229], s[12:13]
	s_mov_b64 exec, -1
	v_lshlrev_b32_e32 v216, 16, v58
	v_and_b32_e32 v217, 0xffff0000, v58
	v_lshlrev_b32_e32 v218, 16, v59
	v_and_b32_e32 v219, 0xffff0000, v59
	v_exp_f32_e32 v216, v216
	v_exp_f32_e32 v217, v217
	v_exp_f32_e32 v218, v218
	v_exp_f32_e32 v219, v219
	v_lshlrev_b32_e32 v220, 16, v126
	v_and_b32_e32 v221, 0xffff0000, v126
	v_lshlrev_b32_e32 v222, 16, v127
	v_and_b32_e32 v223, 0xffff0000, v127
	v_lshlrev_b32_e32 v224, 16, v194
	v_and_b32_e32 v225, 0xffff0000, v194
	v_lshlrev_b32_e32 v226, 16, v195
	v_and_b32_e32 v227, 0xffff0000, v195
	v_fma_f32 v208, v216, v208, v220
	v_fma_f32 v209, v217, v209, v221
	v_fma_f32 v210, v218, v210, v222
	v_fma_f32 v211, v219, v211, v223
	v_mul_f32_e32 v224, v208, v224
	v_mul_f32_e32 v225, v209, v225
	v_mul_f32_e32 v226, v210, v226
	v_mul_f32_e32 v227, v211, v227
	v_cvt_pk_bf16_f32 v228, v224, v225
	v_cvt_pk_bf16_f32 v229, v226, v227
	s_mov_b64 exec, s[16:17]
	global_store_dwordx2 v2, v[228:229], s[12:13] offset:2048
	s_mov_b64 exec, -1
	v_add_u32_e32 v2, 0xe000, v3
	v_lshlrev_b32_e32 v216, 16, v60
	v_and_b32_e32 v217, 0xffff0000, v60
	v_lshlrev_b32_e32 v218, 16, v61
	v_and_b32_e32 v219, 0xffff0000, v61
	v_exp_f32_e32 v216, v216
	v_exp_f32_e32 v217, v217
	v_exp_f32_e32 v218, v218
	v_exp_f32_e32 v219, v219
	v_lshlrev_b32_e32 v220, 16, v128
	v_and_b32_e32 v221, 0xffff0000, v128
	v_lshlrev_b32_e32 v222, 16, v129
	v_and_b32_e32 v223, 0xffff0000, v129
	v_lshlrev_b32_e32 v224, 16, v196
	v_and_b32_e32 v225, 0xffff0000, v196
	v_lshlrev_b32_e32 v226, 16, v197
	v_and_b32_e32 v227, 0xffff0000, v197
	v_fma_f32 v208, v216, v208, v220
	v_fma_f32 v209, v217, v209, v221
	v_fma_f32 v210, v218, v210, v222
	v_fma_f32 v211, v219, v211, v223
	v_mul_f32_e32 v224, v208, v224
	v_mul_f32_e32 v225, v209, v225
	v_mul_f32_e32 v226, v210, v226
	v_mul_f32_e32 v227, v211, v227
	v_cvt_pk_bf16_f32 v228, v224, v225
	v_cvt_pk_bf16_f32 v229, v226, v227
	s_mov_b64 exec, s[16:17]
	global_store_dwordx2 v2, v[228:229], s[12:13]
	s_mov_b64 exec, -1
	v_lshlrev_b32_e32 v216, 16, v62
	v_and_b32_e32 v217, 0xffff0000, v62
	v_lshlrev_b32_e32 v218, 16, v63
	v_and_b32_e32 v219, 0xffff0000, v63
	v_exp_f32_e32 v216, v216
	v_exp_f32_e32 v217, v217
	v_exp_f32_e32 v218, v218
	v_exp_f32_e32 v219, v219
	v_lshlrev_b32_e32 v220, 16, v130
	v_and_b32_e32 v221, 0xffff0000, v130
	v_lshlrev_b32_e32 v222, 16, v131
	v_and_b32_e32 v223, 0xffff0000, v131
	v_lshlrev_b32_e32 v224, 16, v198
	v_and_b32_e32 v225, 0xffff0000, v198
	v_lshlrev_b32_e32 v226, 16, v199
	v_and_b32_e32 v227, 0xffff0000, v199
	v_fma_f32 v208, v216, v208, v220
	v_fma_f32 v209, v217, v209, v221
	v_fma_f32 v210, v218, v210, v222
	v_fma_f32 v211, v219, v211, v223
	v_mul_f32_e32 v224, v208, v224
	v_mul_f32_e32 v225, v209, v225
	v_mul_f32_e32 v226, v210, v226
	v_mul_f32_e32 v227, v211, v227
	v_cvt_pk_bf16_f32 v228, v224, v225
	v_cvt_pk_bf16_f32 v229, v226, v227
	s_mov_b64 exec, s[16:17]
	global_store_dwordx2 v2, v[228:229], s[12:13] offset:2048
	s_mov_b64 exec, -1
	v_add_u32_e32 v2, 0xf000, v3
	v_lshlrev_b32_e32 v216, 16, v64
	v_and_b32_e32 v217, 0xffff0000, v64
	v_lshlrev_b32_e32 v218, 16, v65
	v_and_b32_e32 v219, 0xffff0000, v65
	v_exp_f32_e32 v216, v216
	v_exp_f32_e32 v217, v217
	v_exp_f32_e32 v218, v218
	v_exp_f32_e32 v219, v219
	v_lshlrev_b32_e32 v220, 16, v132
	v_and_b32_e32 v221, 0xffff0000, v132
	v_lshlrev_b32_e32 v222, 16, v133
	v_and_b32_e32 v223, 0xffff0000, v133
	v_lshlrev_b32_e32 v224, 16, v200
	v_and_b32_e32 v225, 0xffff0000, v200
	v_lshlrev_b32_e32 v226, 16, v201
	v_and_b32_e32 v227, 0xffff0000, v201
	v_fma_f32 v208, v216, v208, v220
	v_fma_f32 v209, v217, v209, v221
	v_fma_f32 v210, v218, v210, v222
	v_fma_f32 v211, v219, v211, v223
	v_mul_f32_e32 v224, v208, v224
	v_mul_f32_e32 v225, v209, v225
	v_mul_f32_e32 v226, v210, v226
	v_mul_f32_e32 v227, v211, v227
	v_cvt_pk_bf16_f32 v228, v224, v225
	v_cvt_pk_bf16_f32 v229, v226, v227
	s_mov_b64 exec, s[16:17]
	global_store_dwordx2 v2, v[228:229], s[12:13]
	s_mov_b64 exec, -1
	v_lshlrev_b32_e32 v216, 16, v66
	v_and_b32_e32 v217, 0xffff0000, v66
	v_lshlrev_b32_e32 v218, 16, v67
	v_and_b32_e32 v219, 0xffff0000, v67
	v_exp_f32_e32 v216, v216
	v_exp_f32_e32 v217, v217
	v_exp_f32_e32 v218, v218
	v_exp_f32_e32 v219, v219
	v_lshlrev_b32_e32 v220, 16, v134
	v_and_b32_e32 v221, 0xffff0000, v134
	v_lshlrev_b32_e32 v222, 16, v135
	v_and_b32_e32 v223, 0xffff0000, v135
	v_lshlrev_b32_e32 v224, 16, v202
	v_and_b32_e32 v225, 0xffff0000, v202
	v_lshlrev_b32_e32 v226, 16, v203
	v_and_b32_e32 v227, 0xffff0000, v203
	v_fma_f32 v208, v216, v208, v220
	v_fma_f32 v209, v217, v209, v221
	v_fma_f32 v210, v218, v210, v222
	v_fma_f32 v211, v219, v211, v223
	v_mul_f32_e32 v224, v208, v224
	v_mul_f32_e32 v225, v209, v225
	v_mul_f32_e32 v226, v210, v226
	v_mul_f32_e32 v227, v211, v227
	v_cvt_pk_bf16_f32 v228, v224, v225
	v_cvt_pk_bf16_f32 v229, v226, v227
	s_mov_b64 exec, s[16:17]
	global_store_dwordx2 v2, v[228:229], s[12:13] offset:2048
	s_mov_b64 exec, -1
	v_add_u32_e32 v2, 0x10000, v3
	v_lshlrev_b32_e32 v216, 16, v68
	v_and_b32_e32 v217, 0xffff0000, v68
	v_lshlrev_b32_e32 v218, 16, v69
	v_and_b32_e32 v219, 0xffff0000, v69
	v_exp_f32_e32 v216, v216
	v_exp_f32_e32 v217, v217
	v_exp_f32_e32 v218, v218
	v_exp_f32_e32 v219, v219
	v_lshlrev_b32_e32 v220, 16, v136
	v_and_b32_e32 v221, 0xffff0000, v136
	v_lshlrev_b32_e32 v222, 16, v137
	v_and_b32_e32 v223, 0xffff0000, v137
	v_lshlrev_b32_e32 v224, 16, v204
	v_and_b32_e32 v225, 0xffff0000, v204
	v_lshlrev_b32_e32 v226, 16, v205
	v_and_b32_e32 v227, 0xffff0000, v205
	v_fma_f32 v208, v216, v208, v220
	v_fma_f32 v209, v217, v209, v221
	v_fma_f32 v210, v218, v210, v222
	v_fma_f32 v211, v219, v211, v223
	v_mul_f32_e32 v224, v208, v224
	v_mul_f32_e32 v225, v209, v225
	v_mul_f32_e32 v226, v210, v226
	v_mul_f32_e32 v227, v211, v227
	v_cvt_pk_bf16_f32 v228, v224, v225
	v_cvt_pk_bf16_f32 v229, v226, v227
	s_mov_b64 exec, s[16:17]
	global_store_dwordx2 v2, v[228:229], s[12:13]
	s_mov_b64 exec, -1
	v_lshlrev_b32_e32 v216, 16, v70
	v_and_b32_e32 v217, 0xffff0000, v70
	v_lshlrev_b32_e32 v218, 16, v71
	v_and_b32_e32 v219, 0xffff0000, v71
	v_exp_f32_e32 v216, v216
	v_exp_f32_e32 v217, v217
	v_exp_f32_e32 v218, v218
	v_exp_f32_e32 v219, v219
	v_lshlrev_b32_e32 v220, 16, v138
	v_and_b32_e32 v221, 0xffff0000, v138
	v_lshlrev_b32_e32 v222, 16, v139
	v_and_b32_e32 v223, 0xffff0000, v139
	v_lshlrev_b32_e32 v224, 16, v206
	v_and_b32_e32 v225, 0xffff0000, v206
	v_lshlrev_b32_e32 v226, 16, v207
	v_and_b32_e32 v227, 0xffff0000, v207
	v_fma_f32 v208, v216, v208, v220
	v_fma_f32 v209, v217, v209, v221
	v_fma_f32 v210, v218, v210, v222
	v_fma_f32 v211, v219, v211, v223
	v_mul_f32_e32 v224, v208, v224
	v_mul_f32_e32 v225, v209, v225
	v_mul_f32_e32 v226, v210, v226
	v_mul_f32_e32 v227, v211, v227
	v_cvt_pk_bf16_f32 v228, v224, v225
	v_cvt_pk_bf16_f32 v229, v226, v227
	s_mov_b64 exec, s[16:17]
	global_store_dwordx2 v2, v[228:229], s[12:13] offset:2048
	s_mov_b64 exec, -1
	s_branch .LBB0_185

.LBB0_380:
	v_readlane_b32 s4, v254, 30
	v_readlane_b32 s5, v254, 31
	s_andn2_b64 vcc, exec, s[4:5]
	s_barrier
	s_cbranch_vccnz .LBB0_319
	ds_bpermute_b32 v0, v115, v117
	v_cmp_gt_i32_e32 vcc, 16, v114
	s_and_b64 s[6:7], s[2:3], vcc
	s_and_saveexec_b64 s[4:5], s[6:7]
	s_cbranch_execz .LBB0_383
	s_waitcnt lgkmcnt(0)
	v_add_f32_e32 v0, v117, v0
	v_div_scale_f32 v66, s[6:7], v0, v0, 1.0
	v_rcp_f32_e32 v67, v66
	v_ashrrev_i32_e32 v115, 31, v114
	v_readlane_b32 s6, v252, 43
	v_readlane_b32 s7, v252, 44
	v_fma_f32 v68, -v66, v67, 1.0
	v_fmac_f32_e32 v67, v68, v67
	v_div_scale_f32 v68, vcc, 1.0, v0, 1.0
	v_mul_f32_e32 v69, v68, v67
	v_fma_f32 v70, -v66, v69, v68
	v_fmac_f32_e32 v69, v70, v67
	v_fma_f32 v66, -v66, v69, v68
	v_div_fmas_f32 v66, v66, v67, v69
	v_lshl_add_u64 v[68:69], s[10:11], 0, v[114:115]
	v_lshlrev_b64 v[68:69], 11, v[68:69]
	v_lshl_add_u64 v[68:69], s[6:7], 0, v[68:69]
	s_mov_b32 s17, s45
	v_div_fixup_f32 v66, v66, v0, 1.0
	v_lshl_add_u64 v[68:69], v[68:69], 0, s[16:17]
	v_lshlrev_b32_e32 v0, 1, v116
	v_lshl_add_u64 v[68:69], v[68:69], 0, v[0:1]
	global_load_dwordx2 v[98:99], v[68:69], off
	global_load_dwordx2 v[100:101], v[68:69], off offset:16
	global_load_dwordx2 v[102:103], v[68:69], off offset:32
	global_load_dwordx2 v[104:105], v[68:69], off offset:48
	global_load_dwordx2 v[106:107], v[68:69], off offset:64
	global_load_dwordx2 v[108:109], v[68:69], off offset:80
	global_load_dwordx2 v[110:111], v[68:69], off offset:96
	global_load_dwordx2 v[112:113], v[68:69], off offset:112
	global_load_dwordx2 v[114:115], v[68:69], off offset:128
	global_load_dwordx2 v[116:117], v[68:69], off offset:144
	global_load_dwordx2 v[118:119], v[68:69], off offset:160
	global_load_dwordx2 v[120:121], v[68:69], off offset:176
	global_load_dwordx2 v[122:123], v[68:69], off offset:192
	global_load_dwordx2 v[124:125], v[68:69], off offset:208
	global_load_dwordx2 v[126:127], v[68:69], off offset:224
	global_load_dwordx2 v[128:129], v[68:69], off offset:240
	s_waitcnt vmcnt(15)
	v_lshlrev_b32_e32 v130, 16, v98
	v_and_b32_e32 v131, 0xffff0000, v98
	v_lshlrev_b32_e32 v132, 16, v99
	v_and_b32_e32 v133, 0xffff0000, v99
	v_mul_f32_e32 v50, v66, v50
	v_mul_f32_e32 v51, v66, v51
	v_mul_f32_e32 v52, v66, v52
	v_mul_f32_e32 v53, v66, v53
	v_mul_f32_e32 v50, v50, v130
	v_mul_f32_e32 v51, v51, v131
	v_mul_f32_e32 v52, v52, v132
	v_mul_f32_e32 v53, v53, v133
	v_cvt_pk_bf16_f32 v50, v50, v51
	v_cvt_pk_bf16_f32 v51, v52, v53
	global_store_dwordx2 v[68:69], v[50:51], off
	s_waitcnt vmcnt(15)
	v_lshlrev_b32_e32 v130, 16, v100
	v_and_b32_e32 v131, 0xffff0000, v100
	v_lshlrev_b32_e32 v132, 16, v101
	v_and_b32_e32 v133, 0xffff0000, v101
	v_mul_f32_e32 v54, v66, v54
	v_mul_f32_e32 v55, v66, v55
	v_mul_f32_e32 v56, v66, v56
	v_mul_f32_e32 v57, v66, v57
	v_mul_f32_e32 v54, v54, v130
	v_mul_f32_e32 v55, v55, v131
	v_mul_f32_e32 v56, v56, v132
	v_mul_f32_e32 v57, v57, v133
	v_cvt_pk_bf16_f32 v54, v54, v55
	v_cvt_pk_bf16_f32 v55, v56, v57
	global_store_dwordx2 v[68:69], v[54:55], off offset:16
	s_waitcnt vmcnt(15)
	v_lshlrev_b32_e32 v130, 16, v102
	v_and_b32_e32 v131, 0xffff0000, v102
	v_lshlrev_b32_e32 v132, 16, v103
	v_and_b32_e32 v133, 0xffff0000, v103
	v_mul_f32_e32 v58, v66, v58
	v_mul_f32_e32 v59, v66, v59
	v_mul_f32_e32 v60, v66, v60
	v_mul_f32_e32 v61, v66, v61
	v_mul_f32_e32 v58, v58, v130
	v_mul_f32_e32 v59, v59, v131
	v_mul_f32_e32 v60, v60, v132
	v_mul_f32_e32 v61, v61, v133
	v_cvt_pk_bf16_f32 v58, v58, v59
	v_cvt_pk_bf16_f32 v59, v60, v61
	global_store_dwordx2 v[68:69], v[58:59], off offset:32
	s_waitcnt vmcnt(15)
	v_lshlrev_b32_e32 v130, 16, v104
	v_and_b32_e32 v131, 0xffff0000, v104
	v_lshlrev_b32_e32 v132, 16, v105
	v_and_b32_e32 v133, 0xffff0000, v105
	v_mul_f32_e32 v62, v66, v62
	v_mul_f32_e32 v63, v66, v63
	v_mul_f32_e32 v64, v66, v64
	v_mul_f32_e32 v65, v66, v65
	v_mul_f32_e32 v62, v62, v130
	v_mul_f32_e32 v63, v63, v131
	v_mul_f32_e32 v64, v64, v132
	v_mul_f32_e32 v65, v65, v133
	v_cvt_pk_bf16_f32 v62, v62, v63
	v_cvt_pk_bf16_f32 v63, v64, v65
	global_store_dwordx2 v[68:69], v[62:63], off offset:48
	s_waitcnt vmcnt(15)
	v_lshlrev_b32_e32 v130, 16, v106
	v_and_b32_e32 v131, 0xffff0000, v106
	v_lshlrev_b32_e32 v132, 16, v107
	v_and_b32_e32 v133, 0xffff0000, v107
	v_mul_f32_e32 v34, v66, v34
	v_mul_f32_e32 v35, v66, v35
	v_mul_f32_e32 v36, v66, v36
	v_mul_f32_e32 v37, v66, v37
	v_mul_f32_e32 v34, v34, v130
	v_mul_f32_e32 v35, v35, v131
	v_mul_f32_e32 v36, v36, v132
	v_mul_f32_e32 v37, v37, v133
	v_cvt_pk_bf16_f32 v34, v34, v35
	v_cvt_pk_bf16_f32 v35, v36, v37
	global_store_dwordx2 v[68:69], v[34:35], off offset:64
	s_waitcnt vmcnt(15)
	v_lshlrev_b32_e32 v130, 16, v108
	v_and_b32_e32 v131, 0xffff0000, v108
	v_lshlrev_b32_e32 v132, 16, v109
	v_and_b32_e32 v133, 0xffff0000, v109
	v_mul_f32_e32 v38, v66, v38
	v_mul_f32_e32 v39, v66, v39
	v_mul_f32_e32 v40, v66, v40
	v_mul_f32_e32 v41, v66, v41
	v_mul_f32_e32 v38, v38, v130
	v_mul_f32_e32 v39, v39, v131
	v_mul_f32_e32 v40, v40, v132
	v_mul_f32_e32 v41, v41, v133
	v_cvt_pk_bf16_f32 v38, v38, v39
	v_cvt_pk_bf16_f32 v39, v40, v41
	global_store_dwordx2 v[68:69], v[38:39], off offset:80
	s_waitcnt vmcnt(15)
	v_lshlrev_b32_e32 v130, 16, v110
	v_and_b32_e32 v131, 0xffff0000, v110
	v_lshlrev_b32_e32 v132, 16, v111
	v_and_b32_e32 v133, 0xffff0000, v111
	v_mul_f32_e32 v42, v66, v42
	v_mul_f32_e32 v43, v66, v43
	v_mul_f32_e32 v44, v66, v44
	v_mul_f32_e32 v45, v66, v45
	v_mul_f32_e32 v42, v42, v130
	v_mul_f32_e32 v43, v43, v131
	v_mul_f32_e32 v44, v44, v132
	v_mul_f32_e32 v45, v45, v133
	v_cvt_pk_bf16_f32 v42, v42, v43
	v_cvt_pk_bf16_f32 v43, v44, v45
	global_store_dwordx2 v[68:69], v[42:43], off offset:96
	s_waitcnt vmcnt(15)
	v_lshlrev_b32_e32 v130, 16, v112
	v_and_b32_e32 v131, 0xffff0000, v112
	v_lshlrev_b32_e32 v132, 16, v113
	v_and_b32_e32 v133, 0xffff0000, v113
	v_mul_f32_e32 v46, v66, v46
	v_mul_f32_e32 v47, v66, v47
	v_mul_f32_e32 v48, v66, v48
	v_mul_f32_e32 v49, v66, v49
	v_mul_f32_e32 v46, v46, v130
	v_mul_f32_e32 v47, v47, v131
	v_mul_f32_e32 v48, v48, v132
	v_mul_f32_e32 v49, v49, v133
	v_cvt_pk_bf16_f32 v46, v46, v47
	v_cvt_pk_bf16_f32 v47, v48, v49
	global_store_dwordx2 v[68:69], v[46:47], off offset:112
	s_waitcnt vmcnt(15)
	v_lshlrev_b32_e32 v130, 16, v114
	v_and_b32_e32 v131, 0xffff0000, v114
	v_lshlrev_b32_e32 v132, 16, v115
	v_and_b32_e32 v133, 0xffff0000, v115
	v_mul_f32_e32 v18, v66, v18
	v_mul_f32_e32 v19, v66, v19
	v_mul_f32_e32 v20, v66, v20
	v_mul_f32_e32 v21, v66, v21
	v_mul_f32_e32 v18, v18, v130
	v_mul_f32_e32 v19, v19, v131
	v_mul_f32_e32 v20, v20, v132
	v_mul_f32_e32 v21, v21, v133
	v_cvt_pk_bf16_f32 v18, v18, v19
	v_cvt_pk_bf16_f32 v19, v20, v21
	global_store_dwordx2 v[68:69], v[18:19], off offset:128
	s_waitcnt vmcnt(15)
	v_lshlrev_b32_e32 v130, 16, v116
	v_and_b32_e32 v131, 0xffff0000, v116
	v_lshlrev_b32_e32 v132, 16, v117
	v_and_b32_e32 v133, 0xffff0000, v117
	v_mul_f32_e32 v22, v66, v22
	v_mul_f32_e32 v23, v66, v23
	v_mul_f32_e32 v24, v66, v24
	v_mul_f32_e32 v25, v66, v25
	v_mul_f32_e32 v22, v22, v130
	v_mul_f32_e32 v23, v23, v131
	v_mul_f32_e32 v24, v24, v132
	v_mul_f32_e32 v25, v25, v133
	v_cvt_pk_bf16_f32 v22, v22, v23
	v_cvt_pk_bf16_f32 v23, v24, v25
	global_store_dwordx2 v[68:69], v[22:23], off offset:144
	s_waitcnt vmcnt(15)
	v_lshlrev_b32_e32 v130, 16, v118
	v_and_b32_e32 v131, 0xffff0000, v118
	v_lshlrev_b32_e32 v132, 16, v119
	v_and_b32_e32 v133, 0xffff0000, v119
	v_mul_f32_e32 v26, v66, v26
	v_mul_f32_e32 v27, v66, v27
	v_mul_f32_e32 v28, v66, v28
	v_mul_f32_e32 v29, v66, v29
	v_mul_f32_e32 v26, v26, v130
	v_mul_f32_e32 v27, v27, v131
	v_mul_f32_e32 v28, v28, v132
	v_mul_f32_e32 v29, v29, v133
	v_cvt_pk_bf16_f32 v26, v26, v27
	v_cvt_pk_bf16_f32 v27, v28, v29
	global_store_dwordx2 v[68:69], v[26:27], off offset:160
	s_waitcnt vmcnt(15)
	v_lshlrev_b32_e32 v130, 16, v120
	v_and_b32_e32 v131, 0xffff0000, v120
	v_lshlrev_b32_e32 v132, 16, v121
	v_and_b32_e32 v133, 0xffff0000, v121
	v_mul_f32_e32 v30, v66, v30
	v_mul_f32_e32 v31, v66, v31
	v_mul_f32_e32 v32, v66, v32
	v_mul_f32_e32 v33, v66, v33
	v_mul_f32_e32 v30, v30, v130
	v_mul_f32_e32 v31, v31, v131
	v_mul_f32_e32 v32, v32, v132
	v_mul_f32_e32 v33, v33, v133
	v_cvt_pk_bf16_f32 v30, v30, v31
	v_cvt_pk_bf16_f32 v31, v32, v33
	global_store_dwordx2 v[68:69], v[30:31], off offset:176
	s_waitcnt vmcnt(15)
	v_lshlrev_b32_e32 v130, 16, v122
	v_and_b32_e32 v131, 0xffff0000, v122
	v_lshlrev_b32_e32 v132, 16, v123
	v_and_b32_e32 v133, 0xffff0000, v123
	v_mul_f32_e32 v2, v66, v2
	v_mul_f32_e32 v3, v66, v3
	v_mul_f32_e32 v4, v66, v4
	v_mul_f32_e32 v5, v66, v5
	v_mul_f32_e32 v2, v2, v130
	v_mul_f32_e32 v3, v3, v131
	v_mul_f32_e32 v4, v4, v132
	v_mul_f32_e32 v5, v5, v133
	v_cvt_pk_bf16_f32 v2, v2, v3
	v_cvt_pk_bf16_f32 v3, v4, v5
	global_store_dwordx2 v[68:69], v[2:3], off offset:192
	s_waitcnt vmcnt(15)
	v_lshlrev_b32_e32 v130, 16, v124
	v_and_b32_e32 v131, 0xffff0000, v124
	v_lshlrev_b32_e32 v132, 16, v125
	v_and_b32_e32 v133, 0xffff0000, v125
	v_mul_f32_e32 v6, v66, v6
	v_mul_f32_e32 v7, v66, v7
	v_mul_f32_e32 v8, v66, v8
	v_mul_f32_e32 v9, v66, v9
	v_mul_f32_e32 v6, v6, v130
	v_mul_f32_e32 v7, v7, v131
	v_mul_f32_e32 v8, v8, v132
	v_mul_f32_e32 v9, v9, v133
	v_cvt_pk_bf16_f32 v6, v6, v7
	v_cvt_pk_bf16_f32 v7, v8, v9
	global_store_dwordx2 v[68:69], v[6:7], off offset:208
	s_waitcnt vmcnt(15)
	v_lshlrev_b32_e32 v130, 16, v126
	v_and_b32_e32 v131, 0xffff0000, v126
	v_lshlrev_b32_e32 v132, 16, v127
	v_and_b32_e32 v133, 0xffff0000, v127
	v_mul_f32_e32 v10, v66, v10
	v_mul_f32_e32 v11, v66, v11
	v_mul_f32_e32 v12, v66, v12
	v_mul_f32_e32 v13, v66, v13
	v_mul_f32_e32 v10, v10, v130
	v_mul_f32_e32 v11, v11, v131
	v_mul_f32_e32 v12, v12, v132
	v_mul_f32_e32 v13, v13, v133
	v_cvt_pk_bf16_f32 v10, v10, v11
	v_cvt_pk_bf16_f32 v11, v12, v13
	global_store_dwordx2 v[68:69], v[10:11], off offset:224
	s_waitcnt vmcnt(15)
	v_lshlrev_b32_e32 v130, 16, v128
	v_and_b32_e32 v131, 0xffff0000, v128
	v_lshlrev_b32_e32 v132, 16, v129
	v_and_b32_e32 v133, 0xffff0000, v129
	v_mul_f32_e32 v14, v66, v14
	v_mul_f32_e32 v15, v66, v15
	v_mul_f32_e32 v16, v66, v16
	v_mul_f32_e32 v17, v66, v17
	v_mul_f32_e32 v14, v14, v130
	v_mul_f32_e32 v15, v15, v131
	v_mul_f32_e32 v16, v16, v132
	v_mul_f32_e32 v17, v17, v133
	v_cvt_pk_bf16_f32 v14, v14, v15
	v_cvt_pk_bf16_f32 v15, v16, v17
	global_store_dwordx2 v[68:69], v[14:15], off offset:240

.LBB0_561:
	v_readlane_b32 s20, v252, 51
	v_or_b32_e32 v3, s62, v4
	s_add_i32 s29, 0, 0x10000
	v_or_b32_e32 v4, s20, v4
	v_add_u32_e32 v16, s29, v4
	ds_read_b128 v[18:21], v16
	ds_read_b128 v[22:25], v16 offset:1024
	ds_read_b128 v[26:29], v16 offset:2048
	ds_read_b128 v[30:33], v16 offset:3072
	s_add_i32 s34, 0, 0x1c000
	v_add_u32_e32 v12, 0, v3
	s_add_i32 s30, 0, 0x14000
	s_add_i32 s31, 0, 0x18000
	v_add_u32_e32 v13, s34, v4
	v_add_u32_e32 v15, s30, v4
	v_add_u32_e32 v14, s31, v4
	s_add_u32 s20, s4, 0x18080
	s_addc_u32 s21, s5, 0
	s_add_i32 s35, s63, 0xc000
	s_mov_b32 m0, s35
	s_add_i32 s36, s63, 0xe000
	ds_read_b128 v[8:11], v12
	ds_read_b128 v[34:37], v12 offset:1024
	ds_read_b128 v[38:41], v12 offset:2048
	ds_read_b128 v[42:45], v12 offset:3072
	ds_read_b128 v[46:49], v12 offset:4096
	ds_read_b128 v[50:53], v12 offset:5120
	ds_read_b128 v[54:57], v12 offset:6144
	ds_read_b128 v[58:61], v12 offset:7168
	global_load_lds_dwordx4 v0, s[20:21]
	s_mov_b32 m0, s36
	v_mov_b32_e32 v3, v1
	s_waitcnt lgkmcnt(0)
	global_load_lds_dwordx4 v2, s[20:21]
	s_waitcnt lgkmcnt(8)
	s_barrier
	s_waitcnt lgkmcnt(0)
	s_setprio 1
	s_waitcnt lgkmcnt(0)
	v_mfma_f32_16x16x32_bf16 v[4:7], v[18:21], v[8:11], 0
	v_mfma_f32_16x16x32_bf16 v[62:65], v[22:25], v[34:37], v[4:7]
	v_mfma_f32_16x16x32_bf16 v[4:7], v[26:29], v[8:11], 0
	v_mfma_f32_16x16x32_bf16 v[66:69], v[30:33], v[34:37], v[4:7]
	v_mfma_f32_16x16x32_bf16 v[4:7], v[18:21], v[38:41], 0
	s_waitcnt vmcnt(0)
	v_mfma_f32_16x16x32_bf16 v[70:73], v[22:25], v[42:45], v[4:7]
	v_mfma_f32_16x16x32_bf16 v[4:7], v[26:29], v[38:41], 0
	v_mfma_f32_16x16x32_bf16 v[74:77], v[30:33], v[42:45], v[4:7]
	v_mfma_f32_16x16x32_bf16 v[4:7], v[18:21], v[46:49], 0
	v_mfma_f32_16x16x32_bf16 v[78:81], v[22:25], v[50:53], v[4:7]
	v_mfma_f32_16x16x32_bf16 v[4:7], v[26:29], v[46:49], 0
	v_mfma_f32_16x16x32_bf16 v[82:85], v[30:33], v[50:53], v[4:7]
	v_mfma_f32_16x16x32_bf16 v[4:7], v[18:21], v[54:57], 0
	v_mfma_f32_16x16x32_bf16 v[86:89], v[22:25], v[58:61], v[4:7]
	v_mfma_f32_16x16x32_bf16 v[4:7], v[26:29], v[54:57], 0
	v_mfma_f32_16x16x32_bf16 v[90:93], v[30:33], v[58:61], v[4:7]
	s_setprio 0
	s_barrier
	s_nop 4
	v_lshl_add_u64 v[4:5], s[18:19], 0, v[0:1]
	s_add_i32 s37, s29, s53
	v_lshl_add_u64 v[6:7], v[4:5], 0, s[76:77]
	s_mov_b32 m0, s37
	ds_read_b128 v[94:97], v15
	ds_read_b128 v[98:101], v15 offset:1024
	ds_read_b128 v[102:105], v15 offset:2048
	ds_read_b128 v[106:109], v15 offset:3072
	global_load_lds_dwordx4 v[6:7], off
	v_lshl_add_u64 v[6:7], s[18:19], 0, v[2:3]
	s_add_i32 s38, s37, 0x2000
	v_lshl_add_u64 v[110:111], v[6:7], 0, s[76:77]
	s_mov_b32 m0, s38
	s_nop 0
	global_load_lds_dwordx4 v[110:111], off
	s_barrier
	s_waitcnt lgkmcnt(0)
	s_setprio 1
	s_waitcnt lgkmcnt(0)
	v_mfma_f32_16x16x32_bf16 v[110:113], v[94:97], v[8:11], 0
	v_mfma_f32_16x16x32_bf16 v[8:11], v[102:105], v[8:11], 0
	v_mfma_f32_16x16x32_bf16 v[110:113], v[98:101], v[34:37], v[110:113]
	v_mfma_f32_16x16x32_bf16 v[34:37], v[106:109], v[34:37], v[8:11]
	v_mfma_f32_16x16x32_bf16 v[8:11], v[94:97], v[38:41], 0
	v_mfma_f32_16x16x32_bf16 v[114:117], v[98:101], v[42:45], v[8:11]
	v_mfma_f32_16x16x32_bf16 v[8:11], v[102:105], v[38:41], 0
	v_mfma_f32_16x16x32_bf16 v[38:41], v[106:109], v[42:45], v[8:11]
	v_mfma_f32_16x16x32_bf16 v[8:11], v[94:97], v[46:49], 0
	v_mfma_f32_16x16x32_bf16 v[42:45], v[98:101], v[50:53], v[8:11]
	v_mfma_f32_16x16x32_bf16 v[8:11], v[102:105], v[46:49], 0
	v_mfma_f32_16x16x32_bf16 v[46:49], v[106:109], v[50:53], v[8:11]
	v_mfma_f32_16x16x32_bf16 v[8:11], v[94:97], v[54:57], 0
	v_mfma_f32_16x16x32_bf16 v[50:53], v[98:101], v[58:61], v[8:11]
	v_mfma_f32_16x16x32_bf16 v[8:11], v[102:105], v[54:57], 0
	v_mfma_f32_16x16x32_bf16 v[54:57], v[106:109], v[58:61], v[8:11]
	s_setprio 0
	s_nop 5
	v_lshl_add_u64 v[8:9], s[4:5], 0, v[0:1]
	s_mov_b32 m0, s63
	v_lshl_add_u64 v[10:11], v[8:9], 0, s[76:77]
	s_barrier
	ds_read_b128 v[58:61], v12 offset:16384
	ds_read_b128 v[118:121], v12 offset:17408
	ds_read_b128 v[122:125], v12 offset:18432
	ds_read_b128 v[126:129], v12 offset:19456
	ds_read_b128 v[130:133], v12 offset:20480
	ds_read_b128 v[134:137], v12 offset:21504
	ds_read_b128 v[138:141], v12 offset:22528
	ds_read_b128 v[142:145], v12 offset:23552
	global_load_lds_dwordx4 v[10:11], off
	v_lshl_add_u64 v[10:11], s[4:5], 0, v[2:3]
	v_lshl_add_u64 v[146:147], v[10:11], 0, s[76:77]
	s_mov_b32 m0, s24
	s_nop 0
	global_load_lds_dwordx4 v[146:147], off
	s_barrier
	s_waitcnt lgkmcnt(0)
	s_setprio 1
	s_waitcnt lgkmcnt(0)
	v_mfma_f32_16x16x32_bf16 v[146:149], v[18:21], v[58:61], 0
	v_mfma_f32_16x16x32_bf16 v[154:157], v[18:21], v[122:125], 0
	v_mfma_f32_16x16x32_bf16 v[162:165], v[18:21], v[130:133], 0
	v_mfma_f32_16x16x32_bf16 v[18:21], v[18:21], v[138:141], 0
	v_mfma_f32_16x16x32_bf16 v[146:149], v[22:25], v[118:121], v[146:149]
	v_mfma_f32_16x16x32_bf16 v[150:153], v[26:29], v[58:61], 0
	v_mfma_f32_16x16x32_bf16 v[154:157], v[22:25], v[126:129], v[154:157]
	v_mfma_f32_16x16x32_bf16 v[158:161], v[26:29], v[122:125], 0
	v_mfma_f32_16x16x32_bf16 v[162:165], v[22:25], v[134:137], v[162:165]
	v_mfma_f32_16x16x32_bf16 v[166:169], v[26:29], v[130:133], 0
	v_mfma_f32_16x16x32_bf16 v[18:21], v[22:25], v[142:145], v[18:21]
	v_mfma_f32_16x16x32_bf16 v[22:25], v[26:29], v[138:141], 0
	v_mfma_f32_16x16x32_bf16 v[150:153], v[30:33], v[118:121], v[150:153]
	v_mfma_f32_16x16x32_bf16 v[158:161], v[30:33], v[126:129], v[158:161]
	v_mfma_f32_16x16x32_bf16 v[166:169], v[30:33], v[134:137], v[166:169]
	v_mfma_f32_16x16x32_bf16 v[22:25], v[30:33], v[142:145], v[22:25]
	s_setprio 0
	s_barrier
	s_add_u32 s20, s18, 0x18100
	s_addc_u32 s21, s19, 0
	s_add_i32 s39, s30, s53
	s_mov_b32 m0, s39
	s_add_i32 s43, s39, 0x2000
	global_load_lds_dwordx4 v0, s[20:21]
	s_mov_b32 m0, s43
	s_nop 0
	global_load_lds_dwordx4 v2, s[20:21]
	s_waitcnt vmcnt(6)
	s_barrier
	s_setprio 1
	v_mfma_f32_16x16x32_bf16 v[26:29], v[94:97], v[58:61], 0
	v_mfma_f32_16x16x32_bf16 v[30:33], v[102:105], v[58:61], 0
	v_mfma_f32_16x16x32_bf16 v[26:29], v[98:101], v[118:121], v[26:29]
	v_mfma_f32_16x16x32_bf16 v[30:33], v[106:109], v[118:121], v[30:33]
	v_mfma_f32_16x16x32_bf16 v[58:61], v[94:97], v[122:125], 0
	v_mfma_f32_16x16x32_bf16 v[118:121], v[102:105], v[122:125], 0
	v_mfma_f32_16x16x32_bf16 v[122:125], v[94:97], v[130:133], 0
	v_mfma_f32_16x16x32_bf16 v[94:97], v[94:97], v[138:141], 0
	v_mfma_f32_16x16x32_bf16 v[58:61], v[98:101], v[126:129], v[58:61]
	v_mfma_f32_16x16x32_bf16 v[118:121], v[106:109], v[126:129], v[118:121]
	v_mfma_f32_16x16x32_bf16 v[122:125], v[98:101], v[134:137], v[122:125]
	v_mfma_f32_16x16x32_bf16 v[126:129], v[102:105], v[130:133], 0
	v_mfma_f32_16x16x32_bf16 v[94:97], v[98:101], v[142:145], v[94:97]
	v_mfma_f32_16x16x32_bf16 v[98:101], v[102:105], v[138:141], 0
	v_mfma_f32_16x16x32_bf16 v[126:129], v[106:109], v[134:137], v[126:129]
	v_mfma_f32_16x16x32_bf16 v[98:101], v[106:109], v[142:145], v[98:101]
	s_setprio 0
	s_barrier
	ds_read_b128 v[102:105], v14
	ds_read_b128 v[106:109], v14 offset:1024
	ds_read_b128 v[130:133], v14 offset:2048
	ds_read_b128 v[134:137], v14 offset:3072
	s_add_u32 s20, s4, 0x18100
	s_addc_u32 s21, s5, 0
	s_mov_b32 m0, s25
	ds_read_b128 v[138:141], v12 offset:32768
	ds_read_b128 v[142:145], v12 offset:33792
	ds_read_b128 v[170:173], v12 offset:34816
	ds_read_b128 v[174:177], v12 offset:35840
	ds_read_b128 v[178:181], v12 offset:36864
	ds_read_b128 v[182:185], v12 offset:37888
	ds_read_b128 v[186:189], v12 offset:38912
	ds_read_b128 v[204:207], v12 offset:39936
	global_load_lds_dwordx4 v0, s[20:21]
	s_mov_b32 m0, s26
	s_nop 0
	global_load_lds_dwordx4 v2, s[20:21]
	s_waitcnt lgkmcnt(8)
	s_barrier
	s_waitcnt lgkmcnt(0)
	s_setprio 1
	s_waitcnt lgkmcnt(0)
	v_mfma_f32_16x16x32_bf16 v[62:65], v[102:105], v[138:141], v[62:65]
	v_mfma_f32_16x16x32_bf16 v[66:69], v[130:133], v[138:141], v[66:69]
	v_mfma_f32_16x16x32_bf16 v[74:77], v[130:133], v[170:173], v[74:77]
	v_mfma_f32_16x16x32_bf16 v[86:89], v[102:105], v[186:189], v[86:89]
	v_mfma_f32_16x16x32_bf16 v[90:93], v[130:133], v[186:189], v[90:93]
	v_mfma_f32_16x16x32_bf16 v[62:65], v[106:109], v[142:145], v[62:65]
	v_mfma_f32_16x16x32_bf16 v[66:69], v[134:137], v[142:145], v[66:69]
	v_mfma_f32_16x16x32_bf16 v[70:73], v[102:105], v[170:173], v[70:73]
	v_mfma_f32_16x16x32_bf16 v[74:77], v[134:137], v[174:177], v[74:77]
	v_mfma_f32_16x16x32_bf16 v[78:81], v[102:105], v[178:181], v[78:81]
	v_mfma_f32_16x16x32_bf16 v[82:85], v[130:133], v[178:181], v[82:85]
	v_mfma_f32_16x16x32_bf16 v[86:89], v[106:109], v[204:207], v[86:89]
	v_mfma_f32_16x16x32_bf16 v[90:93], v[134:137], v[204:207], v[90:93]
	v_mfma_f32_16x16x32_bf16 v[70:73], v[106:109], v[174:177], v[70:73]
	v_mfma_f32_16x16x32_bf16 v[78:81], v[106:109], v[182:185], v[78:81]
	v_mfma_f32_16x16x32_bf16 v[82:85], v[134:137], v[182:185], v[82:85]
	s_setprio 0
	s_barrier
	s_mov_b64 s[20:21], 0x180
	s_add_i32 s46, s31, s53
	v_lshl_add_u64 v[192:193], v[4:5], 0, s[20:21]
	s_mov_b32 m0, s46
	s_add_i32 s47, s46, 0x2000
	ds_read_b128 v[208:211], v13
	ds_read_b128 v[212:215], v13 offset:1024
	ds_read_b128 v[216:219], v13 offset:2048
	ds_read_b128 v[220:223], v13 offset:3072
	global_load_lds_dwordx4 v[192:193], off
	v_lshl_add_u64 v[192:193], v[6:7], 0, s[20:21]
	s_mov_b32 m0, s47
	s_nop 0
	global_load_lds_dwordx4 v[192:193], off
	s_barrier
	s_waitcnt lgkmcnt(0)
	s_setprio 1
	s_waitcnt lgkmcnt(0)
	v_mfma_f32_16x16x32_bf16 v[110:113], v[208:211], v[138:141], v[110:113]
	v_mfma_f32_16x16x32_bf16 v[34:37], v[216:219], v[138:141], v[34:37]
	v_mfma_f32_16x16x32_bf16 v[114:117], v[208:211], v[170:173], v[114:117]
	v_mfma_f32_16x16x32_bf16 v[38:41], v[216:219], v[170:173], v[38:41]
	v_mfma_f32_16x16x32_bf16 v[42:45], v[208:211], v[178:181], v[42:45]
	v_mfma_f32_16x16x32_bf16 v[46:49], v[216:219], v[178:181], v[46:49]
	v_mfma_f32_16x16x32_bf16 v[50:53], v[208:211], v[186:189], v[50:53]
	v_mfma_f32_16x16x32_bf16 v[54:57], v[216:219], v[186:189], v[54:57]
	v_mfma_f32_16x16x32_bf16 v[110:113], v[212:215], v[142:145], v[110:113]
	v_mfma_f32_16x16x32_bf16 v[34:37], v[220:223], v[142:145], v[34:37]
	v_mfma_f32_16x16x32_bf16 v[114:117], v[212:215], v[174:177], v[114:117]
	v_mfma_f32_16x16x32_bf16 v[38:41], v[220:223], v[174:177], v[38:41]
	v_mfma_f32_16x16x32_bf16 v[42:45], v[212:215], v[182:185], v[42:45]
	v_mfma_f32_16x16x32_bf16 v[46:49], v[220:223], v[182:185], v[46:49]
	v_mfma_f32_16x16x32_bf16 v[50:53], v[212:215], v[204:207], v[50:53]
	v_mfma_f32_16x16x32_bf16 v[54:57], v[220:223], v[204:207], v[54:57]
	s_setprio 0
	s_mov_b32 m0, s27
	v_lshl_add_u64 v[192:193], v[8:9], 0, s[20:21]
	s_barrier
	ds_read_b128 v[138:141], v12 offset:49152
	ds_read_b128 v[142:145], v12 offset:50176
	ds_read_b128 v[170:173], v12 offset:51200
	ds_read_b128 v[174:177], v12 offset:52224
	ds_read_b128 v[178:181], v12 offset:53248
	ds_read_b128 v[182:185], v12 offset:54272
	ds_read_b128 v[186:189], v12 offset:55296
	ds_read_b128 v[204:207], v12 offset:56320
	global_load_lds_dwordx4 v[192:193], off
	v_lshl_add_u64 v[192:193], v[10:11], 0, s[20:21]
	s_mov_b32 m0, s28
	s_nop 0
	global_load_lds_dwordx4 v[192:193], off
	s_barrier
	s_waitcnt lgkmcnt(0)
	s_setprio 1
	s_waitcnt lgkmcnt(0)
	v_mfma_f32_16x16x32_bf16 v[146:149], v[102:105], v[138:141], v[146:149]
	v_mfma_f32_16x16x32_bf16 v[150:153], v[130:133], v[138:141], v[150:153]
	v_mfma_f32_16x16x32_bf16 v[154:157], v[102:105], v[170:173], v[154:157]
	v_mfma_f32_16x16x32_bf16 v[158:161], v[130:133], v[170:173], v[158:161]
	v_mfma_f32_16x16x32_bf16 v[162:165], v[102:105], v[178:181], v[162:165]
	v_mfma_f32_16x16x32_bf16 v[166:169], v[130:133], v[178:181], v[166:169]
	v_mfma_f32_16x16x32_bf16 v[22:25], v[130:133], v[186:189], v[22:25]
	v_mfma_f32_16x16x32_bf16 v[146:149], v[106:109], v[142:145], v[146:149]
	v_mfma_f32_16x16x32_bf16 v[150:153], v[134:137], v[142:145], v[150:153]
	v_mfma_f32_16x16x32_bf16 v[154:157], v[106:109], v[174:177], v[154:157]
	v_mfma_f32_16x16x32_bf16 v[158:161], v[134:137], v[174:177], v[158:161]
	v_mfma_f32_16x16x32_bf16 v[162:165], v[106:109], v[182:185], v[162:165]
	v_mfma_f32_16x16x32_bf16 v[166:169], v[134:137], v[182:185], v[166:169]
	v_mfma_f32_16x16x32_bf16 v[18:21], v[102:105], v[186:189], v[18:21]
	v_mfma_f32_16x16x32_bf16 v[22:25], v[134:137], v[204:207], v[22:25]
	v_mfma_f32_16x16x32_bf16 v[18:21], v[106:109], v[204:207], v[18:21]
	s_setprio 0
	s_barrier
	s_add_u32 s20, s18, 0x18180
	s_addc_u32 s21, s19, 0
	s_add_i32 s52, s34, s53
	s_mov_b32 m0, s52
	s_add_i32 s60, s52, 0x2000
	global_load_lds_dwordx4 v0, s[20:21]
	s_mov_b32 m0, s60
	s_nop 0
	global_load_lds_dwordx4 v2, s[20:21]
	s_waitcnt vmcnt(6)
	s_barrier
	s_setprio 1
	v_mfma_f32_16x16x32_bf16 v[26:29], v[208:211], v[138:141], v[26:29]
	v_mfma_f32_16x16x32_bf16 v[30:33], v[216:219], v[138:141], v[30:33]
	v_mfma_f32_16x16x32_bf16 v[58:61], v[208:211], v[170:173], v[58:61]
	v_mfma_f32_16x16x32_bf16 v[102:105], v[216:219], v[170:173], v[118:121]
	v_mfma_f32_16x16x32_bf16 v[106:109], v[208:211], v[178:181], v[122:125]
	v_mfma_f32_16x16x32_bf16 v[118:121], v[216:219], v[178:181], v[126:129]
	v_mfma_f32_16x16x32_bf16 v[94:97], v[208:211], v[186:189], v[94:97]
	v_mfma_f32_16x16x32_bf16 v[98:101], v[216:219], v[186:189], v[98:101]
	v_mfma_f32_16x16x32_bf16 v[26:29], v[212:215], v[142:145], v[26:29]
	v_mfma_f32_16x16x32_bf16 v[30:33], v[220:223], v[142:145], v[30:33]
	v_mfma_f32_16x16x32_bf16 v[58:61], v[212:215], v[174:177], v[58:61]
	v_mfma_f32_16x16x32_bf16 v[102:105], v[220:223], v[174:177], v[102:105]
	v_mfma_f32_16x16x32_bf16 v[106:109], v[212:215], v[182:185], v[106:109]
	v_mfma_f32_16x16x32_bf16 v[118:121], v[220:223], v[182:185], v[118:121]
	v_mfma_f32_16x16x32_bf16 v[94:97], v[212:215], v[204:207], v[94:97]
	v_mfma_f32_16x16x32_bf16 v[98:101], v[220:223], v[204:207], v[98:101]
	s_setprio 0
	s_barrier
	ds_read_b128 v[122:125], v16
	ds_read_b128 v[126:129], v16 offset:1024
	ds_read_b128 v[130:133], v16 offset:2048
	ds_read_b128 v[134:137], v16 offset:3072
	s_add_u32 s20, s4, 0x18180
	s_addc_u32 s21, s5, 0
	s_mov_b32 m0, s35
	ds_read_b128 v[138:141], v12
	ds_read_b128 v[142:145], v12 offset:1024
	ds_read_b128 v[170:173], v12 offset:2048
	ds_read_b128 v[174:177], v12 offset:3072
	ds_read_b128 v[178:181], v12 offset:4096
	ds_read_b128 v[182:185], v12 offset:5120
	ds_read_b128 v[186:189], v12 offset:6144
	ds_read_b128 v[204:207], v12 offset:7168
	global_load_lds_dwordx4 v0, s[20:21]
	s_mov_b32 m0, s36
	s_nop 0
	global_load_lds_dwordx4 v2, s[20:21]
	s_waitcnt lgkmcnt(8)
	s_barrier
	s_waitcnt lgkmcnt(0)
	s_setprio 1
	s_waitcnt lgkmcnt(0)
	v_mfma_f32_16x16x32_bf16 v[62:65], v[122:125], v[138:141], v[62:65]
	v_mfma_f32_16x16x32_bf16 v[66:69], v[130:133], v[138:141], v[66:69]
	v_mfma_f32_16x16x32_bf16 v[74:77], v[130:133], v[170:173], v[74:77]
	v_mfma_f32_16x16x32_bf16 v[86:89], v[122:125], v[186:189], v[86:89]
	v_mfma_f32_16x16x32_bf16 v[90:93], v[130:133], v[186:189], v[90:93]
	v_mfma_f32_16x16x32_bf16 v[62:65], v[126:129], v[142:145], v[62:65]
	v_mfma_f32_16x16x32_bf16 v[66:69], v[134:137], v[142:145], v[66:69]
	v_mfma_f32_16x16x32_bf16 v[70:73], v[122:125], v[170:173], v[70:73]
	v_mfma_f32_16x16x32_bf16 v[74:77], v[134:137], v[174:177], v[74:77]
	v_mfma_f32_16x16x32_bf16 v[78:81], v[122:125], v[178:181], v[78:81]
	v_mfma_f32_16x16x32_bf16 v[82:85], v[130:133], v[178:181], v[82:85]
	v_mfma_f32_16x16x32_bf16 v[86:89], v[126:129], v[204:207], v[86:89]
	v_mfma_f32_16x16x32_bf16 v[90:93], v[134:137], v[204:207], v[90:93]
	v_mfma_f32_16x16x32_bf16 v[70:73], v[126:129], v[174:177], v[70:73]
	v_mfma_f32_16x16x32_bf16 v[78:81], v[126:129], v[182:185], v[78:81]
	v_mfma_f32_16x16x32_bf16 v[82:85], v[134:137], v[182:185], v[82:85]
	s_setprio 0
	s_barrier
	s_mov_b64 s[20:21], 0x200
	s_mov_b32 m0, s37
	v_lshl_add_u64 v[192:193], v[4:5], 0, s[20:21]
	ds_read_b128 v[208:211], v15
	ds_read_b128 v[212:215], v15 offset:1024
	ds_read_b128 v[216:219], v15 offset:2048
	ds_read_b128 v[220:223], v15 offset:3072
	global_load_lds_dwordx4 v[192:193], off
	v_lshl_add_u64 v[192:193], v[6:7], 0, s[20:21]
	s_mov_b32 m0, s38
	s_nop 0
	global_load_lds_dwordx4 v[192:193], off
	s_barrier
	s_waitcnt lgkmcnt(0)
	s_setprio 1
	s_waitcnt lgkmcnt(0)
	v_mfma_f32_16x16x32_bf16 v[110:113], v[208:211], v[138:141], v[110:113]
	v_mfma_f32_16x16x32_bf16 v[34:37], v[216:219], v[138:141], v[34:37]
	v_mfma_f32_16x16x32_bf16 v[114:117], v[208:211], v[170:173], v[114:117]
	v_mfma_f32_16x16x32_bf16 v[38:41], v[216:219], v[170:173], v[38:41]
	v_mfma_f32_16x16x32_bf16 v[42:45], v[208:211], v[178:181], v[42:45]
	v_mfma_f32_16x16x32_bf16 v[46:49], v[216:219], v[178:181], v[46:49]
	v_mfma_f32_16x16x32_bf16 v[50:53], v[208:211], v[186:189], v[50:53]
	v_mfma_f32_16x16x32_bf16 v[54:57], v[216:219], v[186:189], v[54:57]
	v_mfma_f32_16x16x32_bf16 v[110:113], v[212:215], v[142:145], v[110:113]
	v_mfma_f32_16x16x32_bf16 v[34:37], v[220:223], v[142:145], v[34:37]
	v_mfma_f32_16x16x32_bf16 v[114:117], v[212:215], v[174:177], v[114:117]
	v_mfma_f32_16x16x32_bf16 v[38:41], v[220:223], v[174:177], v[38:41]
	v_mfma_f32_16x16x32_bf16 v[42:45], v[212:215], v[182:185], v[42:45]
	v_mfma_f32_16x16x32_bf16 v[46:49], v[220:223], v[182:185], v[46:49]
	v_mfma_f32_16x16x32_bf16 v[50:53], v[212:215], v[204:207], v[50:53]
	v_mfma_f32_16x16x32_bf16 v[54:57], v[220:223], v[204:207], v[54:57]
	s_setprio 0
	s_mov_b32 m0, s63
	v_lshl_add_u64 v[192:193], v[8:9], 0, s[20:21]
	s_barrier
	ds_read_b128 v[138:141], v12 offset:16384
	ds_read_b128 v[142:145], v12 offset:17408
	ds_read_b128 v[170:173], v12 offset:18432
	ds_read_b128 v[174:177], v12 offset:19456
	ds_read_b128 v[178:181], v12 offset:20480
	ds_read_b128 v[182:185], v12 offset:21504
	ds_read_b128 v[186:189], v12 offset:22528
	ds_read_b128 v[204:207], v12 offset:23552
	global_load_lds_dwordx4 v[192:193], off
	v_lshl_add_u64 v[192:193], v[10:11], 0, s[20:21]
	s_mov_b32 m0, s24
	s_nop 0
	global_load_lds_dwordx4 v[192:193], off
	s_barrier
	s_waitcnt lgkmcnt(0)
	s_setprio 1
	s_waitcnt lgkmcnt(0)
	v_mfma_f32_16x16x32_bf16 v[146:149], v[122:125], v[138:141], v[146:149]
	v_mfma_f32_16x16x32_bf16 v[150:153], v[130:133], v[138:141], v[150:153]
	v_mfma_f32_16x16x32_bf16 v[154:157], v[122:125], v[170:173], v[154:157]
	v_mfma_f32_16x16x32_bf16 v[158:161], v[130:133], v[170:173], v[158:161]
	v_mfma_f32_16x16x32_bf16 v[162:165], v[122:125], v[178:181], v[162:165]
	v_mfma_f32_16x16x32_bf16 v[166:169], v[130:133], v[178:181], v[166:169]
	v_mfma_f32_16x16x32_bf16 v[22:25], v[130:133], v[186:189], v[22:25]
	v_mfma_f32_16x16x32_bf16 v[146:149], v[126:129], v[142:145], v[146:149]
	v_mfma_f32_16x16x32_bf16 v[150:153], v[134:137], v[142:145], v[150:153]
	v_mfma_f32_16x16x32_bf16 v[154:157], v[126:129], v[174:177], v[154:157]
	v_mfma_f32_16x16x32_bf16 v[158:161], v[134:137], v[174:177], v[158:161]
	v_mfma_f32_16x16x32_bf16 v[162:165], v[126:129], v[182:185], v[162:165]
	v_mfma_f32_16x16x32_bf16 v[166:169], v[134:137], v[182:185], v[166:169]
	v_mfma_f32_16x16x32_bf16 v[18:21], v[122:125], v[186:189], v[18:21]
	v_mfma_f32_16x16x32_bf16 v[22:25], v[134:137], v[204:207], v[22:25]
	v_mfma_f32_16x16x32_bf16 v[18:21], v[126:129], v[204:207], v[18:21]
	s_setprio 0
	s_barrier
	s_add_u32 s20, s18, 0x18200
	s_addc_u32 s21, s19, 0
	s_mov_b32 m0, s39
	s_nop 0
	global_load_lds_dwordx4 v0, s[20:21]
	s_mov_b32 m0, s43
	s_nop 0
	global_load_lds_dwordx4 v2, s[20:21]
	s_waitcnt vmcnt(6)
	s_barrier
	s_setprio 1
	v_mfma_f32_16x16x32_bf16 v[26:29], v[208:211], v[138:141], v[26:29]
	v_mfma_f32_16x16x32_bf16 v[30:33], v[216:219], v[138:141], v[30:33]
	v_mfma_f32_16x16x32_bf16 v[58:61], v[208:211], v[170:173], v[58:61]
	v_mfma_f32_16x16x32_bf16 v[102:105], v[216:219], v[170:173], v[102:105]
	v_mfma_f32_16x16x32_bf16 v[106:109], v[208:211], v[178:181], v[106:109]
	v_mfma_f32_16x16x32_bf16 v[118:121], v[216:219], v[178:181], v[118:121]
	v_mfma_f32_16x16x32_bf16 v[94:97], v[208:211], v[186:189], v[94:97]
	v_mfma_f32_16x16x32_bf16 v[98:101], v[216:219], v[186:189], v[98:101]
	v_mfma_f32_16x16x32_bf16 v[26:29], v[212:215], v[142:145], v[26:29]
	v_mfma_f32_16x16x32_bf16 v[30:33], v[220:223], v[142:145], v[30:33]
	v_mfma_f32_16x16x32_bf16 v[58:61], v[212:215], v[174:177], v[58:61]
	v_mfma_f32_16x16x32_bf16 v[102:105], v[220:223], v[174:177], v[102:105]
	v_mfma_f32_16x16x32_bf16 v[106:109], v[212:215], v[182:185], v[106:109]
	v_mfma_f32_16x16x32_bf16 v[118:121], v[220:223], v[182:185], v[118:121]
	v_mfma_f32_16x16x32_bf16 v[94:97], v[212:215], v[204:207], v[94:97]
	v_mfma_f32_16x16x32_bf16 v[98:101], v[220:223], v[204:207], v[98:101]
	s_setprio 0
	s_barrier
	ds_read_b128 v[122:125], v14
	ds_read_b128 v[126:129], v14 offset:1024
	ds_read_b128 v[130:133], v14 offset:2048
	ds_read_b128 v[134:137], v14 offset:3072
	s_add_u32 s20, s4, 0x18200
	s_addc_u32 s21, s5, 0
	s_mov_b32 m0, s25
	ds_read_b128 v[138:141], v12 offset:32768
	ds_read_b128 v[142:145], v12 offset:33792
	ds_read_b128 v[170:173], v12 offset:34816
	ds_read_b128 v[174:177], v12 offset:35840
	ds_read_b128 v[178:181], v12 offset:36864
	ds_read_b128 v[182:185], v12 offset:37888
	ds_read_b128 v[186:189], v12 offset:38912
	ds_read_b128 v[204:207], v12 offset:39936
	global_load_lds_dwordx4 v0, s[20:21]
	s_mov_b32 m0, s26
	s_nop 0
	global_load_lds_dwordx4 v2, s[20:21]
	s_waitcnt lgkmcnt(8)
	s_barrier
	s_waitcnt lgkmcnt(0)
	s_setprio 1
	s_waitcnt lgkmcnt(0)
	v_mfma_f32_16x16x32_bf16 v[62:65], v[122:125], v[138:141], v[62:65]
	v_mfma_f32_16x16x32_bf16 v[66:69], v[130:133], v[138:141], v[66:69]
	v_mfma_f32_16x16x32_bf16 v[74:77], v[130:133], v[170:173], v[74:77]
	v_mfma_f32_16x16x32_bf16 v[86:89], v[122:125], v[186:189], v[86:89]
	v_mfma_f32_16x16x32_bf16 v[90:93], v[130:133], v[186:189], v[90:93]
	v_mfma_f32_16x16x32_bf16 v[62:65], v[126:129], v[142:145], v[62:65]
	v_mfma_f32_16x16x32_bf16 v[66:69], v[134:137], v[142:145], v[66:69]
	v_mfma_f32_16x16x32_bf16 v[70:73], v[122:125], v[170:173], v[70:73]
	v_mfma_f32_16x16x32_bf16 v[74:77], v[134:137], v[174:177], v[74:77]
	v_mfma_f32_16x16x32_bf16 v[78:81], v[122:125], v[178:181], v[78:81]
	v_mfma_f32_16x16x32_bf16 v[82:85], v[130:133], v[178:181], v[82:85]
	v_mfma_f32_16x16x32_bf16 v[86:89], v[126:129], v[204:207], v[86:89]
	v_mfma_f32_16x16x32_bf16 v[90:93], v[134:137], v[204:207], v[90:93]
	v_mfma_f32_16x16x32_bf16 v[70:73], v[126:129], v[174:177], v[70:73]
	v_mfma_f32_16x16x32_bf16 v[78:81], v[126:129], v[182:185], v[78:81]
	v_mfma_f32_16x16x32_bf16 v[82:85], v[134:137], v[182:185], v[82:85]
	s_setprio 0
	s_barrier
	s_mov_b64 s[20:21], 0x280
	s_mov_b32 m0, s46
	v_lshl_add_u64 v[4:5], v[4:5], 0, s[20:21]
	ds_read_b128 v[208:211], v13
	ds_read_b128 v[212:215], v13 offset:1024
	ds_read_b128 v[216:219], v13 offset:2048
	ds_read_b128 v[220:223], v13 offset:3072
	global_load_lds_dwordx4 v[4:5], off
	v_lshl_add_u64 v[4:5], v[6:7], 0, s[20:21]
	s_mov_b32 m0, s47
	s_nop 0
	global_load_lds_dwordx4 v[4:5], off
	s_barrier
	s_waitcnt lgkmcnt(0)
	s_setprio 1
	s_waitcnt lgkmcnt(0)
	v_mfma_f32_16x16x32_bf16 v[4:7], v[208:211], v[138:141], v[110:113]
	v_mfma_f32_16x16x32_bf16 v[34:37], v[216:219], v[138:141], v[34:37]
	v_mfma_f32_16x16x32_bf16 v[110:113], v[208:211], v[170:173], v[114:117]
	v_mfma_f32_16x16x32_bf16 v[38:41], v[216:219], v[170:173], v[38:41]
	v_mfma_f32_16x16x32_bf16 v[42:45], v[208:211], v[178:181], v[42:45]
	v_mfma_f32_16x16x32_bf16 v[46:49], v[216:219], v[178:181], v[46:49]
	v_mfma_f32_16x16x32_bf16 v[50:53], v[208:211], v[186:189], v[50:53]
	v_mfma_f32_16x16x32_bf16 v[54:57], v[216:219], v[186:189], v[54:57]
	v_mfma_f32_16x16x32_bf16 v[34:37], v[220:223], v[142:145], v[34:37]
	v_mfma_f32_16x16x32_bf16 v[110:113], v[212:215], v[174:177], v[110:113]
	v_mfma_f32_16x16x32_bf16 v[38:41], v[220:223], v[174:177], v[38:41]
	v_mfma_f32_16x16x32_bf16 v[42:45], v[212:215], v[182:185], v[42:45]
	v_mfma_f32_16x16x32_bf16 v[46:49], v[220:223], v[182:185], v[46:49]
	v_mfma_f32_16x16x32_bf16 v[50:53], v[212:215], v[204:207], v[50:53]
	v_mfma_f32_16x16x32_bf16 v[54:57], v[220:223], v[204:207], v[54:57]
	v_mfma_f32_16x16x32_bf16 v[4:7], v[212:215], v[142:145], v[4:7]
	s_setprio 0
	s_mov_b32 m0, s27
	v_lshl_add_u64 v[8:9], v[8:9], 0, s[20:21]
	s_barrier
	ds_read_b128 v[114:117], v12 offset:49152
	ds_read_b128 v[138:141], v12 offset:50176
	ds_read_b128 v[142:145], v12 offset:51200
	ds_read_b128 v[170:173], v12 offset:52224
	ds_read_b128 v[174:177], v12 offset:53248
	ds_read_b128 v[178:181], v12 offset:54272
	ds_read_b128 v[182:185], v12 offset:55296
	ds_read_b128 v[186:189], v12 offset:56320
	global_load_lds_dwordx4 v[8:9], off
	v_lshl_add_u64 v[8:9], v[10:11], 0, s[20:21]
	s_mov_b32 m0, s28
	s_nop 0
	global_load_lds_dwordx4 v[8:9], off
	s_barrier
	s_waitcnt lgkmcnt(0)
	s_setprio 1
	s_waitcnt lgkmcnt(0)
	v_mfma_f32_16x16x32_bf16 v[8:11], v[122:125], v[114:117], v[146:149]
	v_mfma_f32_16x16x32_bf16 v[146:149], v[130:133], v[114:117], v[150:153]
	v_mfma_f32_16x16x32_bf16 v[150:153], v[122:125], v[142:145], v[154:157]
	v_mfma_f32_16x16x32_bf16 v[154:157], v[130:133], v[142:145], v[158:161]
	v_mfma_f32_16x16x32_bf16 v[158:161], v[122:125], v[174:177], v[162:165]
	v_mfma_f32_16x16x32_bf16 v[162:165], v[130:133], v[174:177], v[166:169]
	v_mfma_f32_16x16x32_bf16 v[22:25], v[130:133], v[182:185], v[22:25]
	v_mfma_f32_16x16x32_bf16 v[8:11], v[126:129], v[138:141], v[8:11]
	v_mfma_f32_16x16x32_bf16 v[146:149], v[134:137], v[138:141], v[146:149]
	v_mfma_f32_16x16x32_bf16 v[150:153], v[126:129], v[170:173], v[150:153]
	v_mfma_f32_16x16x32_bf16 v[154:157], v[134:137], v[170:173], v[154:157]
	v_mfma_f32_16x16x32_bf16 v[158:161], v[126:129], v[178:181], v[158:161]
	v_mfma_f32_16x16x32_bf16 v[162:165], v[134:137], v[178:181], v[162:165]
	v_mfma_f32_16x16x32_bf16 v[18:21], v[122:125], v[182:185], v[18:21]
	v_mfma_f32_16x16x32_bf16 v[22:25], v[134:137], v[186:189], v[22:25]
	v_mfma_f32_16x16x32_bf16 v[18:21], v[126:129], v[186:189], v[18:21]
	s_setprio 0
	s_barrier
	s_add_u32 s18, s18, 0x18280
	s_addc_u32 s19, s19, 0
	s_mov_b32 m0, s52
	s_nop 0
	global_load_lds_dwordx4 v0, s[18:19]
	s_mov_b32 m0, s60
	s_nop 0
	global_load_lds_dwordx4 v2, s[18:19]
	s_waitcnt vmcnt(6)
	s_barrier
	s_setprio 1
	v_mfma_f32_16x16x32_bf16 v[26:29], v[208:211], v[114:117], v[26:29]
	v_mfma_f32_16x16x32_bf16 v[30:33], v[216:219], v[114:117], v[30:33]
	v_mfma_f32_16x16x32_bf16 v[58:61], v[208:211], v[142:145], v[58:61]
	v_mfma_f32_16x16x32_bf16 v[102:105], v[216:219], v[142:145], v[102:105]
	v_mfma_f32_16x16x32_bf16 v[106:109], v[208:211], v[174:177], v[106:109]
	v_mfma_f32_16x16x32_bf16 v[114:117], v[216:219], v[174:177], v[118:121]
	v_mfma_f32_16x16x32_bf16 v[94:97], v[208:211], v[182:185], v[94:97]
	v_mfma_f32_16x16x32_bf16 v[98:101], v[216:219], v[182:185], v[98:101]
	v_mfma_f32_16x16x32_bf16 v[26:29], v[212:215], v[138:141], v[26:29]
	v_mfma_f32_16x16x32_bf16 v[30:33], v[220:223], v[138:141], v[30:33]
	v_mfma_f32_16x16x32_bf16 v[58:61], v[212:215], v[170:173], v[58:61]
	v_mfma_f32_16x16x32_bf16 v[102:105], v[220:223], v[170:173], v[102:105]
	v_mfma_f32_16x16x32_bf16 v[106:109], v[212:215], v[178:181], v[106:109]
	v_mfma_f32_16x16x32_bf16 v[114:117], v[220:223], v[178:181], v[114:117]
	v_mfma_f32_16x16x32_bf16 v[94:97], v[212:215], v[186:189], v[94:97]
	v_mfma_f32_16x16x32_bf16 v[98:101], v[220:223], v[186:189], v[98:101]
	s_setprio 0
	s_barrier
	ds_read_b128 v[118:121], v16
	ds_read_b128 v[122:125], v16 offset:1024
	ds_read_b128 v[126:129], v16 offset:2048
	ds_read_b128 v[130:133], v16 offset:3072
	s_add_u32 s4, s4, 0x18280
	s_addc_u32 s5, s5, 0
	s_mov_b32 m0, s35
	ds_read_b128 v[134:137], v12
	ds_read_b128 v[138:141], v12 offset:1024
	ds_read_b128 v[142:145], v12 offset:2048
	ds_read_b128 v[166:169], v12 offset:3072
	ds_read_b128 v[170:173], v12 offset:4096
	ds_read_b128 v[174:177], v12 offset:5120
	ds_read_b128 v[178:181], v12 offset:6144
	ds_read_b128 v[182:185], v12 offset:7168
	global_load_lds_dwordx4 v0, s[4:5]
	s_mov_b32 m0, s36
	s_nop 0
	global_load_lds_dwordx4 v2, s[4:5]
	s_waitcnt lgkmcnt(8)
	s_barrier
	s_waitcnt lgkmcnt(0)
	s_setprio 1
	s_waitcnt lgkmcnt(0)
	v_mfma_f32_16x16x32_bf16 v[62:65], v[118:121], v[134:137], v[62:65]
	v_mfma_f32_16x16x32_bf16 v[66:69], v[126:129], v[134:137], v[66:69]
	v_mfma_f32_16x16x32_bf16 v[74:77], v[126:129], v[142:145], v[74:77]
	v_mfma_f32_16x16x32_bf16 v[86:89], v[118:121], v[178:181], v[86:89]
	v_mfma_f32_16x16x32_bf16 v[90:93], v[126:129], v[178:181], v[90:93]
	v_mfma_f32_16x16x32_bf16 v[62:65], v[122:125], v[138:141], v[62:65]
	v_mfma_f32_16x16x32_bf16 v[66:69], v[130:133], v[138:141], v[66:69]
	v_mfma_f32_16x16x32_bf16 v[70:73], v[118:121], v[142:145], v[70:73]
	v_mfma_f32_16x16x32_bf16 v[74:77], v[130:133], v[166:169], v[74:77]
	v_mfma_f32_16x16x32_bf16 v[78:81], v[118:121], v[170:173], v[78:81]
	v_mfma_f32_16x16x32_bf16 v[82:85], v[126:129], v[170:173], v[82:85]
	v_mfma_f32_16x16x32_bf16 v[86:89], v[122:125], v[182:185], v[86:89]
	v_mfma_f32_16x16x32_bf16 v[90:93], v[130:133], v[182:185], v[90:93]
	v_mfma_f32_16x16x32_bf16 v[70:73], v[122:125], v[166:169], v[70:73]
	v_mfma_f32_16x16x32_bf16 v[78:81], v[122:125], v[174:177], v[78:81]
	v_mfma_f32_16x16x32_bf16 v[82:85], v[130:133], v[174:177], v[82:85]
	s_setprio 0
	s_barrier
	s_mov_b32 m0, s37
	ds_read_b128 v[186:189], v15
	ds_read_b128 v[204:207], v15 offset:1024
	ds_read_b128 v[208:211], v15 offset:2048
	ds_read_b128 v[212:215], v15 offset:3072
	global_load_lds_dwordx4 v0, s[12:13]
	s_mov_b32 m0, s38
	v_lshl_add_u64 v[196:197], s[12:13], 0, v[0:1]
	global_load_lds_dwordx4 v2, s[12:13]
	s_barrier
	s_waitcnt lgkmcnt(0)
	v_lshl_add_u64 v[198:199], s[12:13], 0, v[2:3]
	s_setprio 1
	s_waitcnt lgkmcnt(0)
	v_mfma_f32_16x16x32_bf16 v[34:37], v[208:211], v[134:137], v[34:37]
	v_mfma_f32_16x16x32_bf16 v[110:113], v[186:189], v[142:145], v[110:113]
	v_mfma_f32_16x16x32_bf16 v[38:41], v[208:211], v[142:145], v[38:41]
	v_mfma_f32_16x16x32_bf16 v[42:45], v[186:189], v[170:173], v[42:45]
	v_mfma_f32_16x16x32_bf16 v[46:49], v[208:211], v[170:173], v[46:49]
	v_mfma_f32_16x16x32_bf16 v[50:53], v[186:189], v[178:181], v[50:53]
	v_mfma_f32_16x16x32_bf16 v[54:57], v[208:211], v[178:181], v[54:57]
	v_mfma_f32_16x16x32_bf16 v[4:7], v[186:189], v[134:137], v[4:7]
	v_mfma_f32_16x16x32_bf16 v[34:37], v[212:215], v[138:141], v[34:37]
	v_mfma_f32_16x16x32_bf16 v[110:113], v[204:207], v[166:169], v[110:113]
	v_mfma_f32_16x16x32_bf16 v[38:41], v[212:215], v[166:169], v[38:41]
	v_mfma_f32_16x16x32_bf16 v[42:45], v[204:207], v[174:177], v[42:45]
	v_mfma_f32_16x16x32_bf16 v[46:49], v[212:215], v[174:177], v[46:49]
	v_mfma_f32_16x16x32_bf16 v[50:53], v[204:207], v[182:185], v[50:53]
	v_mfma_f32_16x16x32_bf16 v[54:57], v[212:215], v[182:185], v[54:57]
	v_mfma_f32_16x16x32_bf16 v[4:7], v[204:207], v[138:141], v[4:7]
	s_setprio 0
	s_mov_b32 m0, s63
	s_barrier
	ds_read_b128 v[134:137], v12 offset:16384
	ds_read_b128 v[138:141], v12 offset:17408
	ds_read_b128 v[142:145], v12 offset:18432
	ds_read_b128 v[166:169], v12 offset:19456
	ds_read_b128 v[170:173], v12 offset:20480
	ds_read_b128 v[174:177], v12 offset:21504
	ds_read_b128 v[178:181], v12 offset:22528
	ds_read_b128 v[182:185], v12 offset:23552
	global_load_lds_dwordx4 v0, s[10:11]
	s_mov_b32 m0, s24
	v_lshl_add_u64 v[248:249], s[10:11], 0, v[0:1]
	global_load_lds_dwordx4 v2, s[10:11]
	s_barrier
	s_waitcnt lgkmcnt(0)
	v_lshl_add_u64 v[190:191], s[10:11], 0, v[2:3]
	s_setprio 1
	s_waitcnt lgkmcnt(0)
	v_mfma_f32_16x16x32_bf16 v[146:149], v[126:129], v[134:137], v[146:149]
	v_mfma_f32_16x16x32_bf16 v[216:219], v[130:133], v[138:141], v[146:149]
	v_mfma_f32_16x16x32_bf16 v[146:149], v[118:121], v[142:145], v[150:153]
	v_mfma_f32_16x16x32_bf16 v[220:223], v[122:125], v[166:169], v[146:149]
	v_mfma_f32_16x16x32_bf16 v[146:149], v[126:129], v[142:145], v[154:157]
	v_mfma_f32_16x16x32_bf16 v[8:11], v[118:121], v[134:137], v[8:11]
	v_mfma_f32_16x16x32_bf16 v[224:227], v[130:133], v[166:169], v[146:149]
	v_mfma_f32_16x16x32_bf16 v[146:149], v[118:121], v[170:173], v[158:161]
	v_mfma_f32_16x16x32_bf16 v[16:19], v[118:121], v[178:181], v[18:21]
	v_mfma_f32_16x16x32_bf16 v[20:23], v[126:129], v[178:181], v[22:25]
	v_mfma_f32_16x16x32_bf16 v[8:11], v[122:125], v[138:141], v[8:11]
	v_mfma_f32_16x16x32_bf16 v[228:231], v[122:125], v[174:177], v[146:149]
	v_mfma_f32_16x16x32_bf16 v[146:149], v[126:129], v[170:173], v[162:165]
	v_mfma_f32_16x16x32_bf16 v[20:23], v[130:133], v[182:185], v[20:23]
	v_mfma_f32_16x16x32_bf16 v[232:235], v[130:133], v[174:177], v[146:149]
	v_mfma_f32_16x16x32_bf16 v[16:19], v[122:125], v[182:185], v[16:19]
	s_setprio 0
	s_barrier
	s_add_u32 s4, s12, 0x18000
	s_addc_u32 s5, s13, 0
	s_mov_b32 m0, s39
	s_nop 0
	global_load_lds_dwordx4 v0, s[4:5]
	s_mov_b32 m0, s43
	s_nop 0
	global_load_lds_dwordx4 v2, s[4:5]
	s_waitcnt vmcnt(6)
	s_barrier
	s_setprio 1
	v_mfma_f32_16x16x32_bf16 v[24:27], v[186:189], v[134:137], v[26:29]
	v_mfma_f32_16x16x32_bf16 v[28:31], v[208:211], v[134:137], v[30:33]
	v_mfma_f32_16x16x32_bf16 v[236:239], v[212:215], v[138:141], v[28:31]
	v_mfma_f32_16x16x32_bf16 v[28:31], v[186:189], v[142:145], v[58:61]
	v_mfma_f32_16x16x32_bf16 v[58:61], v[204:207], v[166:169], v[28:31]
	v_mfma_f32_16x16x32_bf16 v[28:31], v[208:211], v[142:145], v[102:105]
	v_mfma_f32_16x16x32_bf16 v[240:243], v[212:215], v[166:169], v[28:31]
	v_mfma_f32_16x16x32_bf16 v[28:31], v[186:189], v[170:173], v[106:109]
	v_mfma_f32_16x16x32_bf16 v[244:247], v[204:207], v[174:177], v[28:31]
	v_mfma_f32_16x16x32_bf16 v[28:31], v[208:211], v[170:173], v[114:117]
	v_mfma_f32_16x16x32_bf16 v[174:177], v[212:215], v[174:177], v[28:31]
	v_mfma_f32_16x16x32_bf16 v[28:31], v[186:189], v[178:181], v[94:97]
	v_mfma_f32_16x16x32_bf16 v[186:189], v[204:207], v[182:185], v[28:31]
	v_mfma_f32_16x16x32_bf16 v[28:31], v[208:211], v[178:181], v[98:101]
	v_mfma_f32_16x16x32_bf16 v[24:27], v[204:207], v[138:141], v[24:27]
	v_mfma_f32_16x16x32_bf16 v[178:181], v[212:215], v[182:185], v[28:31]
	s_setprio 0
	s_barrier
	s_nop 3
	ds_read_b128 v[28:31], v14
	ds_read_b128 v[94:97], v14 offset:1024
	ds_read_b128 v[98:101], v14 offset:2048
	ds_read_b128 v[182:185], v14 offset:3072
	s_add_u32 s4, s10, 0x18000
	s_addc_u32 s5, s11, 0
	s_mov_b32 m0, s25
	ds_read_b128 v[102:105], v12 offset:32768
	ds_read_b128 v[106:109], v12 offset:33792
	ds_read_b128 v[114:117], v12 offset:34816
	ds_read_b128 v[126:129], v12 offset:35840
	ds_read_b128 v[204:207], v12 offset:36864
	ds_read_b128 v[208:211], v12 offset:37888
	ds_read_b128 v[212:215], v12 offset:38912
	ds_read_b128 v[192:195], v12 offset:39936
	global_load_lds_dwordx4 v0, s[4:5]
	s_mov_b32 m0, s26
	s_nop 0
	global_load_lds_dwordx4 v2, s[4:5]
	s_waitcnt lgkmcnt(8)
	s_barrier
	s_waitcnt lgkmcnt(0)
	s_setprio 1
	s_waitcnt lgkmcnt(0)
	v_mfma_f32_16x16x32_bf16 v[62:65], v[28:31], v[102:105], v[62:65]
	v_mfma_f32_16x16x32_bf16 v[170:173], v[94:97], v[106:109], v[62:65]
	v_mfma_f32_16x16x32_bf16 v[62:65], v[98:101], v[102:105], v[66:69]
	v_mfma_f32_16x16x32_bf16 v[166:169], v[182:185], v[106:109], v[62:65]
	v_mfma_f32_16x16x32_bf16 v[62:65], v[28:31], v[114:117], v[70:73]
	v_mfma_f32_16x16x32_bf16 v[154:157], v[94:97], v[126:129], v[62:65]
	v_mfma_f32_16x16x32_bf16 v[62:65], v[98:101], v[114:117], v[74:77]
	v_mfma_f32_16x16x32_bf16 v[150:153], v[182:185], v[126:129], v[62:65]
	v_mfma_f32_16x16x32_bf16 v[62:65], v[28:31], v[204:207], v[78:81]
	v_mfma_f32_16x16x32_bf16 v[138:141], v[94:97], v[208:211], v[62:65]
	v_mfma_f32_16x16x32_bf16 v[62:65], v[98:101], v[204:207], v[82:85]
	v_mfma_f32_16x16x32_bf16 v[134:137], v[182:185], v[208:211], v[62:65]
	v_mfma_f32_16x16x32_bf16 v[62:65], v[28:31], v[212:215], v[86:89]
	v_mfma_f32_16x16x32_bf16 v[122:125], v[94:97], v[192:195], v[62:65]
	v_mfma_f32_16x16x32_bf16 v[62:65], v[98:101], v[212:215], v[90:93]
	v_mfma_f32_16x16x32_bf16 v[118:121], v[182:185], v[192:195], v[62:65]
	s_setprio 0
	s_barrier
	s_mov_b32 m0, s46
	v_lshl_add_u64 v[14:15], v[196:197], 0, s[70:71]
	ds_read_b128 v[70:73], v13
	ds_read_b128 v[74:77], v13 offset:1024
	ds_read_b128 v[78:81], v13 offset:2048
	ds_read_b128 v[82:85], v13 offset:3072
	global_load_lds_dwordx4 v[14:15], off
	v_lshl_add_u64 v[14:15], v[198:199], 0, s[70:71]
	s_mov_b32 m0, s47
	s_nop 0
	global_load_lds_dwordx4 v[14:15], off
	s_barrier
	s_waitcnt lgkmcnt(0)
	s_setprio 1
	s_waitcnt lgkmcnt(0)
	v_mfma_f32_16x16x32_bf16 v[4:7], v[70:73], v[102:105], v[4:7]
	v_mfma_f32_16x16x32_bf16 v[162:165], v[74:77], v[106:109], v[4:7]
	v_mfma_f32_16x16x32_bf16 v[4:7], v[78:81], v[102:105], v[34:37]
	v_mfma_f32_16x16x32_bf16 v[158:161], v[82:85], v[106:109], v[4:7]
	v_mfma_f32_16x16x32_bf16 v[4:7], v[70:73], v[114:117], v[110:113]
	v_mfma_f32_16x16x32_bf16 v[146:149], v[74:77], v[126:129], v[4:7]
	v_mfma_f32_16x16x32_bf16 v[4:7], v[78:81], v[114:117], v[38:41]
	v_mfma_f32_16x16x32_bf16 v[142:145], v[82:85], v[126:129], v[4:7]
	v_mfma_f32_16x16x32_bf16 v[4:7], v[70:73], v[204:207], v[42:45]
	v_mfma_f32_16x16x32_bf16 v[130:133], v[74:77], v[208:211], v[4:7]
	v_mfma_f32_16x16x32_bf16 v[4:7], v[78:81], v[204:207], v[46:49]
	v_mfma_f32_16x16x32_bf16 v[126:129], v[82:85], v[208:211], v[4:7]
	v_mfma_f32_16x16x32_bf16 v[4:7], v[70:73], v[212:215], v[50:53]
	v_mfma_f32_16x16x32_bf16 v[114:117], v[74:77], v[192:195], v[4:7]
	v_mfma_f32_16x16x32_bf16 v[4:7], v[78:81], v[212:215], v[54:57]
	v_mfma_f32_16x16x32_bf16 v[110:113], v[82:85], v[192:195], v[4:7]
	s_setprio 0
	s_mov_b32 m0, s27
	v_lshl_add_u64 v[32:33], v[248:249], 0, s[70:71]
	s_barrier
	s_nop 2
	ds_read_b128 v[4:7], v12 offset:49152
	ds_read_b128 v[38:41], v12 offset:50176
	ds_read_b128 v[42:45], v12 offset:51200
	ds_read_b128 v[46:49], v12 offset:52224
	ds_read_b128 v[50:53], v12 offset:53248
	ds_read_b128 v[54:57], v12 offset:54272
	ds_read_b128 v[210:213], v12 offset:55296
	ds_read_b128 v[12:15], v12 offset:56320
	global_load_lds_dwordx4 v[32:33], off
	v_lshl_add_u64 v[32:33], v[190:191], 0, s[70:71]
	s_mov_b32 m0, s28
	s_nop 0
	global_load_lds_dwordx4 v[32:33], off
	s_barrier
	s_waitcnt lgkmcnt(0)
	s_setprio 1
	s_waitcnt lgkmcnt(0)
	v_mfma_f32_16x16x32_bf16 v[8:11], v[28:31], v[4:7], v[8:11]
	v_mfma_f32_16x16x32_bf16 v[106:109], v[94:97], v[38:41], v[8:11]
	v_mfma_f32_16x16x32_bf16 v[8:11], v[98:101], v[4:7], v[216:219]
	v_mfma_f32_16x16x32_bf16 v[102:105], v[182:185], v[38:41], v[8:11]
	v_mfma_f32_16x16x32_bf16 v[8:11], v[28:31], v[42:45], v[220:223]
	v_mfma_f32_16x16x32_bf16 v[90:93], v[94:97], v[46:49], v[8:11]
	v_mfma_f32_16x16x32_bf16 v[8:11], v[98:101], v[42:45], v[224:227]
	v_mfma_f32_16x16x32_bf16 v[86:89], v[182:185], v[46:49], v[8:11]
	v_mfma_f32_16x16x32_bf16 v[8:11], v[28:31], v[50:53], v[228:231]
	v_mfma_f32_16x16x32_bf16 v[66:69], v[94:97], v[54:57], v[8:11]
	v_mfma_f32_16x16x32_bf16 v[8:11], v[98:101], v[50:53], v[232:235]
	v_mfma_f32_16x16x32_bf16 v[62:65], v[182:185], v[54:57], v[8:11]
	v_mfma_f32_16x16x32_bf16 v[8:11], v[28:31], v[210:213], v[16:19]
	v_mfma_f32_16x16x32_bf16 v[34:37], v[94:97], v[12:15], v[8:11]
	v_mfma_f32_16x16x32_bf16 v[8:11], v[98:101], v[210:213], v[20:23]
	v_mfma_f32_16x16x32_bf16 v[30:33], v[182:185], v[12:15], v[8:11]
	s_setprio 0
	s_barrier
	s_add_u32 s4, s12, 0x18080
	s_addc_u32 s5, s13, 0
	s_mov_b32 m0, s52
	s_nop 0
	global_load_lds_dwordx4 v0, s[4:5]
	s_mov_b32 m0, s60
	s_nop 0
	global_load_lds_dwordx4 v2, s[4:5]
	s_waitcnt vmcnt(6)
	s_barrier
	s_setprio 1
	v_mfma_f32_16x16x32_bf16 v[8:11], v[70:73], v[4:7], v[24:27]
	v_mfma_f32_16x16x32_bf16 v[2:5], v[78:81], v[4:7], v[236:239]
	v_mfma_f32_16x16x32_bf16 v[94:97], v[82:85], v[38:41], v[2:5]
	v_mfma_f32_16x16x32_bf16 v[2:5], v[70:73], v[42:45], v[58:61]
	v_mfma_f32_16x16x32_bf16 v[206:209], v[74:77], v[46:49], v[2:5]
	v_mfma_f32_16x16x32_bf16 v[2:5], v[78:81], v[42:45], v[240:243]
	v_mfma_f32_16x16x32_bf16 v[192:195], v[82:85], v[46:49], v[2:5]
	v_mfma_f32_16x16x32_bf16 v[2:5], v[70:73], v[50:53], v[244:247]
	v_mfma_f32_16x16x32_bf16 v[58:61], v[74:77], v[54:57], v[2:5]
	v_mfma_f32_16x16x32_bf16 v[2:5], v[78:81], v[50:53], v[174:177]
	v_mfma_f32_16x16x32_bf16 v[54:57], v[82:85], v[54:57], v[2:5]
	v_mfma_f32_16x16x32_bf16 v[2:5], v[70:73], v[210:213], v[186:189]
	v_mfma_f32_16x16x32_bf16 v[26:29], v[74:77], v[12:15], v[2:5]
	v_mfma_f32_16x16x32_bf16 v[2:5], v[78:81], v[210:213], v[178:181]
	v_mfma_f32_16x16x32_bf16 v[98:101], v[74:77], v[38:41], v[8:11]
	v_mfma_f32_16x16x32_bf16 v[22:25], v[82:85], v[12:15], v[2:5]
	s_setprio 0
	s_mov_b32 s21, s49
	s_mov_b32 s20, s48
	s_barrier
	s_lshl_b32 s94, s17, 8
	v_readlane_b32 s95, v255, 15
	s_nop 0
	s_lshl_b32 s95, s95, 5
	s_add_i32 s95, s95, 0x20100
	v_mov_b32_e32 v200, s95
	v_mbcnt_lo_u32_b32 v187, -1, 0
	v_mbcnt_hi_u32_b32 v187, -1, v187
	s_add_u32 s18, s20, 0x14fa8000
	v_bfe_u32 v0, v187, 4, 2
	s_addc_u32 s19, s21, 0
	v_readlane_b32 s4, v255, 15
	s_add_u32 s22, s20, 0x14fe8800
	s_addc_u32 s23, s21, 0
	v_lshl_or_b32 v189, v0, 3, s4
	v_readlane_b32 s4, v255, 51
	s_mov_b32 s40, s51
	s_mov_b32 s41, s50
	v_lshl_or_b32 v188, v0, 2, s4
	s_lshl_b32 s4, s17, 8
	s_add_i32 s4, s4, s42
	v_and_or_b32 v174, v187, 15, s4
	v_ashrrev_i32_e32 v175, 31, v174
	v_lshl_add_u64 v[2:3], v[174:175], 2, s[20:21]
	s_mov_b64 s[4:5], 0x15049800
	v_lshl_add_u64 v[4:5], v[2:3], 0, s[4:5]
	s_mov_b32 s4, 0x15049000
	v_add_co_u32_e32 v2, vcc, s4, v2
	v_lshlrev_b32_e32 v0, 2, v189
	s_nop 0
	v_addc_co_u32_e32 v3, vcc, 0, v3, vcc
	global_load_dword v204, v[2:3], off offset:2048
	global_load_dword v186, v[4:5], off offset:64
	global_load_dword v184, v[4:5], off offset:128
	global_load_dword v183, v[4:5], off offset:192
	global_load_dword v182, v[4:5], off offset:512
	global_load_dword v181, v[4:5], off offset:576
	global_load_dword v180, v[4:5], off offset:640
	global_load_dword v175, v[4:5], off offset:704
	global_load_dwordx4 v[46:49], v0, s[8:9] offset:16
	global_load_dwordx4 v[50:53], v0, s[8:9]
	v_lshlrev_b32_e32 v0, 2, v188
	global_load_dwordx4 v[42:45], v0, s[8:9] offset:512
	global_load_dwordx4 v[38:41], v0, s[8:9] offset:640
	v_readlane_b32 s90, v255, 8
	v_readlane_b32 s91, v255, 9
	v_mov_b32_e32 v10, 0
	s_andn2_b64 vcc, exec, s[90:91]
	v_cndmask_b32_e64 v2, 0, 1, s[90:91]
	v_cmp_ne_u32_e64 s[4:5], 1, v2
	v_mov_b32_e32 v11, 0
	v_mov_b32_e32 v12, 0
	v_mov_b32_e32 v13, 0
	s_cbranch_vccnz .LBB0_563
	v_mul_hi_i32 v2, v174, s59
	v_lshrrev_b32_e32 v3, 31, v2
	v_ashrrev_i32_e32 v2, 7, v2
	v_add_u32_e32 v2, v2, v3
	v_mul_lo_u32 v2, v2, s33
	v_sub_u32_e32 v2, v174, v2
	v_lshlrev_b32_e32 v2, 5, v2
	v_ashrrev_i32_e32 v3, 31, v2
	v_lshlrev_b64 v[2:3], 2, v[2:3]
	v_lshl_add_u64 v[4:5], s[18:19], 0, v[2:3]
	v_lshl_add_u64 v[4:5], v[4:5], 0, v[0:1]
	v_lshl_add_u64 v[2:3], s[22:23], 0, v[2:3]
	v_lshl_add_u64 v[2:3], v[2:3], 0, v[0:1]
	global_load_dwordx4 v[10:13], v[4:5], off
	global_load_dwordx4 v[74:77], v[2:3], off

.LBB0_568:
	v_and_b32_e32 v15, 63, v187
	v_lshlrev_b32_e32 v16, 2, v15
	v_xor_b32_e32 v160, 64, v16
	v_xor_b32_e32 v159, 0x80, v16
	ds_bpermute_b32 v16, v160, v14
	s_ashr_i32 s17, s16, 31
	v_cmp_gt_u32_e32 vcc, 16, v15
	s_lshl_b64 s[16:17], s[16:17], 2
	s_add_u32 s16, s20, s16
	s_waitcnt lgkmcnt(0)
	v_add_f32_e32 v14, v14, v16
	ds_bpermute_b32 v15, v159, v14
	s_addc_u32 s17, s21, s17
	s_add_u32 s16, s16, 0x1507a400
	s_addc_u32 s17, s17, 0
	s_and_b64 s[20:21], s[2:3], vcc
	s_and_saveexec_b64 s[22:23], s[20:21]
	s_cbranch_execz .LBB0_570
	v_and_b32_e32 v16, 0xff, v174
	v_lshl_add_u32 v16, v16, 2, v200
	s_waitcnt lgkmcnt(0)
	v_add_f32_e32 v14, v14, v15
	ds_write_b32 v16, v14

.LBB0_574:
	ds_bpermute_b32 v78, v160, v150
	s_waitcnt lgkmcnt(0)
	v_add_f32_e32 v142, v150, v78
	ds_bpermute_b32 v143, v159, v142
	s_and_saveexec_b64 s[22:23], s[20:21]
	s_cbranch_execz .LBB0_576
	v_and_b32_e32 v78, 0xff, v185
	v_lshl_add_u32 v78, v78, 2, v200
	s_waitcnt lgkmcnt(0)
	v_add_f32_e32 v80, v142, v143
	ds_write_b32 v78, v80

.LBB0_580:
	ds_bpermute_b32 v78, v160, v134
	s_waitcnt lgkmcnt(0)
	v_add_f32_e32 v126, v134, v78
	ds_bpermute_b32 v127, v159, v126
	s_and_saveexec_b64 s[22:23], s[20:21]
	s_cbranch_execz .LBB0_582
	v_and_b32_e32 v78, 0xff, v161
	v_lshl_add_u32 v78, v78, 2, v200
	s_waitcnt lgkmcnt(0)
	v_add_f32_e32 v80, v126, v127
	ds_write_b32 v78, v80

.LBB0_586:
	ds_bpermute_b32 v78, v160, v118
	s_waitcnt lgkmcnt(0)
	v_add_f32_e32 v110, v118, v78
	ds_bpermute_b32 v111, v159, v110
	s_and_saveexec_b64 s[22:23], s[20:21]
	s_cbranch_execz .LBB0_588
	v_and_b32_e32 v78, 0xff, v143
	v_lshl_add_u32 v78, v78, 2, v200
	s_waitcnt lgkmcnt(0)
	v_add_f32_e32 v80, v110, v111
	ds_write_b32 v78, v80

.LBB0_592:
	ds_bpermute_b32 v15, v160, v14
	s_waitcnt lgkmcnt(0)
	v_add_f32_e32 v14, v14, v15
	ds_bpermute_b32 v15, v159, v14
	s_and_saveexec_b64 s[22:23], s[20:21]
	s_cbranch_execz .LBB0_594
	v_and_b32_e32 v16, 0xff, v127
	v_lshl_add_u32 v16, v16, 2, v200
	s_waitcnt lgkmcnt(0)
	v_add_f32_e32 v14, v14, v15
	ds_write_b32 v16, v14

.LBB0_598:
	ds_bpermute_b32 v15, v160, v14
	s_waitcnt lgkmcnt(0)
	v_add_f32_e32 v14, v14, v15
	ds_bpermute_b32 v15, v159, v14
	s_and_saveexec_b64 s[22:23], s[20:21]
	s_cbranch_execz .LBB0_600
	v_and_b32_e32 v16, 0xff, v17
	v_lshl_add_u32 v16, v16, 2, v200
	s_waitcnt lgkmcnt(0)
	v_add_f32_e32 v14, v14, v15
	ds_write_b32 v16, v14

.LBB0_604:
	ds_bpermute_b32 v2, v160, v10
	s_waitcnt lgkmcnt(0)
	v_add_f32_e32 v2, v10, v2
	ds_bpermute_b32 v3, v159, v2
	s_and_saveexec_b64 s[22:23], s[20:21]
	s_cbranch_execz .LBB0_606
	v_and_b32_e32 v4, 0xff, v13
	v_lshl_add_u32 v4, v4, 2, v200
	s_waitcnt lgkmcnt(0)
	v_add_f32_e32 v2, v2, v3
	ds_write_b32 v4, v2

.LBB0_608:
	ds_bpermute_b32 v0, v160, v2
	s_waitcnt lgkmcnt(0)
	v_add_f32_e32 v0, v2, v0
	ds_bpermute_b32 v2, v159, v0
	s_and_saveexec_b64 s[4:5], s[20:21]
	s_cbranch_execz .LBB0_610
	v_and_b32_e32 v4, 0xff, v5
	v_lshl_add_u32 v4, v4, 2, v200
	s_waitcnt lgkmcnt(0)
	v_add_f32_e32 v0, v0, v2
	ds_write_b32 v4, v0
.LBB0_610:
	s_or_b64 exec, exec, s[4:5]
	s_waitcnt lgkmcnt(0)
	s_barrier
	s_barrier
	s_cmp_lg_u32 s42, 0
	s_cbranch_scc1 .Lqred_skip
	s_and_b64 vcc, exec, s[2:3]
	s_cbranch_vccz .Lqred_skip
	v_readlane_b32 s95, v255, 15
	s_nop 0
	s_lshl_b32 s95, s95, 1
	v_mbcnt_lo_u32_b32 v201, -1, 0
	v_mbcnt_hi_u32_b32 v201, -1, v201
	v_add_u32_e32 v201, s95, v201
	s_mov_b32 s95, 0x20100
	v_lshl_add_u32 v202, v201, 2, s95
	ds_read_b32 v203, v202
	ds_read_b32 v200, v202 offset:1024
	s_waitcnt lgkmcnt(0)
	v_add_f32_e32 v203, v203, v200
	ds_read_b32 v200, v202 offset:2048
	s_waitcnt lgkmcnt(0)
	v_add_f32_e32 v203, v203, v200
	ds_read_b32 v200, v202 offset:3072
	s_waitcnt lgkmcnt(0)
	v_add_f32_e32 v203, v203, v200
	v_add_u32_e32 v201, s94, v201
	v_lshlrev_b32_e32 v201, 5, v201
	global_store_dword v201, v203, s[16:17]
.Lqred_skip:
	s_mov_b64 s[4:5], -1
	s_andn2_b64 vcc, exec, s[14:15]
	v_readfirstlane_b32 s14, v0
	s_cbranch_vccnz .LBB0_558
	v_mbcnt_lo_u32_b32 v3, -1, 0
	v_mbcnt_hi_u32_b32 v3, -1, v3
	v_mov_b32_e32 v8, 1
	s_waitcnt lgkmcnt(0)
	v_lshl_add_u32 v2, v3, 4, s53
	v_ashrrev_i32_e32 v0, 31, v2
	v_lshrrev_b32_e32 v0, 22, v0
	v_add_u32_e32 v0, v2, v0
	v_ashrrev_i32_e32 v0, 10, v0
	v_mul_i32_i24_e32 v4, 0x400, v0
	v_sub_u32_e32 v4, v2, v4
	v_lshrrev_b32_e32 v5, 4, v4
	v_bitop3_b32 v4, v5, v4, 32 bitop3:0x6c
	v_ashrrev_i32_e32 v6, 31, v4
	v_lshrrev_b32_e32 v6, 26, v6
	v_add_u32_e32 v6, v4, v6
	v_lshlrev_b32_e32 v5, 3, v0
	v_lshrrev_b32_e32 v7, 6, v6
	v_and_b32_e32 v6, 0xc0, v6
	v_and_b32_e32 v5, 0xfffff0, v5
	v_lshlrev_b32_e32 v0, 5, v0
	v_sub_u32_e32 v4, v4, v6
	v_add_u32_e32 v5, v7, v5
	v_and_b32_e32 v0, 32, v0
	v_ashrrev_i16_sdwa v4, v8, sext(v4) dst_sel:DWORD dst_unused:UNUSED_PAD src0_sel:DWORD src1_sel:BYTE_0
	s_movk_i32 s4, 0x300
	v_add_u32_sdwa v0, v0, sext(v4) dst_sel:DWORD dst_unused:UNUSED_PAD src0_sel:DWORD src1_sel:WORD_0
	v_mul_lo_u32 v4, v5, s4
	v_add_u32_e32 v2, 0x2000, v2
	v_lshl_add_u32 v0, v0, 1, v4
	v_ashrrev_i32_e32 v4, 31, v2
	v_lshrrev_b32_e32 v4, 22, v4
	v_add_u32_e32 v4, v2, v4
	v_ashrrev_i32_e32 v4, 10, v4
	v_mul_i32_i24_e32 v5, 0x400, v4
	v_sub_u32_e32 v2, v2, v5
	v_lshrrev_b32_e32 v5, 4, v2
	v_bitop3_b32 v2, v5, v2, 32 bitop3:0x6c
	v_ashrrev_i32_e32 v6, 31, v2
	v_lshrrev_b32_e32 v6, 26, v6
	v_add_u32_e32 v6, v2, v6
	v_lshrrev_b32_e32 v7, 6, v6
	v_and_b32_e32 v6, 0xffc0, v6
	v_sub_u32_e32 v2, v2, v6
	v_lshrrev_b16_e32 v6, 7, v2
	v_lshlrev_b32_e32 v5, 3, v4
	v_and_b32_e32 v6, 1, v6
	v_and_b32_e32 v5, 0xfffff0, v5
	v_lshlrev_b32_e32 v4, 5, v4
	v_add_u16_e32 v2, v2, v6
	v_add_u32_e32 v5, v7, v5
	v_and_b32_e32 v4, 32, v4
	v_ashrrev_i16_sdwa v2, v8, sext(v2) dst_sel:DWORD dst_unused:UNUSED_PAD src0_sel:DWORD src1_sel:BYTE_0
	v_add_u32_sdwa v2, v4, sext(v2) dst_sel:DWORD dst_unused:UNUSED_PAD src0_sel:DWORD src1_sel:WORD_0
	v_mul_lo_u32 v4, v5, s4
	v_lshl_add_u32 v2, v2, 1, v4
	v_and_b32_e32 v4, 15, v3
	v_and_b32_e32 v5, 48, v3
	v_lshlrev_b32_e32 v3, 2, v3
	v_lshlrev_b32_e32 v4, 6, v4
	v_and_b32_e32 v3, 32, v3
	v_bitop3_b32 v4, v4, v3, v5 bitop3:0x36
	s_add_i32 s14, s89, s55
	s_mov_b64 s[4:5], 0
	s_branch .LBB0_558

	.amdhsa_kernel _Z4mega6Params
		.amdhsa_group_segment_fixed_size 4608
		.amdhsa_private_segment_fixed_size 0
		.amdhsa_kernarg_size 480
		.amdhsa_user_sgpr_count 2
		.amdhsa_user_sgpr_dispatch_ptr 0
		.amdhsa_user_sgpr_queue_ptr 0
		.amdhsa_user_sgpr_kernarg_segment_ptr 1
		.amdhsa_user_sgpr_dispatch_id 0
		.amdhsa_user_sgpr_kernarg_preload_length 0
		.amdhsa_user_sgpr_kernarg_preload_offset 0
		.amdhsa_user_sgpr_private_segment_size 0
		.amdhsa_uses_dynamic_stack 0
		.amdhsa_enable_private_segment 0
		.amdhsa_system_sgpr_workgroup_id_x 1
		.amdhsa_system_sgpr_workgroup_id_y 0
		.amdhsa_system_sgpr_workgroup_id_z 0
		.amdhsa_system_sgpr_workgroup_info 0
		.amdhsa_system_vgpr_workitem_id 2
		.amdhsa_next_free_vgpr 256
		.amdhsa_next_free_sgpr 102
		.amdhsa_accum_offset 256
		.amdhsa_reserve_vcc 1
		.amdhsa_float_round_mode_32 0
		.amdhsa_float_round_mode_16_64 0
		.amdhsa_float_denorm_mode_32 3
		.amdhsa_float_denorm_mode_16_64 3
		.amdhsa_dx10_clamp 1
		.amdhsa_ieee_mode 1
		.amdhsa_fp16_overflow 0
		.amdhsa_tg_split 0
		.amdhsa_exception_fp_ieee_invalid_op 0
		.amdhsa_exception_fp_denorm_src 0
		.amdhsa_exception_fp_ieee_div_zero 0
		.amdhsa_exception_fp_ieee_overflow 0
		.amdhsa_exception_fp_ieee_underflow 0
		.amdhsa_exception_fp_ieee_inexact 0
		.amdhsa_exception_int_div_zero 0
	.end_amdhsa_kernel

amdhsa.kernels:
  - .agpr_count:     0
    .args:
      - .offset:         0
        .size:           224
        .value_kind:     by_value
      - .offset:         224
        .size:           4
        .value_kind:     hidden_block_count_x
      - .offset:         228
        .size:           4
        .value_kind:     hidden_block_count_y
      - .offset:         232
        .size:           4
        .value_kind:     hidden_block_count_z
      - .offset:         236
        .size:           2
        .value_kind:     hidden_group_size_x
      - .offset:         238
        .size:           2
        .value_kind:     hidden_group_size_y
      - .offset:         240
        .size:           2
        .value_kind:     hidden_group_size_z
      - .offset:         242
        .size:           2
        .value_kind:     hidden_remainder_x
      - .offset:         244
        .size:           2
        .value_kind:     hidden_remainder_y
      - .offset:         246
        .size:           2
        .value_kind:     hidden_remainder_z
      - .offset:         264
        .size:           8
        .value_kind:     hidden_global_offset_x
      - .offset:         272
        .size:           8
        .value_kind:     hidden_global_offset_y
      - .offset:         280
        .size:           8
        .value_kind:     hidden_global_offset_z
      - .offset:         288
        .size:           2
        .value_kind:     hidden_grid_dims
      - .offset:         312
        .size:           8
        .value_kind:     hidden_multigrid_sync_arg
      - .offset:         344
        .size:           4
        .value_kind:     hidden_dynamic_lds_size
    .group_segment_fixed_size: 4608
    .kernarg_segment_align: 8
    .kernarg_segment_size: 480
    .language:       OpenCL C
    .language_version:
      - 2
      - 0
    .max_flat_workgroup_size: 512
    .name:           _Z4mega6Params
    .private_segment_fixed_size: 0
    .sgpr_count:     106
    .sgpr_spill_count: 287
    .symbol:         _Z4mega6Params.kd
    .uniform_work_group_size: 1
    .uses_dynamic_stack: false
    .vgpr_count:     256
    .vgpr_spill_count: 0
    .wavefront_size: 64
